# all GEMM K-loops: MFMAs reordered so both k-halves of each accumulator issue back-to-back (bit-identical math); on top of P14 pipeline + P0 load hoists
# speedup vs baseline: 1.0310x; 1.0171x over previous
; #define PG8_STAGE(bufoff, gbase, voff) do { _Pragma("unroll") for (int _i = 0; _i < 2; ++_i) \
;         __builtin_amdgcn_global_load_lds((const unsigned*)((const char*)(gbase) + (voff)[_i]), (LAS unsigned*)(lds + (bufoff) + ldsw + _i * 8192), 16, 0, 0); } while (0)
; #define PG8_LDA(dst, b, h) do { _Pragma("unroll") for (int m = 0; m < 4; ++m) _Pragma("unroll") for (int k = 0; k < 2; ++k) dst[m][k] = *(const LAS bf16x8*)(lds + PG8_SA(b, h) + aoff + m * 2048 + k * 1024); } while (0)
; #define PG8_LDB(dst, b, h) do { _Pragma("unroll") for (int n = 0; n < 2; ++n) _Pragma("unroll") for (int k = 0; k < 2; ++k) dst[n][k] = *(const LAS bf16x8*)(lds + PG8_SB(b, h) + boff + n * 2048 + k * 1024); } while (0)
; #define PG8_MMA(ai, bj, At, Bt) do { __builtin_amdgcn_s_setprio(1); _Pragma("unroll") for (int m = 0; m < 4; ++m) _Pragma("unroll") for (int n = 0; n < 2; ++n) _Pragma("unroll") for (int k = 0; k < 2; ++k) \
;         acc[ai][bj][m][n] = __builtin_amdgcn_mfma_f32_16x16x32_bf16(Bt[n][k], At[m][k], acc[ai][bj][m][n], 0, 0, 0); __builtin_amdgcn_s_setprio(0); } while (0)
; #define PG8_WAIT_V(n) asm volatile("s_waitcnt vmcnt(" #n ")" ::: "memory")
; #define PG8_WAIT_L(n) asm volatile("s_waitcnt lgkmcnt(" #n ")" ::: "memory")
; template <bool ALIGN_EPI, class Epi, class Sched>
; __device__ __forceinline__ void gemm_phase(LAS unsigned char* lds, const int lda, const int ldb, const int K, const Sched& S, const Epi& E, const size_t kstepA = (size_t)(BK * 2), const size_t kstepB = (size_t)(BK * 2)) {
;     ...
;         for (int t = 0; t < nt; t += 2) {
;             const bool last = (t == nt - 2);
;             const char* a1 = cA + (size_t)(t + 1) * kstepA;
;             const char* a2 = last ? nA : cA + (size_t)(t + 2) * kstepA; const char* b2 = last ? nB : cB + (size_t)(t + 2) * kstep;
;             const char* a3 = a2 + kstepA; const char* b3 = b2 + kstep;
;             PG8_LDB(B0, 0, 0); PG8_LDB(B1, 0, 1); PG8_SCHED; PG8_LDA(At, 0, 0); PG8_STAGE(PG8_SA(1, 1), a1 + hstepA, voffA);
;             PG8_WAIT_V(8); PG8_WAIT_L(0); PG8_BAR; PG8_MMA(0, 0, At, B0); PG8_MMA(0, 1, At, B1); PG8_BAR; PG8_SCHED;
;             PG8_LDA(At, 0, 1); PG8_STAGE(PG8_SB(0, 0), b2, voffB); PG8_STAGE(PG8_SB(0, 1), b2 + hstepB, voffB); PG8_STAGE(PG8_SA(0, 0), a2, voffA);
;             PG8_WAIT_V(8); PG8_WAIT_L(0); PG8_BAR; PG8_MMA(1, 0, At, B0); PG8_MMA(1, 1, At, B1); PG8_BAR; PG8_SCHED;
.LBB0_139:
	ds_read_b128 v[154:157], v150
	ds_read_b128 v[158:161], v150 offset:1024
	ds_read_b128 v[162:165], v150 offset:2048
	ds_read_b128 v[166:169], v150 offset:3072
	ds_read_b128 v[170:173], v151
	ds_read_b128 v[174:177], v151 offset:1024
	ds_read_b128 v[178:181], v151 offset:2048
	ds_read_b128 v[194:197], v151 offset:3072
	s_add_u32 s54, s70, 0x1fc000
	s_addc_u32 s55, s71, 0
	s_cmp_eq_u32 s51, 28
	s_cselect_b32 s78, s6, s54
	s_cselect_b32 s79, s7, s55
	s_cselect_b32 s76, s68, s41
	s_cselect_b32 s77, s69, s49
	s_add_u32 s74, s78, 0x200000
	s_addc_u32 s75, s79, 0
	v_lshl_add_u64 v[146:147], s[70:71], 0, v[138:139]
	s_add_i32 m0, s20, 0xc000
	ds_read_b128 v[198:201], v152
	ds_read_b128 v[202:205], v152 offset:1024
	ds_read_b128 v[206:209], v152 offset:2048
	ds_read_b128 v[210:213], v152 offset:3072
	ds_read_b128 v[214:217], v152 offset:4096
	ds_read_b128 v[218:221], v152 offset:5120
	ds_read_b128 v[222:225], v152 offset:6144
	ds_read_b128 v[226:229], v152 offset:7168
	global_load_lds_dwordx4 v[146:147], off
	v_lshl_add_u64 v[146:147], s[70:71], 0, v[140:141]
	s_add_i32 m0, s20, 0xe000
	s_nop 0
	global_load_lds_dwordx4 v[146:147], off
	s_waitcnt vmcnt(8)
	s_waitcnt lgkmcnt(0)
	s_barrier
	s_setprio 1
	s_waitcnt lgkmcnt(0)
	v_mfma_f32_16x16x32_bf16 v[124:127], v[154:157], v[198:201], v[124:127]
	v_mfma_f32_16x16x32_bf16 v[124:127], v[158:161], v[202:205], v[124:127]
	v_mfma_f32_16x16x32_bf16 v[116:119], v[162:165], v[198:201], v[116:119]
	v_mfma_f32_16x16x32_bf16 v[116:119], v[166:169], v[202:205], v[116:119]
	v_mfma_f32_16x16x32_bf16 v[108:111], v[154:157], v[206:209], v[108:111]
	v_mfma_f32_16x16x32_bf16 v[108:111], v[158:161], v[210:213], v[108:111]
	v_mfma_f32_16x16x32_bf16 v[100:103], v[162:165], v[206:209], v[100:103]
	v_mfma_f32_16x16x32_bf16 v[100:103], v[166:169], v[210:213], v[100:103]
	v_mfma_f32_16x16x32_bf16 v[92:95], v[154:157], v[214:217], v[92:95]
	v_mfma_f32_16x16x32_bf16 v[92:95], v[158:161], v[218:221], v[92:95]
	v_mfma_f32_16x16x32_bf16 v[84:87], v[162:165], v[214:217], v[84:87]
	v_mfma_f32_16x16x32_bf16 v[84:87], v[166:169], v[218:221], v[84:87]
	v_mfma_f32_16x16x32_bf16 v[76:79], v[154:157], v[222:225], v[76:79]
	v_mfma_f32_16x16x32_bf16 v[76:79], v[158:161], v[226:229], v[76:79]
	v_mfma_f32_16x16x32_bf16 v[68:71], v[162:165], v[222:225], v[68:71]
	v_mfma_f32_16x16x32_bf16 v[68:71], v[166:169], v[226:229], v[68:71]
	s_setprio 0
	s_setprio 1
	v_mfma_f32_16x16x32_bf16 v[120:123], v[170:173], v[198:201], v[120:123]
	v_mfma_f32_16x16x32_bf16 v[120:123], v[174:177], v[202:205], v[120:123]
	v_mfma_f32_16x16x32_bf16 v[112:115], v[178:181], v[198:201], v[112:115]
	v_mfma_f32_16x16x32_bf16 v[112:115], v[194:197], v[202:205], v[112:115]
	v_mfma_f32_16x16x32_bf16 v[104:107], v[170:173], v[206:209], v[104:107]
	v_mfma_f32_16x16x32_bf16 v[104:107], v[174:177], v[210:213], v[104:107]
	v_mfma_f32_16x16x32_bf16 v[96:99], v[178:181], v[206:209], v[96:99]
	v_mfma_f32_16x16x32_bf16 v[96:99], v[194:197], v[210:213], v[96:99]
	v_mfma_f32_16x16x32_bf16 v[88:91], v[170:173], v[214:217], v[88:91]
	v_mfma_f32_16x16x32_bf16 v[88:91], v[174:177], v[218:221], v[88:91]
	v_mfma_f32_16x16x32_bf16 v[80:83], v[178:181], v[214:217], v[80:83]
	v_mfma_f32_16x16x32_bf16 v[80:83], v[194:197], v[218:221], v[80:83]
	v_mfma_f32_16x16x32_bf16 v[72:75], v[170:173], v[222:225], v[72:75]
	v_mfma_f32_16x16x32_bf16 v[72:75], v[174:177], v[226:229], v[72:75]
	v_mfma_f32_16x16x32_bf16 v[64:67], v[178:181], v[222:225], v[64:67]
	v_mfma_f32_16x16x32_bf16 v[64:67], v[194:197], v[226:229], v[64:67]
	s_setprio 0
	s_barrier
	s_add_i32 s54, s42, s18
	v_lshl_add_u64 v[146:147], s[76:77], 0, v[132:133]
	s_mov_b32 m0, s54
	ds_read_b128 v[198:201], v152 offset:16384
	ds_read_b128 v[202:205], v152 offset:17408
	ds_read_b128 v[206:209], v152 offset:18432
	ds_read_b128 v[210:213], v152 offset:19456
	ds_read_b128 v[214:217], v152 offset:20480
	ds_read_b128 v[218:221], v152 offset:21504
	ds_read_b128 v[222:225], v152 offset:22528
	ds_read_b128 v[226:229], v152 offset:23552
	global_load_lds_dwordx4 v[146:147], off
	s_add_i32 m0, s54, 0x2000
	s_add_u32 s54, s76, 0x4000
	v_lshl_add_u64 v[146:147], s[76:77], 0, v[128:129]
	s_addc_u32 s55, s77, 0
	s_add_i32 s56, s43, s18
	global_load_lds_dwordx4 v[146:147], off
	v_lshl_add_u64 v[146:147], s[54:55], 0, v[132:133]
	s_mov_b32 m0, s56
	s_nop 0
	global_load_lds_dwordx4 v[146:147], off
	v_lshl_add_u64 v[146:147], s[54:55], 0, v[128:129]
	s_add_i32 m0, s56, 0x2000
	s_nop 0
	global_load_lds_dwordx4 v[146:147], off
	v_lshl_add_u64 v[146:147], s[78:79], 0, v[134:135]
	s_mov_b32 m0, s20
	s_nop 0
	global_load_lds_dwordx4 v[146:147], off
	v_lshl_add_u64 v[146:147], s[78:79], 0, v[130:131]
	s_mov_b32 m0, s21
	s_nop 0
	global_load_lds_dwordx4 v[146:147], off
	s_waitcnt vmcnt(8)
	s_waitcnt lgkmcnt(0)
	s_barrier
; #define PG8_STAGE(bufoff, gbase, voff) do { _Pragma("unroll") for (int _i = 0; _i < 2; ++_i) \
;         __builtin_amdgcn_global_load_lds((const unsigned*)((const char*)(gbase) + (voff)[_i]), (LAS unsigned*)(lds + (bufoff) + ldsw + _i * 8192), 16, 0, 0); } while (0)
; #define PG8_LDA(dst, b, h) do { _Pragma("unroll") for (int m = 0; m < 4; ++m) _Pragma("unroll") for (int k = 0; k < 2; ++k) dst[m][k] = *(const LAS bf16x8*)(lds + PG8_SA(b, h) + aoff + m * 2048 + k * 1024); } while (0)
; #define PG8_LDB(dst, b, h) do { _Pragma("unroll") for (int n = 0; n < 2; ++n) _Pragma("unroll") for (int k = 0; k < 2; ++k) dst[n][k] = *(const LAS bf16x8*)(lds + PG8_SB(b, h) + boff + n * 2048 + k * 1024); } while (0)
; #define PG8_MMA(ai, bj, At, Bt) do { __builtin_amdgcn_s_setprio(1); _Pragma("unroll") for (int m = 0; m < 4; ++m) _Pragma("unroll") for (int n = 0; n < 2; ++n) _Pragma("unroll") for (int k = 0; k < 2; ++k) \
;         acc[ai][bj][m][n] = __builtin_amdgcn_mfma_f32_16x16x32_bf16(Bt[n][k], At[m][k], acc[ai][bj][m][n], 0, 0, 0); __builtin_amdgcn_s_setprio(0); } while (0)
; #define PG8_WAIT_V(n) asm volatile("s_waitcnt vmcnt(" #n ")" ::: "memory")
; #define PG8_WAIT_L(n) asm volatile("s_waitcnt lgkmcnt(" #n ")" ::: "memory")
; #define PG8_BAR __builtin_amdgcn_s_barrier()
; #define PG8_SCHED __builtin_amdgcn_sched_barrier(0)
; template <bool ALIGN_EPI, class Epi, class Sched>
; __device__ __forceinline__ void gemm_phase(LAS unsigned char* lds, const int lda, const int ldb, const int K, const Sched& S, const Epi& E, const size_t kstepA = (size_t)(BK * 2), const size_t kstepB = (size_t)(BK * 2)) {
;     ...
;             PG8_WAIT_V(8); PG8_WAIT_L(0); PG8_BAR; PG8_MMA(1, 0, At, B0); PG8_MMA(1, 1, At, B1); PG8_BAR; PG8_SCHED;
;             PG8_LDB(B0, 1, 0); PG8_LDB(B1, 1, 1); PG8_SCHED; PG8_LDA(At, 1, 0); PG8_STAGE(PG8_SA(0, 1), a2 + hstepA, voffA);
;             PG8_WAIT_V(8); PG8_WAIT_L(0); PG8_BAR; PG8_MMA(0, 0, At, B0); PG8_MMA(0, 1, At, B1); PG8_BAR; PG8_SCHED;
	s_setprio 1
	s_waitcnt lgkmcnt(0)
	v_mfma_f32_16x16x32_bf16 v[60:63], v[154:157], v[198:201], v[60:63]
	v_mfma_f32_16x16x32_bf16 v[60:63], v[158:161], v[202:205], v[60:63]
	v_mfma_f32_16x16x32_bf16 v[52:55], v[162:165], v[198:201], v[52:55]
	v_mfma_f32_16x16x32_bf16 v[52:55], v[166:169], v[202:205], v[52:55]
	v_mfma_f32_16x16x32_bf16 v[44:47], v[154:157], v[206:209], v[44:47]
	v_mfma_f32_16x16x32_bf16 v[44:47], v[158:161], v[210:213], v[44:47]
	v_mfma_f32_16x16x32_bf16 v[36:39], v[162:165], v[206:209], v[36:39]
	v_mfma_f32_16x16x32_bf16 v[36:39], v[166:169], v[210:213], v[36:39]
	v_mfma_f32_16x16x32_bf16 v[28:31], v[154:157], v[214:217], v[28:31]
	v_mfma_f32_16x16x32_bf16 v[28:31], v[158:161], v[218:221], v[28:31]
	v_mfma_f32_16x16x32_bf16 v[20:23], v[162:165], v[214:217], v[20:23]
	v_mfma_f32_16x16x32_bf16 v[20:23], v[166:169], v[218:221], v[20:23]
	v_mfma_f32_16x16x32_bf16 v[12:15], v[154:157], v[222:225], v[12:15]
	v_mfma_f32_16x16x32_bf16 v[12:15], v[158:161], v[226:229], v[12:15]
	v_mfma_f32_16x16x32_bf16 v[4:7], v[162:165], v[222:225], v[4:7]
	v_mfma_f32_16x16x32_bf16 v[4:7], v[166:169], v[226:229], v[4:7]
	s_setprio 0
	s_setprio 1
	v_mfma_f32_16x16x32_bf16 v[56:59], v[170:173], v[198:201], v[56:59]
	v_mfma_f32_16x16x32_bf16 v[56:59], v[174:177], v[202:205], v[56:59]
	v_mfma_f32_16x16x32_bf16 v[48:51], v[178:181], v[198:201], v[48:51]
	v_mfma_f32_16x16x32_bf16 v[48:51], v[194:197], v[202:205], v[48:51]
	v_mfma_f32_16x16x32_bf16 v[40:43], v[170:173], v[206:209], v[40:43]
	v_mfma_f32_16x16x32_bf16 v[40:43], v[174:177], v[210:213], v[40:43]
	v_mfma_f32_16x16x32_bf16 v[32:35], v[178:181], v[206:209], v[32:35]
	v_mfma_f32_16x16x32_bf16 v[32:35], v[194:197], v[210:213], v[32:35]
	v_mfma_f32_16x16x32_bf16 v[24:27], v[170:173], v[214:217], v[24:27]
	v_mfma_f32_16x16x32_bf16 v[24:27], v[174:177], v[218:221], v[24:27]
	v_mfma_f32_16x16x32_bf16 v[16:19], v[178:181], v[214:217], v[16:19]
	v_mfma_f32_16x16x32_bf16 v[16:19], v[194:197], v[218:221], v[16:19]
	v_mfma_f32_16x16x32_bf16 v[8:11], v[170:173], v[222:225], v[8:11]
	v_mfma_f32_16x16x32_bf16 v[8:11], v[174:177], v[226:229], v[8:11]
	v_mfma_f32_16x16x32_bf16 v[0:3], v[178:181], v[222:225], v[0:3]
	v_mfma_f32_16x16x32_bf16 v[0:3], v[194:197], v[226:229], v[0:3]
	s_setprio 0
	s_barrier
	s_add_i32 s56, 0, 0x18000
	v_add_u32_e32 v146, s56, v149
	s_add_i32 s57, 0, 0x1c000
	ds_read_b128 v[154:157], v146
	ds_read_b128 v[158:161], v146 offset:1024
	ds_read_b128 v[162:165], v146 offset:2048
	ds_read_b128 v[166:169], v146 offset:3072
	v_add_u32_e32 v146, s57, v149
	ds_read_b128 v[170:173], v146
	ds_read_b128 v[174:177], v146 offset:1024
	ds_read_b128 v[178:181], v146 offset:2048
	ds_read_b128 v[194:197], v146 offset:3072
	s_add_u32 s54, s78, 0x4000
	s_addc_u32 s55, s79, 0
	s_mov_b32 m0, s22
	v_lshl_add_u64 v[146:147], s[54:55], 0, v[134:135]
	ds_read_b128 v[198:201], v152 offset:32768
	ds_read_b128 v[202:205], v152 offset:33792
	ds_read_b128 v[206:209], v152 offset:34816
	ds_read_b128 v[210:213], v152 offset:35840
	ds_read_b128 v[214:217], v152 offset:36864
	ds_read_b128 v[218:221], v152 offset:37888
	ds_read_b128 v[222:225], v152 offset:38912
	ds_read_b128 v[226:229], v152 offset:39936
	global_load_lds_dwordx4 v[146:147], off
	v_lshl_add_u64 v[146:147], s[54:55], 0, v[130:131]
	s_mov_b32 m0, s23
	s_nop 0
	global_load_lds_dwordx4 v[146:147], off
	s_waitcnt vmcnt(8)
	s_waitcnt lgkmcnt(0)
	s_barrier
	s_setprio 1
	s_waitcnt lgkmcnt(0)
	v_mfma_f32_16x16x32_bf16 v[124:127], v[154:157], v[198:201], v[124:127]
	v_mfma_f32_16x16x32_bf16 v[124:127], v[158:161], v[202:205], v[124:127]
	v_mfma_f32_16x16x32_bf16 v[116:119], v[162:165], v[198:201], v[116:119]
	v_mfma_f32_16x16x32_bf16 v[116:119], v[166:169], v[202:205], v[116:119]
	v_mfma_f32_16x16x32_bf16 v[108:111], v[154:157], v[206:209], v[108:111]
	v_mfma_f32_16x16x32_bf16 v[108:111], v[158:161], v[210:213], v[108:111]
	v_mfma_f32_16x16x32_bf16 v[100:103], v[162:165], v[206:209], v[100:103]
	v_mfma_f32_16x16x32_bf16 v[100:103], v[166:169], v[210:213], v[100:103]
	v_mfma_f32_16x16x32_bf16 v[92:95], v[154:157], v[214:217], v[92:95]
	v_mfma_f32_16x16x32_bf16 v[92:95], v[158:161], v[218:221], v[92:95]
	v_mfma_f32_16x16x32_bf16 v[84:87], v[162:165], v[214:217], v[84:87]
	v_mfma_f32_16x16x32_bf16 v[84:87], v[166:169], v[218:221], v[84:87]
	v_mfma_f32_16x16x32_bf16 v[76:79], v[154:157], v[222:225], v[76:79]
	v_mfma_f32_16x16x32_bf16 v[76:79], v[158:161], v[226:229], v[76:79]
	v_mfma_f32_16x16x32_bf16 v[68:71], v[162:165], v[222:225], v[68:71]
	v_mfma_f32_16x16x32_bf16 v[68:71], v[166:169], v[226:229], v[68:71]
	s_setprio 0
	s_setprio 1
	v_mfma_f32_16x16x32_bf16 v[120:123], v[170:173], v[198:201], v[120:123]
	v_mfma_f32_16x16x32_bf16 v[120:123], v[174:177], v[202:205], v[120:123]
	v_mfma_f32_16x16x32_bf16 v[112:115], v[178:181], v[198:201], v[112:115]
	v_mfma_f32_16x16x32_bf16 v[112:115], v[194:197], v[202:205], v[112:115]
	v_mfma_f32_16x16x32_bf16 v[104:107], v[170:173], v[206:209], v[104:107]
	v_mfma_f32_16x16x32_bf16 v[104:107], v[174:177], v[210:213], v[104:107]
	v_mfma_f32_16x16x32_bf16 v[96:99], v[178:181], v[206:209], v[96:99]
	v_mfma_f32_16x16x32_bf16 v[96:99], v[194:197], v[210:213], v[96:99]
	v_mfma_f32_16x16x32_bf16 v[88:91], v[170:173], v[214:217], v[88:91]
	v_mfma_f32_16x16x32_bf16 v[88:91], v[174:177], v[218:221], v[88:91]
	v_mfma_f32_16x16x32_bf16 v[80:83], v[178:181], v[214:217], v[80:83]
	v_mfma_f32_16x16x32_bf16 v[80:83], v[194:197], v[218:221], v[80:83]
	v_mfma_f32_16x16x32_bf16 v[72:75], v[170:173], v[222:225], v[72:75]
	v_mfma_f32_16x16x32_bf16 v[72:75], v[174:177], v[226:229], v[72:75]
	v_mfma_f32_16x16x32_bf16 v[64:67], v[178:181], v[222:225], v[64:67]
	v_mfma_f32_16x16x32_bf16 v[64:67], v[194:197], v[226:229], v[64:67]
	s_setprio 0
	s_barrier
; #define PG8_STAGE(bufoff, gbase, voff) do { _Pragma("unroll") for (int _i = 0; _i < 2; ++_i) \
;         __builtin_amdgcn_global_load_lds((const unsigned*)((const char*)(gbase) + (voff)[_i]), (LAS unsigned*)(lds + (bufoff) + ldsw + _i * 8192), 16, 0, 0); } while (0)
; #define PG8_LDA(dst, b, h) do { _Pragma("unroll") for (int m = 0; m < 4; ++m) _Pragma("unroll") for (int k = 0; k < 2; ++k) dst[m][k] = *(const LAS bf16x8*)(lds + PG8_SA(b, h) + aoff + m * 2048 + k * 1024); } while (0)
; #define PG8_MMA(ai, bj, At, Bt) do { __builtin_amdgcn_s_setprio(1); _Pragma("unroll") for (int m = 0; m < 4; ++m) _Pragma("unroll") for (int n = 0; n < 2; ++n) _Pragma("unroll") for (int k = 0; k < 2; ++k) \
;         acc[ai][bj][m][n] = __builtin_amdgcn_mfma_f32_16x16x32_bf16(Bt[n][k], At[m][k], acc[ai][bj][m][n], 0, 0, 0); __builtin_amdgcn_s_setprio(0); } while (0)
; #define PG8_WAIT_V(n) asm volatile("s_waitcnt vmcnt(" #n ")" ::: "memory")
; #define PG8_WAIT_L(n) asm volatile("s_waitcnt lgkmcnt(" #n ")" ::: "memory")
; #define PG8_BAR __builtin_amdgcn_s_barrier()
; #define PG8_SCHED __builtin_amdgcn_sched_barrier(0)
; template <bool ALIGN_EPI, class Epi, class Sched>
; __device__ __forceinline__ void gemm_phase(LAS unsigned char* lds, const int lda, const int ldb, const int K, const Sched& S, const Epi& E, const size_t kstepA = (size_t)(BK * 2), const size_t kstepB = (size_t)(BK * 2)) {
;     ...
;             PG8_LDA(At, 1, 1); PG8_STAGE(PG8_SB(1, 0), b3, voffB); PG8_STAGE(PG8_SB(1, 1), b3 + hstepB, voffB); PG8_STAGE(PG8_SA(1, 0), a3, voffA);
;             PG8_WAIT_V(8); PG8_WAIT_L(0); PG8_BAR; PG8_MMA(1, 0, At, B0); PG8_MMA(1, 1, At, B1); PG8_BAR; PG8_SCHED;
;         }
	s_add_u32 s54, s76, 0x160000
	s_addc_u32 s55, s77, 0
	s_add_i32 s56, s56, s18
	v_lshl_add_u64 v[146:147], s[54:55], 0, v[132:133]
	s_mov_b32 m0, s56
	ds_read_b128 v[198:201], v152 offset:49152
	ds_read_b128 v[202:205], v152 offset:50176
	ds_read_b128 v[206:209], v152 offset:51200
	ds_read_b128 v[210:213], v152 offset:52224
	ds_read_b128 v[214:217], v152 offset:53248
	ds_read_b128 v[218:221], v152 offset:54272
	ds_read_b128 v[222:225], v152 offset:55296
	ds_read_b128 v[226:229], v152 offset:56320
	global_load_lds_dwordx4 v[146:147], off
	s_add_i32 m0, s56, 0x2000
	v_lshl_add_u64 v[146:147], s[54:55], 0, v[128:129]
	s_add_u32 s54, s76, 0x164000
	s_addc_u32 s55, s77, 0
	s_add_i32 s56, s57, s18
	global_load_lds_dwordx4 v[146:147], off
	v_lshl_add_u64 v[146:147], s[54:55], 0, v[132:133]
	s_mov_b32 m0, s56
	s_nop 0
	global_load_lds_dwordx4 v[146:147], off
	v_lshl_add_u64 v[146:147], s[54:55], 0, v[128:129]
	s_add_i32 m0, s56, 0x2000
	s_nop 0
	global_load_lds_dwordx4 v[146:147], off
	v_lshl_add_u64 v[146:147], s[74:75], 0, v[134:135]
	s_mov_b32 m0, s31
	s_nop 0
	global_load_lds_dwordx4 v[146:147], off
	v_lshl_add_u64 v[146:147], s[74:75], 0, v[130:131]
	s_mov_b32 m0, s33
	s_nop 0
	global_load_lds_dwordx4 v[146:147], off
	s_waitcnt vmcnt(8)
	s_waitcnt lgkmcnt(0)
	s_barrier
	s_setprio 1
	s_waitcnt lgkmcnt(0)
	v_mfma_f32_16x16x32_bf16 v[60:63], v[154:157], v[198:201], v[60:63]
	v_mfma_f32_16x16x32_bf16 v[60:63], v[158:161], v[202:205], v[60:63]
	v_mfma_f32_16x16x32_bf16 v[52:55], v[162:165], v[198:201], v[52:55]
	v_mfma_f32_16x16x32_bf16 v[52:55], v[166:169], v[202:205], v[52:55]
	v_mfma_f32_16x16x32_bf16 v[44:47], v[154:157], v[206:209], v[44:47]
	v_mfma_f32_16x16x32_bf16 v[44:47], v[158:161], v[210:213], v[44:47]
	v_mfma_f32_16x16x32_bf16 v[36:39], v[162:165], v[206:209], v[36:39]
	v_mfma_f32_16x16x32_bf16 v[36:39], v[166:169], v[210:213], v[36:39]
	v_mfma_f32_16x16x32_bf16 v[28:31], v[154:157], v[214:217], v[28:31]
	v_mfma_f32_16x16x32_bf16 v[28:31], v[158:161], v[218:221], v[28:31]
	v_mfma_f32_16x16x32_bf16 v[20:23], v[162:165], v[214:217], v[20:23]
	v_mfma_f32_16x16x32_bf16 v[20:23], v[166:169], v[218:221], v[20:23]
	v_mfma_f32_16x16x32_bf16 v[12:15], v[154:157], v[222:225], v[12:15]
	v_mfma_f32_16x16x32_bf16 v[12:15], v[158:161], v[226:229], v[12:15]
	v_mfma_f32_16x16x32_bf16 v[4:7], v[162:165], v[222:225], v[4:7]
	v_mfma_f32_16x16x32_bf16 v[4:7], v[166:169], v[226:229], v[4:7]
	s_setprio 0
	s_setprio 1
	v_mfma_f32_16x16x32_bf16 v[56:59], v[170:173], v[198:201], v[56:59]
	v_mfma_f32_16x16x32_bf16 v[56:59], v[174:177], v[202:205], v[56:59]
	v_mfma_f32_16x16x32_bf16 v[48:51], v[178:181], v[198:201], v[48:51]
	v_mfma_f32_16x16x32_bf16 v[48:51], v[194:197], v[202:205], v[48:51]
	v_mfma_f32_16x16x32_bf16 v[40:43], v[170:173], v[206:209], v[40:43]
	v_mfma_f32_16x16x32_bf16 v[40:43], v[174:177], v[210:213], v[40:43]
	v_mfma_f32_16x16x32_bf16 v[32:35], v[178:181], v[206:209], v[32:35]
	v_mfma_f32_16x16x32_bf16 v[32:35], v[194:197], v[210:213], v[32:35]
	v_mfma_f32_16x16x32_bf16 v[24:27], v[170:173], v[214:217], v[24:27]
	v_mfma_f32_16x16x32_bf16 v[24:27], v[174:177], v[218:221], v[24:27]
	v_mfma_f32_16x16x32_bf16 v[16:19], v[178:181], v[214:217], v[16:19]
	v_mfma_f32_16x16x32_bf16 v[16:19], v[194:197], v[218:221], v[16:19]
	v_mfma_f32_16x16x32_bf16 v[8:11], v[170:173], v[222:225], v[8:11]
	v_mfma_f32_16x16x32_bf16 v[8:11], v[174:177], v[226:229], v[8:11]
	v_mfma_f32_16x16x32_bf16 v[0:3], v[178:181], v[222:225], v[0:3]
	v_mfma_f32_16x16x32_bf16 v[0:3], v[194:197], v[226:229], v[0:3]
	s_setprio 0
	s_barrier
	s_add_i32 s51, s51, 2
	s_add_u32 s41, s41, 0x2c0000
	s_addc_u32 s49, s49, 0
	s_add_u32 s70, s70, 0x400000
	s_addc_u32 s71, s71, 0
	s_cmp_gt_u32 s51, 29
	s_cbranch_scc0 .LBB0_139
	s_and_b64 vcc, exec, s[12:13]
	s_cbranch_vccz .LBB0_142
	s_barrier

; #define PG8_STAGE(bufoff, gbase, voff) do { _Pragma("unroll") for (int _i = 0; _i < 2; ++_i) \
;         __builtin_amdgcn_global_load_lds((const unsigned*)((const char*)(gbase) + (voff)[_i]), (LAS unsigned*)(lds + (bufoff) + ldsw + _i * 8192), 16, 0, 0); } while (0)
; #define PG8_LDA(dst, b, h) do { _Pragma("unroll") for (int m = 0; m < 4; ++m) _Pragma("unroll") for (int k = 0; k < 2; ++k) dst[m][k] = *(const LAS bf16x8*)(lds + PG8_SA(b, h) + aoff + m * 2048 + k * 1024); } while (0)
; #define PG8_LDB(dst, b, h) do { _Pragma("unroll") for (int n = 0; n < 2; ++n) _Pragma("unroll") for (int k = 0; k < 2; ++k) dst[n][k] = *(const LAS bf16x8*)(lds + PG8_SB(b, h) + boff + n * 2048 + k * 1024); } while (0)
; #define PG8_MMA(ai, bj, At, Bt) do { __builtin_amdgcn_s_setprio(1); _Pragma("unroll") for (int m = 0; m < 4; ++m) _Pragma("unroll") for (int n = 0; n < 2; ++n) _Pragma("unroll") for (int k = 0; k < 2; ++k) \
;         acc[ai][bj][m][n] = __builtin_amdgcn_mfma_f32_16x16x32_bf16(Bt[n][k], At[m][k], acc[ai][bj][m][n], 0, 0, 0); __builtin_amdgcn_s_setprio(0); } while (0)
; #define PG8_WAIT_V(n) asm volatile("s_waitcnt vmcnt(" #n ")" ::: "memory")
; #define PG8_WAIT_L(n) asm volatile("s_waitcnt lgkmcnt(" #n ")" ::: "memory")
; template <bool ALIGN_EPI, class Epi, class Sched>
; __device__ __forceinline__ void gemm_phase(LAS unsigned char* lds, const int lda, const int ldb, const int K, const Sched& S, const Epi& E, const size_t kstepA = (size_t)(BK * 2), const size_t kstepB = (size_t)(BK * 2)) {
;     ...
;         for (int t = 0; t < nt; t += 2) {
;             const bool last = (t == nt - 2);
;             const char* a1 = cA + (size_t)(t + 1) * kstepA;
;             const char* a2 = last ? nA : cA + (size_t)(t + 2) * kstepA; const char* b2 = last ? nB : cB + (size_t)(t + 2) * kstep;
;             const char* a3 = a2 + kstepA; const char* b3 = b2 + kstep;
;             PG8_LDB(B0, 0, 0); PG8_LDB(B1, 0, 1); PG8_SCHED; PG8_LDA(At, 0, 0); PG8_STAGE(PG8_SA(1, 1), a1 + hstepA, voffA);
;             PG8_WAIT_V(8); PG8_WAIT_L(0); PG8_BAR; PG8_MMA(0, 0, At, B0); PG8_MMA(0, 1, At, B1); PG8_BAR; PG8_SCHED;
;             PG8_LDA(At, 0, 1); PG8_STAGE(PG8_SB(0, 0), b2, voffB); PG8_STAGE(PG8_SB(0, 1), b2 + hstepB, voffB); PG8_STAGE(PG8_SA(0, 0), a2, voffA);
;             PG8_WAIT_V(8); PG8_WAIT_L(0); PG8_BAR; PG8_MMA(1, 0, At, B0); PG8_MMA(1, 1, At, B1); PG8_BAR; PG8_SCHED;
.LBB0_218:
	ds_read_b128 v[64:67], v193
	ds_read_b128 v[68:71], v193 offset:1024
	ds_read_b128 v[80:83], v193 offset:2048
	ds_read_b128 v[84:87], v193 offset:3072
	ds_read_b128 v[144:147], v232
	ds_read_b128 v[148:151], v232 offset:1024
	ds_read_b128 v[152:155], v232 offset:2048
	ds_read_b128 v[156:159], v232 offset:3072
	s_add_u32 s54, s82, 0x1fc000
	s_addc_u32 s55, s83, 0
	s_cmpk_eq_i32 s51, 0x54
	s_cselect_b32 vcc_lo, s6, s54
	s_cselect_b32 vcc_hi, s7, s55
	s_cselect_b32 s96, s78, s13
	s_cselect_b32 s97, s79, s50
	s_add_u32 s94, vcc_lo, 0x200000
	s_addc_u32 s95, vcc_hi, 0
	v_lshl_add_u64 v[220:221], s[82:83], 0, v[204:205]
	s_add_i32 m0, s19, 0xc000
	ds_read_b128 v[160:163], v233
	ds_read_b128 v[164:167], v233 offset:1024
	ds_read_b128 v[168:171], v233 offset:2048
	ds_read_b128 v[172:175], v233 offset:3072
	ds_read_b128 v[176:179], v233 offset:4096
	ds_read_b128 v[180:183], v233 offset:5120
	ds_read_b128 v[212:215], v233 offset:6144
	ds_read_b128 v[216:219], v233 offset:7168
	global_load_lds_dwordx4 v[220:221], off
	v_lshl_add_u64 v[220:221], s[82:83], 0, v[206:207]
	s_add_i32 m0, s19, 0xe000
	s_nop 0
	global_load_lds_dwordx4 v[220:221], off
	s_waitcnt vmcnt(8)
	s_waitcnt lgkmcnt(0)
	s_barrier
	s_setprio 1
	s_waitcnt lgkmcnt(0)
	v_mfma_f32_16x16x32_bf16 v[140:143], v[64:67], v[160:163], v[140:143]
	v_mfma_f32_16x16x32_bf16 v[140:143], v[68:71], v[164:167], v[140:143]
	v_mfma_f32_16x16x32_bf16 v[136:139], v[80:83], v[160:163], v[136:139]
	v_mfma_f32_16x16x32_bf16 v[136:139], v[84:87], v[164:167], v[136:139]
	v_mfma_f32_16x16x32_bf16 v[124:127], v[64:67], v[168:171], v[124:127]
	v_mfma_f32_16x16x32_bf16 v[124:127], v[68:71], v[172:175], v[124:127]
	v_mfma_f32_16x16x32_bf16 v[120:123], v[80:83], v[168:171], v[120:123]
	v_mfma_f32_16x16x32_bf16 v[120:123], v[84:87], v[172:175], v[120:123]
	v_mfma_f32_16x16x32_bf16 v[108:111], v[64:67], v[176:179], v[108:111]
	v_mfma_f32_16x16x32_bf16 v[108:111], v[68:71], v[180:183], v[108:111]
	v_mfma_f32_16x16x32_bf16 v[104:107], v[80:83], v[176:179], v[104:107]
	v_mfma_f32_16x16x32_bf16 v[104:107], v[84:87], v[180:183], v[104:107]
	v_mfma_f32_16x16x32_bf16 v[92:95], v[64:67], v[212:215], v[92:95]
	v_mfma_f32_16x16x32_bf16 v[92:95], v[68:71], v[216:219], v[92:95]
	v_mfma_f32_16x16x32_bf16 v[88:91], v[80:83], v[212:215], v[88:91]
	v_mfma_f32_16x16x32_bf16 v[88:91], v[84:87], v[216:219], v[88:91]
	s_setprio 0
	s_setprio 1
	v_mfma_f32_16x16x32_bf16 v[132:135], v[144:147], v[160:163], v[132:135]
	v_mfma_f32_16x16x32_bf16 v[132:135], v[148:151], v[164:167], v[132:135]
	v_mfma_f32_16x16x32_bf16 v[128:131], v[152:155], v[160:163], v[128:131]
	v_mfma_f32_16x16x32_bf16 v[128:131], v[156:159], v[164:167], v[128:131]
	v_mfma_f32_16x16x32_bf16 v[116:119], v[144:147], v[168:171], v[116:119]
	v_mfma_f32_16x16x32_bf16 v[116:119], v[148:151], v[172:175], v[116:119]
	v_mfma_f32_16x16x32_bf16 v[112:115], v[152:155], v[168:171], v[112:115]
	v_mfma_f32_16x16x32_bf16 v[112:115], v[156:159], v[172:175], v[112:115]
	v_mfma_f32_16x16x32_bf16 v[100:103], v[144:147], v[176:179], v[100:103]
	v_mfma_f32_16x16x32_bf16 v[100:103], v[148:151], v[180:183], v[100:103]
	v_mfma_f32_16x16x32_bf16 v[96:99], v[152:155], v[176:179], v[96:99]
	v_mfma_f32_16x16x32_bf16 v[96:99], v[156:159], v[180:183], v[96:99]
	v_mfma_f32_16x16x32_bf16 v[76:79], v[144:147], v[212:215], v[76:79]
	v_mfma_f32_16x16x32_bf16 v[76:79], v[148:151], v[216:219], v[76:79]
	v_mfma_f32_16x16x32_bf16 v[72:75], v[152:155], v[212:215], v[72:75]
	v_mfma_f32_16x16x32_bf16 v[72:75], v[156:159], v[216:219], v[72:75]
	s_setprio 0
	s_barrier
	s_add_i32 s54, s33, s18
	v_lshl_add_u64 v[220:221], s[96:97], 0, v[196:197]
	s_mov_b32 m0, s54
	ds_read_b128 v[160:163], v233 offset:16384
	ds_read_b128 v[164:167], v233 offset:17408
	ds_read_b128 v[168:171], v233 offset:18432
	ds_read_b128 v[172:175], v233 offset:19456
	ds_read_b128 v[176:179], v233 offset:20480
	ds_read_b128 v[180:183], v233 offset:21504
	ds_read_b128 v[212:215], v233 offset:22528
	ds_read_b128 v[216:219], v233 offset:23552
	global_load_lds_dwordx4 v[220:221], off
	s_add_i32 m0, s54, 0x2000
	s_add_u32 s54, s96, 0x4000
	v_lshl_add_u64 v[220:221], s[96:97], 0, v[200:201]
	s_addc_u32 s55, s97, 0
	s_add_i32 s56, s42, s18
	global_load_lds_dwordx4 v[220:221], off
	v_lshl_add_u64 v[220:221], s[54:55], 0, v[196:197]
	s_mov_b32 m0, s56
	s_nop 0
	global_load_lds_dwordx4 v[220:221], off
	v_lshl_add_u64 v[220:221], s[54:55], 0, v[200:201]
	s_add_i32 m0, s56, 0x2000
	s_nop 0
	global_load_lds_dwordx4 v[220:221], off
	v_lshl_add_u64 v[220:221], vcc, 0, v[194:195]
	s_mov_b32 m0, s19
	s_nop 0
	global_load_lds_dwordx4 v[220:221], off
	v_lshl_add_u64 v[220:221], vcc, 0, v[198:199]
	s_mov_b32 m0, s20
	s_nop 0
	global_load_lds_dwordx4 v[220:221], off
	s_waitcnt vmcnt(8)
	s_waitcnt lgkmcnt(0)
	s_barrier
; #define PG8_STAGE(bufoff, gbase, voff) do { _Pragma("unroll") for (int _i = 0; _i < 2; ++_i) \
;         __builtin_amdgcn_global_load_lds((const unsigned*)((const char*)(gbase) + (voff)[_i]), (LAS unsigned*)(lds + (bufoff) + ldsw + _i * 8192), 16, 0, 0); } while (0)
; #define PG8_LDA(dst, b, h) do { _Pragma("unroll") for (int m = 0; m < 4; ++m) _Pragma("unroll") for (int k = 0; k < 2; ++k) dst[m][k] = *(const LAS bf16x8*)(lds + PG8_SA(b, h) + aoff + m * 2048 + k * 1024); } while (0)
; #define PG8_LDB(dst, b, h) do { _Pragma("unroll") for (int n = 0; n < 2; ++n) _Pragma("unroll") for (int k = 0; k < 2; ++k) dst[n][k] = *(const LAS bf16x8*)(lds + PG8_SB(b, h) + boff + n * 2048 + k * 1024); } while (0)
; #define PG8_MMA(ai, bj, At, Bt) do { __builtin_amdgcn_s_setprio(1); _Pragma("unroll") for (int m = 0; m < 4; ++m) _Pragma("unroll") for (int n = 0; n < 2; ++n) _Pragma("unroll") for (int k = 0; k < 2; ++k) \
;         acc[ai][bj][m][n] = __builtin_amdgcn_mfma_f32_16x16x32_bf16(Bt[n][k], At[m][k], acc[ai][bj][m][n], 0, 0, 0); __builtin_amdgcn_s_setprio(0); } while (0)
; #define PG8_WAIT_V(n) asm volatile("s_waitcnt vmcnt(" #n ")" ::: "memory")
; #define PG8_WAIT_L(n) asm volatile("s_waitcnt lgkmcnt(" #n ")" ::: "memory")
; #define PG8_BAR __builtin_amdgcn_s_barrier()
; #define PG8_SCHED __builtin_amdgcn_sched_barrier(0)
; template <bool ALIGN_EPI, class Epi, class Sched>
; __device__ __forceinline__ void gemm_phase(LAS unsigned char* lds, const int lda, const int ldb, const int K, const Sched& S, const Epi& E, const size_t kstepA = (size_t)(BK * 2), const size_t kstepB = (size_t)(BK * 2)) {
;     ...
;             PG8_WAIT_V(8); PG8_WAIT_L(0); PG8_BAR; PG8_MMA(1, 0, At, B0); PG8_MMA(1, 1, At, B1); PG8_BAR; PG8_SCHED;
;             PG8_LDB(B0, 1, 0); PG8_LDB(B1, 1, 1); PG8_SCHED; PG8_LDA(At, 1, 0); PG8_STAGE(PG8_SA(0, 1), a2 + hstepA, voffA);
;             PG8_WAIT_V(8); PG8_WAIT_L(0); PG8_BAR; PG8_MMA(0, 0, At, B0); PG8_MMA(0, 1, At, B1); PG8_BAR; PG8_SCHED;
	s_setprio 1
	s_waitcnt lgkmcnt(0)
	v_mfma_f32_16x16x32_bf16 v[60:63], v[64:67], v[160:163], v[60:63]
	v_mfma_f32_16x16x32_bf16 v[60:63], v[68:71], v[164:167], v[60:63]
	v_mfma_f32_16x16x32_bf16 v[56:59], v[80:83], v[160:163], v[56:59]
	v_mfma_f32_16x16x32_bf16 v[56:59], v[84:87], v[164:167], v[56:59]
	v_mfma_f32_16x16x32_bf16 v[44:47], v[64:67], v[168:171], v[44:47]
	v_mfma_f32_16x16x32_bf16 v[44:47], v[68:71], v[172:175], v[44:47]
	v_mfma_f32_16x16x32_bf16 v[40:43], v[80:83], v[168:171], v[40:43]
	v_mfma_f32_16x16x32_bf16 v[40:43], v[84:87], v[172:175], v[40:43]
	v_mfma_f32_16x16x32_bf16 v[28:31], v[64:67], v[176:179], v[28:31]
	v_mfma_f32_16x16x32_bf16 v[28:31], v[68:71], v[180:183], v[28:31]
	v_mfma_f32_16x16x32_bf16 v[24:27], v[80:83], v[176:179], v[24:27]
	v_mfma_f32_16x16x32_bf16 v[24:27], v[84:87], v[180:183], v[24:27]
	v_mfma_f32_16x16x32_bf16 v[12:15], v[64:67], v[212:215], v[12:15]
	v_mfma_f32_16x16x32_bf16 v[12:15], v[68:71], v[216:219], v[12:15]
	v_mfma_f32_16x16x32_bf16 v[8:11], v[80:83], v[212:215], v[8:11]
	v_mfma_f32_16x16x32_bf16 v[8:11], v[84:87], v[216:219], v[8:11]
	s_setprio 0
	s_setprio 1
	v_mfma_f32_16x16x32_bf16 v[52:55], v[144:147], v[160:163], v[52:55]
	v_mfma_f32_16x16x32_bf16 v[52:55], v[148:151], v[164:167], v[52:55]
	v_mfma_f32_16x16x32_bf16 v[48:51], v[152:155], v[160:163], v[48:51]
	v_mfma_f32_16x16x32_bf16 v[48:51], v[156:159], v[164:167], v[48:51]
	v_mfma_f32_16x16x32_bf16 v[36:39], v[144:147], v[168:171], v[36:39]
	v_mfma_f32_16x16x32_bf16 v[36:39], v[148:151], v[172:175], v[36:39]
	v_mfma_f32_16x16x32_bf16 v[32:35], v[152:155], v[168:171], v[32:35]
	v_mfma_f32_16x16x32_bf16 v[32:35], v[156:159], v[172:175], v[32:35]
	v_mfma_f32_16x16x32_bf16 v[20:23], v[144:147], v[176:179], v[20:23]
	v_mfma_f32_16x16x32_bf16 v[20:23], v[148:151], v[180:183], v[20:23]
	v_mfma_f32_16x16x32_bf16 v[16:19], v[152:155], v[176:179], v[16:19]
	v_mfma_f32_16x16x32_bf16 v[16:19], v[156:159], v[180:183], v[16:19]
	v_mfma_f32_16x16x32_bf16 v[4:7], v[144:147], v[212:215], v[4:7]
	v_mfma_f32_16x16x32_bf16 v[4:7], v[148:151], v[216:219], v[4:7]
	v_mfma_f32_16x16x32_bf16 v[0:3], v[152:155], v[212:215], v[0:3]
	v_mfma_f32_16x16x32_bf16 v[0:3], v[156:159], v[216:219], v[0:3]
	s_setprio 0
	s_barrier
	s_add_i32 s56, 0, 0x18000
	s_add_i32 s57, 0, 0x1c000
	v_add_u32_e32 v84, s56, v191
	v_add_u32_e32 v156, s57, v191
	ds_read_b128 v[64:67], v84
	ds_read_b128 v[68:71], v84 offset:1024
	ds_read_b128 v[80:83], v84 offset:2048
	ds_read_b128 v[84:87], v84 offset:3072
	ds_read_b128 v[144:147], v156
	ds_read_b128 v[148:151], v156 offset:1024
	ds_read_b128 v[152:155], v156 offset:2048
	ds_read_b128 v[156:159], v156 offset:3072
	s_add_u32 s54, vcc_lo, 0x4000
	s_addc_u32 s55, vcc_hi, 0
	s_mov_b32 m0, s21
	v_lshl_add_u64 v[220:221], s[54:55], 0, v[194:195]
	ds_read_b128 v[160:163], v233 offset:32768
	ds_read_b128 v[164:167], v233 offset:33792
	ds_read_b128 v[168:171], v233 offset:34816
	ds_read_b128 v[172:175], v233 offset:35840
	ds_read_b128 v[176:179], v233 offset:36864
	ds_read_b128 v[180:183], v233 offset:37888
	ds_read_b128 v[212:215], v233 offset:38912
	ds_read_b128 v[216:219], v233 offset:39936
	global_load_lds_dwordx4 v[220:221], off
	v_lshl_add_u64 v[220:221], s[54:55], 0, v[198:199]
	s_mov_b32 m0, s22
	s_nop 0
	global_load_lds_dwordx4 v[220:221], off
	s_waitcnt vmcnt(8)
	s_waitcnt lgkmcnt(0)
	s_barrier
	s_setprio 1
	s_waitcnt lgkmcnt(0)
	v_mfma_f32_16x16x32_bf16 v[140:143], v[64:67], v[160:163], v[140:143]
	v_mfma_f32_16x16x32_bf16 v[140:143], v[68:71], v[164:167], v[140:143]
	v_mfma_f32_16x16x32_bf16 v[136:139], v[80:83], v[160:163], v[136:139]
	v_mfma_f32_16x16x32_bf16 v[136:139], v[84:87], v[164:167], v[136:139]
	v_mfma_f32_16x16x32_bf16 v[124:127], v[64:67], v[168:171], v[124:127]
	v_mfma_f32_16x16x32_bf16 v[124:127], v[68:71], v[172:175], v[124:127]
	v_mfma_f32_16x16x32_bf16 v[120:123], v[80:83], v[168:171], v[120:123]
	v_mfma_f32_16x16x32_bf16 v[120:123], v[84:87], v[172:175], v[120:123]
	v_mfma_f32_16x16x32_bf16 v[108:111], v[64:67], v[176:179], v[108:111]
	v_mfma_f32_16x16x32_bf16 v[108:111], v[68:71], v[180:183], v[108:111]
	v_mfma_f32_16x16x32_bf16 v[104:107], v[80:83], v[176:179], v[104:107]
	v_mfma_f32_16x16x32_bf16 v[104:107], v[84:87], v[180:183], v[104:107]
	v_mfma_f32_16x16x32_bf16 v[92:95], v[64:67], v[212:215], v[92:95]
	v_mfma_f32_16x16x32_bf16 v[92:95], v[68:71], v[216:219], v[92:95]
	v_mfma_f32_16x16x32_bf16 v[88:91], v[80:83], v[212:215], v[88:91]
	v_mfma_f32_16x16x32_bf16 v[88:91], v[84:87], v[216:219], v[88:91]
	s_setprio 0
	s_setprio 1
	v_mfma_f32_16x16x32_bf16 v[132:135], v[144:147], v[160:163], v[132:135]
	v_mfma_f32_16x16x32_bf16 v[132:135], v[148:151], v[164:167], v[132:135]
	v_mfma_f32_16x16x32_bf16 v[128:131], v[152:155], v[160:163], v[128:131]
	v_mfma_f32_16x16x32_bf16 v[128:131], v[156:159], v[164:167], v[128:131]
	v_mfma_f32_16x16x32_bf16 v[116:119], v[144:147], v[168:171], v[116:119]
	v_mfma_f32_16x16x32_bf16 v[116:119], v[148:151], v[172:175], v[116:119]
	v_mfma_f32_16x16x32_bf16 v[112:115], v[152:155], v[168:171], v[112:115]
	v_mfma_f32_16x16x32_bf16 v[112:115], v[156:159], v[172:175], v[112:115]
	v_mfma_f32_16x16x32_bf16 v[100:103], v[144:147], v[176:179], v[100:103]
	v_mfma_f32_16x16x32_bf16 v[100:103], v[148:151], v[180:183], v[100:103]
	v_mfma_f32_16x16x32_bf16 v[96:99], v[152:155], v[176:179], v[96:99]
	v_mfma_f32_16x16x32_bf16 v[96:99], v[156:159], v[180:183], v[96:99]
	v_mfma_f32_16x16x32_bf16 v[76:79], v[144:147], v[212:215], v[76:79]
	v_mfma_f32_16x16x32_bf16 v[76:79], v[148:151], v[216:219], v[76:79]
	v_mfma_f32_16x16x32_bf16 v[72:75], v[152:155], v[212:215], v[72:75]
	v_mfma_f32_16x16x32_bf16 v[72:75], v[156:159], v[216:219], v[72:75]
	s_setprio 0
	s_barrier
; #define PG8_STAGE(bufoff, gbase, voff) do { _Pragma("unroll") for (int _i = 0; _i < 2; ++_i) \
;         __builtin_amdgcn_global_load_lds((const unsigned*)((const char*)(gbase) + (voff)[_i]), (LAS unsigned*)(lds + (bufoff) + ldsw + _i * 8192), 16, 0, 0); } while (0)
; #define PG8_LDA(dst, b, h) do { _Pragma("unroll") for (int m = 0; m < 4; ++m) _Pragma("unroll") for (int k = 0; k < 2; ++k) dst[m][k] = *(const LAS bf16x8*)(lds + PG8_SA(b, h) + aoff + m * 2048 + k * 1024); } while (0)
; #define PG8_MMA(ai, bj, At, Bt) do { __builtin_amdgcn_s_setprio(1); _Pragma("unroll") for (int m = 0; m < 4; ++m) _Pragma("unroll") for (int n = 0; n < 2; ++n) _Pragma("unroll") for (int k = 0; k < 2; ++k) \
;         acc[ai][bj][m][n] = __builtin_amdgcn_mfma_f32_16x16x32_bf16(Bt[n][k], At[m][k], acc[ai][bj][m][n], 0, 0, 0); __builtin_amdgcn_s_setprio(0); } while (0)
; #define PG8_WAIT_V(n) asm volatile("s_waitcnt vmcnt(" #n ")" ::: "memory")
; #define PG8_WAIT_L(n) asm volatile("s_waitcnt lgkmcnt(" #n ")" ::: "memory")
; #define PG8_BAR __builtin_amdgcn_s_barrier()
; #define PG8_SCHED __builtin_amdgcn_sched_barrier(0)
; template <bool ALIGN_EPI, class Epi, class Sched>
; __device__ __forceinline__ void gemm_phase(LAS unsigned char* lds, const int lda, const int ldb, const int K, const Sched& S, const Epi& E, const size_t kstepA = (size_t)(BK * 2), const size_t kstepB = (size_t)(BK * 2)) {
;     ...
;             PG8_LDA(At, 1, 1); PG8_STAGE(PG8_SB(1, 0), b3, voffB); PG8_STAGE(PG8_SB(1, 1), b3 + hstepB, voffB); PG8_STAGE(PG8_SA(1, 0), a3, voffA);
;             PG8_WAIT_V(8); PG8_WAIT_L(0); PG8_BAR; PG8_MMA(1, 0, At, B0); PG8_MMA(1, 1, At, B1); PG8_BAR; PG8_SCHED;
;         }
	s_add_u32 s54, s96, 0x40000
	s_addc_u32 s55, s97, 0
	s_add_i32 s56, s56, s18
	v_lshl_add_u64 v[220:221], s[54:55], 0, v[196:197]
	s_mov_b32 m0, s56
	ds_read_b128 v[160:163], v233 offset:49152
	ds_read_b128 v[164:167], v233 offset:50176
	ds_read_b128 v[168:171], v233 offset:51200
	ds_read_b128 v[172:175], v233 offset:52224
	ds_read_b128 v[176:179], v233 offset:53248
	ds_read_b128 v[180:183], v233 offset:54272
	ds_read_b128 v[212:215], v233 offset:55296
	ds_read_b128 v[216:219], v233 offset:56320
	global_load_lds_dwordx4 v[220:221], off
	s_add_i32 m0, s56, 0x2000
	v_lshl_add_u64 v[220:221], s[54:55], 0, v[200:201]
	s_add_u32 s54, s96, 0x44000
	s_addc_u32 s55, s97, 0
	s_add_i32 s56, s57, s18
	global_load_lds_dwordx4 v[220:221], off
	v_lshl_add_u64 v[220:221], s[54:55], 0, v[196:197]
	s_mov_b32 m0, s56
	s_nop 0
	global_load_lds_dwordx4 v[220:221], off
	v_lshl_add_u64 v[220:221], s[54:55], 0, v[200:201]
	s_add_i32 m0, s56, 0x2000
	s_nop 0
	global_load_lds_dwordx4 v[220:221], off
	v_lshl_add_u64 v[220:221], s[94:95], 0, v[194:195]
	s_mov_b32 m0, s30
	s_nop 0
	global_load_lds_dwordx4 v[220:221], off
	v_lshl_add_u64 v[220:221], s[94:95], 0, v[198:199]
	s_mov_b32 m0, s31
	s_nop 0
	global_load_lds_dwordx4 v[220:221], off
	s_waitcnt vmcnt(8)
	s_waitcnt lgkmcnt(0)
	s_barrier
	s_setprio 1
	s_waitcnt lgkmcnt(0)
	v_mfma_f32_16x16x32_bf16 v[60:63], v[64:67], v[160:163], v[60:63]
	v_mfma_f32_16x16x32_bf16 v[60:63], v[68:71], v[164:167], v[60:63]
	v_mfma_f32_16x16x32_bf16 v[56:59], v[80:83], v[160:163], v[56:59]
	v_mfma_f32_16x16x32_bf16 v[56:59], v[84:87], v[164:167], v[56:59]
	v_mfma_f32_16x16x32_bf16 v[44:47], v[64:67], v[168:171], v[44:47]
	v_mfma_f32_16x16x32_bf16 v[44:47], v[68:71], v[172:175], v[44:47]
	v_mfma_f32_16x16x32_bf16 v[40:43], v[80:83], v[168:171], v[40:43]
	v_mfma_f32_16x16x32_bf16 v[40:43], v[84:87], v[172:175], v[40:43]
	v_mfma_f32_16x16x32_bf16 v[28:31], v[64:67], v[176:179], v[28:31]
	v_mfma_f32_16x16x32_bf16 v[28:31], v[68:71], v[180:183], v[28:31]
	v_mfma_f32_16x16x32_bf16 v[24:27], v[80:83], v[176:179], v[24:27]
	v_mfma_f32_16x16x32_bf16 v[24:27], v[84:87], v[180:183], v[24:27]
	v_mfma_f32_16x16x32_bf16 v[12:15], v[64:67], v[212:215], v[12:15]
	v_mfma_f32_16x16x32_bf16 v[12:15], v[68:71], v[216:219], v[12:15]
	v_mfma_f32_16x16x32_bf16 v[8:11], v[80:83], v[212:215], v[8:11]
	v_mfma_f32_16x16x32_bf16 v[8:11], v[84:87], v[216:219], v[8:11]
	s_setprio 0
	s_setprio 1
	v_mfma_f32_16x16x32_bf16 v[52:55], v[144:147], v[160:163], v[52:55]
	v_mfma_f32_16x16x32_bf16 v[52:55], v[148:151], v[164:167], v[52:55]
	v_mfma_f32_16x16x32_bf16 v[48:51], v[152:155], v[160:163], v[48:51]
	v_mfma_f32_16x16x32_bf16 v[48:51], v[156:159], v[164:167], v[48:51]
	v_mfma_f32_16x16x32_bf16 v[36:39], v[144:147], v[168:171], v[36:39]
	v_mfma_f32_16x16x32_bf16 v[36:39], v[148:151], v[172:175], v[36:39]
	v_mfma_f32_16x16x32_bf16 v[32:35], v[152:155], v[168:171], v[32:35]
	v_mfma_f32_16x16x32_bf16 v[32:35], v[156:159], v[172:175], v[32:35]
	v_mfma_f32_16x16x32_bf16 v[20:23], v[144:147], v[176:179], v[20:23]
	v_mfma_f32_16x16x32_bf16 v[20:23], v[148:151], v[180:183], v[20:23]
	v_mfma_f32_16x16x32_bf16 v[16:19], v[152:155], v[176:179], v[16:19]
	v_mfma_f32_16x16x32_bf16 v[16:19], v[156:159], v[180:183], v[16:19]
	v_mfma_f32_16x16x32_bf16 v[4:7], v[144:147], v[212:215], v[4:7]
	v_mfma_f32_16x16x32_bf16 v[4:7], v[148:151], v[216:219], v[4:7]
	v_mfma_f32_16x16x32_bf16 v[0:3], v[152:155], v[212:215], v[0:3]
	v_mfma_f32_16x16x32_bf16 v[0:3], v[156:159], v[216:219], v[0:3]
	s_setprio 0
	s_barrier
	s_add_i32 s51, s51, 2
	s_add_u32 s13, s13, 0x80000
	s_addc_u32 s50, s50, 0
	s_add_u32 s82, s82, 0x400000
	s_addc_u32 s83, s83, 0
	s_cmpk_gt_u32 s51, 0x55
	s_cbranch_scc0 .LBB0_218
	s_and_b64 vcc, exec, s[84:85]
	s_cbranch_vccz .LBB0_221
	s_barrier

; #define PG8_STAGE(bufoff, gbase, voff) do { _Pragma("unroll") for (int _i = 0; _i < 2; ++_i) \
;         __builtin_amdgcn_global_load_lds((const unsigned*)((const char*)(gbase) + (voff)[_i]), (LAS unsigned*)(lds + (bufoff) + ldsw + _i * 8192), 16, 0, 0); } while (0)
; #define PG8_LDA(dst, b, h) do { _Pragma("unroll") for (int m = 0; m < 4; ++m) _Pragma("unroll") for (int k = 0; k < 2; ++k) dst[m][k] = *(const LAS bf16x8*)(lds + PG8_SA(b, h) + aoff + m * 2048 + k * 1024); } while (0)
; #define PG8_LDB(dst, b, h) do { _Pragma("unroll") for (int n = 0; n < 2; ++n) _Pragma("unroll") for (int k = 0; k < 2; ++k) dst[n][k] = *(const LAS bf16x8*)(lds + PG8_SB(b, h) + boff + n * 2048 + k * 1024); } while (0)
; #define PG8_MMA(ai, bj, At, Bt) do { __builtin_amdgcn_s_setprio(1); _Pragma("unroll") for (int m = 0; m < 4; ++m) _Pragma("unroll") for (int n = 0; n < 2; ++n) _Pragma("unroll") for (int k = 0; k < 2; ++k) \
;         acc[ai][bj][m][n] = __builtin_amdgcn_mfma_f32_16x16x32_bf16(Bt[n][k], At[m][k], acc[ai][bj][m][n], 0, 0, 0); __builtin_amdgcn_s_setprio(0); } while (0)
; #define PG8_WAIT_V(n) asm volatile("s_waitcnt vmcnt(" #n ")" ::: "memory")
; #define PG8_WAIT_L(n) asm volatile("s_waitcnt lgkmcnt(" #n ")" ::: "memory")
; template <bool ALIGN_EPI, class Epi, class Sched>
; __device__ __forceinline__ void gemm_phase(LAS unsigned char* lds, const int lda, const int ldb, const int K, const Sched& S, const Epi& E, const size_t kstepA = (size_t)(BK * 2), const size_t kstepB = (size_t)(BK * 2)) {
;     ...
;         for (int t = 0; t < nt; t += 2) {
;             const bool last = (t == nt - 2);
;             const char* a1 = cA + (size_t)(t + 1) * kstepA;
;             const char* a2 = last ? nA : cA + (size_t)(t + 2) * kstepA; const char* b2 = last ? nB : cB + (size_t)(t + 2) * kstep;
;             const char* a3 = a2 + kstepA; const char* b3 = b2 + kstep;
;             PG8_LDB(B0, 0, 0); PG8_LDB(B1, 0, 1); PG8_SCHED; PG8_LDA(At, 0, 0); PG8_STAGE(PG8_SA(1, 1), a1 + hstepA, voffA);
;             PG8_WAIT_V(8); PG8_WAIT_L(0); PG8_BAR; PG8_MMA(0, 0, At, B0); PG8_MMA(0, 1, At, B1); PG8_BAR; PG8_SCHED;
;             PG8_LDA(At, 0, 1); PG8_STAGE(PG8_SB(0, 0), b2, voffB); PG8_STAGE(PG8_SB(0, 1), b2 + hstepB, voffB); PG8_STAGE(PG8_SA(0, 0), a2, voffA);
;             PG8_WAIT_V(8); PG8_WAIT_L(0); PG8_BAR; PG8_MMA(1, 0, At, B0); PG8_MMA(1, 1, At, B1); PG8_BAR; PG8_SCHED;
.LBB0_261:
	s_add_u32 s60, s6, s16
	s_addc_u32 s61, s7, s17
	s_add_u32 s64, s60, 0x100
	s_addc_u32 s65, s61, 0
	s_and_b64 s[48:49], s[14:15], exec
	s_cselect_b32 s49, s7, s65
	s_cselect_b32 s48, s6, s64
	s_add_u32 s16, s8, s16
	s_addc_u32 s17, s9, s17
	s_add_u32 s16, s16, 0x100
	ds_read_b128 v[144:147], v138
	ds_read_b128 v[148:151], v138 offset:1024
	ds_read_b128 v[152:155], v138 offset:2048
	ds_read_b128 v[156:159], v138 offset:3072
	ds_read_b128 v[160:163], v139
	ds_read_b128 v[164:167], v139 offset:1024
	ds_read_b128 v[168:171], v139 offset:2048
	ds_read_b128 v[172:175], v139 offset:3072
	s_addc_u32 s17, s17, 0
	s_and_b64 s[14:15], s[14:15], exec
	s_cselect_b32 s67, s9, s17
	s_cselect_b32 s66, s8, s16
	s_add_u32 s70, s60, 0x10080
	s_addc_u32 s71, s61, 0
	s_add_u32 s68, s66, 0x40000
	s_addc_u32 s69, s67, 0
	s_add_u32 s16, s48, 0x10000
	s_addc_u32 s17, s49, 0
	s_add_u32 s14, s66, 0x40080
	s_addc_u32 s15, s67, 0
	s_mov_b32 m0, s42
	v_lshl_add_u64 v[218:219], s[70:71], 0, v[134:135]
	ds_read_b128 v[176:179], v140
	ds_read_b128 v[180:183], v140 offset:1024
	ds_read_b128 v[194:197], v140 offset:2048
	ds_read_b128 v[198:201], v140 offset:3072
	ds_read_b128 v[202:205], v140 offset:4096
	ds_read_b128 v[206:209], v140 offset:5120
	ds_read_b128 v[210:213], v140 offset:6144
	ds_read_b128 v[214:217], v140 offset:7168
	global_load_lds_dwordx4 v[218:219], off
	v_lshl_add_u64 v[218:219], s[70:71], 0, v[130:131]
	s_mov_b32 m0, s43
	s_nop 0
	global_load_lds_dwordx4 v[218:219], off
	s_waitcnt vmcnt(8)
	s_waitcnt lgkmcnt(0)
	s_barrier
	s_setprio 1
	s_waitcnt lgkmcnt(0)
	v_mfma_f32_16x16x32_bf16 v[124:127], v[144:147], v[176:179], v[124:127]
	v_mfma_f32_16x16x32_bf16 v[124:127], v[148:151], v[180:183], v[124:127]
	v_mfma_f32_16x16x32_bf16 v[120:123], v[152:155], v[176:179], v[120:123]
	v_mfma_f32_16x16x32_bf16 v[120:123], v[156:159], v[180:183], v[120:123]
	v_mfma_f32_16x16x32_bf16 v[116:119], v[144:147], v[194:197], v[116:119]
	v_mfma_f32_16x16x32_bf16 v[116:119], v[148:151], v[198:201], v[116:119]
	v_mfma_f32_16x16x32_bf16 v[108:111], v[152:155], v[194:197], v[108:111]
	v_mfma_f32_16x16x32_bf16 v[108:111], v[156:159], v[198:201], v[108:111]
	v_mfma_f32_16x16x32_bf16 v[100:103], v[144:147], v[202:205], v[100:103]
	v_mfma_f32_16x16x32_bf16 v[100:103], v[148:151], v[206:209], v[100:103]
	v_mfma_f32_16x16x32_bf16 v[96:99], v[152:155], v[202:205], v[96:99]
	v_mfma_f32_16x16x32_bf16 v[96:99], v[156:159], v[206:209], v[96:99]
	v_mfma_f32_16x16x32_bf16 v[84:87], v[144:147], v[210:213], v[84:87]
	v_mfma_f32_16x16x32_bf16 v[84:87], v[148:151], v[214:217], v[84:87]
	v_mfma_f32_16x16x32_bf16 v[80:83], v[152:155], v[210:213], v[80:83]
	v_mfma_f32_16x16x32_bf16 v[80:83], v[156:159], v[214:217], v[80:83]
	s_setprio 0
	s_setprio 1
	v_mfma_f32_16x16x32_bf16 v[112:115], v[160:163], v[176:179], v[112:115]
	v_mfma_f32_16x16x32_bf16 v[112:115], v[164:167], v[180:183], v[112:115]
	v_mfma_f32_16x16x32_bf16 v[104:107], v[168:171], v[176:179], v[104:107]
	v_mfma_f32_16x16x32_bf16 v[104:107], v[172:175], v[180:183], v[104:107]
	v_mfma_f32_16x16x32_bf16 v[92:95], v[160:163], v[194:197], v[92:95]
	v_mfma_f32_16x16x32_bf16 v[92:95], v[164:167], v[198:201], v[92:95]
	v_mfma_f32_16x16x32_bf16 v[88:91], v[168:171], v[194:197], v[88:91]
	v_mfma_f32_16x16x32_bf16 v[88:91], v[172:175], v[198:201], v[88:91]
	v_mfma_f32_16x16x32_bf16 v[76:79], v[160:163], v[202:205], v[76:79]
	v_mfma_f32_16x16x32_bf16 v[76:79], v[164:167], v[206:209], v[76:79]
	v_mfma_f32_16x16x32_bf16 v[72:75], v[168:171], v[202:205], v[72:75]
	v_mfma_f32_16x16x32_bf16 v[72:75], v[172:175], v[206:209], v[72:75]
	v_mfma_f32_16x16x32_bf16 v[68:71], v[160:163], v[210:213], v[68:71]
	v_mfma_f32_16x16x32_bf16 v[68:71], v[164:167], v[214:217], v[68:71]
	v_mfma_f32_16x16x32_bf16 v[64:67], v[168:171], v[210:213], v[64:67]
	v_mfma_f32_16x16x32_bf16 v[64:67], v[172:175], v[214:217], v[64:67]
	s_setprio 0
	s_barrier
	s_mov_b32 m0, s50
	v_lshl_add_u64 v[218:219], s[66:67], 0, v[132:133]
	ds_read_b128 v[176:179], v140 offset:16384
	ds_read_b128 v[180:183], v140 offset:17408
	ds_read_b128 v[194:197], v140 offset:18432
	ds_read_b128 v[198:201], v140 offset:19456
	ds_read_b128 v[202:205], v140 offset:20480
	ds_read_b128 v[206:209], v140 offset:21504
	ds_read_b128 v[210:213], v140 offset:22528
	ds_read_b128 v[214:217], v140 offset:23552
	global_load_lds_dwordx4 v[218:219], off
	v_lshl_add_u64 v[220:221], s[66:67], 0, v[128:129]
	s_mov_b32 m0, s51
	v_lshl_add_u64 v[222:223], s[68:69], 0, v[132:133]
	global_load_lds_dwordx4 v[220:221], off
	s_mov_b32 m0, s54
	v_lshl_add_u64 v[224:225], s[48:49], 0, v[130:131]
	global_load_lds_dwordx4 v[222:223], off
	v_lshl_add_u64 v[222:223], s[68:69], 0, v[128:129]
	s_mov_b32 m0, s55
	s_nop 0
	global_load_lds_dwordx4 v[222:223], off
	v_lshl_add_u64 v[222:223], s[48:49], 0, v[134:135]
	s_mov_b32 m0, s20
	s_nop 0
	global_load_lds_dwordx4 v[222:223], off
	s_mov_b32 m0, s21
	s_nop 0
	global_load_lds_dwordx4 v[224:225], off
	s_waitcnt vmcnt(8)
	s_waitcnt lgkmcnt(0)
	s_barrier
; #define PG8_STAGE(bufoff, gbase, voff) do { _Pragma("unroll") for (int _i = 0; _i < 2; ++_i) \
;         __builtin_amdgcn_global_load_lds((const unsigned*)((const char*)(gbase) + (voff)[_i]), (LAS unsigned*)(lds + (bufoff) + ldsw + _i * 8192), 16, 0, 0); } while (0)
; #define PG8_LDA(dst, b, h) do { _Pragma("unroll") for (int m = 0; m < 4; ++m) _Pragma("unroll") for (int k = 0; k < 2; ++k) dst[m][k] = *(const LAS bf16x8*)(lds + PG8_SA(b, h) + aoff + m * 2048 + k * 1024); } while (0)
; #define PG8_LDB(dst, b, h) do { _Pragma("unroll") for (int n = 0; n < 2; ++n) _Pragma("unroll") for (int k = 0; k < 2; ++k) dst[n][k] = *(const LAS bf16x8*)(lds + PG8_SB(b, h) + boff + n * 2048 + k * 1024); } while (0)
; #define PG8_MMA(ai, bj, At, Bt) do { __builtin_amdgcn_s_setprio(1); _Pragma("unroll") for (int m = 0; m < 4; ++m) _Pragma("unroll") for (int n = 0; n < 2; ++n) _Pragma("unroll") for (int k = 0; k < 2; ++k) \
;         acc[ai][bj][m][n] = __builtin_amdgcn_mfma_f32_16x16x32_bf16(Bt[n][k], At[m][k], acc[ai][bj][m][n], 0, 0, 0); __builtin_amdgcn_s_setprio(0); } while (0)
; #define PG8_WAIT_V(n) asm volatile("s_waitcnt vmcnt(" #n ")" ::: "memory")
; #define PG8_WAIT_L(n) asm volatile("s_waitcnt lgkmcnt(" #n ")" ::: "memory")
; #define PG8_BAR __builtin_amdgcn_s_barrier()
; #define PG8_SCHED __builtin_amdgcn_sched_barrier(0)
; template <bool ALIGN_EPI, class Epi, class Sched>
; __device__ __forceinline__ void gemm_phase(LAS unsigned char* lds, const int lda, const int ldb, const int K, const Sched& S, const Epi& E, const size_t kstepA = (size_t)(BK * 2), const size_t kstepB = (size_t)(BK * 2)) {
;     ...
;             PG8_WAIT_V(8); PG8_WAIT_L(0); PG8_BAR; PG8_MMA(1, 0, At, B0); PG8_MMA(1, 1, At, B1); PG8_BAR; PG8_SCHED;
;             PG8_LDB(B0, 1, 0); PG8_LDB(B1, 1, 1); PG8_SCHED; PG8_LDA(At, 1, 0); PG8_STAGE(PG8_SA(0, 1), a2 + hstepA, voffA);
;             PG8_WAIT_V(8); PG8_WAIT_L(0); PG8_BAR; PG8_MMA(0, 0, At, B0); PG8_MMA(0, 1, At, B1); PG8_BAR; PG8_SCHED;
	s_setprio 1
	s_waitcnt lgkmcnt(0)
	v_mfma_f32_16x16x32_bf16 v[60:63], v[144:147], v[176:179], v[60:63]
	v_mfma_f32_16x16x32_bf16 v[60:63], v[148:151], v[180:183], v[60:63]
	v_mfma_f32_16x16x32_bf16 v[56:59], v[152:155], v[176:179], v[56:59]
	v_mfma_f32_16x16x32_bf16 v[56:59], v[156:159], v[180:183], v[56:59]
	v_mfma_f32_16x16x32_bf16 v[52:55], v[144:147], v[194:197], v[52:55]
	v_mfma_f32_16x16x32_bf16 v[52:55], v[148:151], v[198:201], v[52:55]
	v_mfma_f32_16x16x32_bf16 v[48:51], v[152:155], v[194:197], v[48:51]
	v_mfma_f32_16x16x32_bf16 v[48:51], v[156:159], v[198:201], v[48:51]
	v_mfma_f32_16x16x32_bf16 v[36:39], v[144:147], v[202:205], v[36:39]
	v_mfma_f32_16x16x32_bf16 v[36:39], v[148:151], v[206:209], v[36:39]
	v_mfma_f32_16x16x32_bf16 v[32:35], v[152:155], v[202:205], v[32:35]
	v_mfma_f32_16x16x32_bf16 v[32:35], v[156:159], v[206:209], v[32:35]
	v_mfma_f32_16x16x32_bf16 v[20:23], v[144:147], v[210:213], v[20:23]
	v_mfma_f32_16x16x32_bf16 v[20:23], v[148:151], v[214:217], v[20:23]
	v_mfma_f32_16x16x32_bf16 v[16:19], v[152:155], v[210:213], v[16:19]
	v_mfma_f32_16x16x32_bf16 v[16:19], v[156:159], v[214:217], v[16:19]
	s_setprio 0
	s_setprio 1
	v_mfma_f32_16x16x32_bf16 v[44:47], v[160:163], v[176:179], v[44:47]
	v_mfma_f32_16x16x32_bf16 v[44:47], v[164:167], v[180:183], v[44:47]
	v_mfma_f32_16x16x32_bf16 v[40:43], v[168:171], v[176:179], v[40:43]
	v_mfma_f32_16x16x32_bf16 v[40:43], v[172:175], v[180:183], v[40:43]
	v_mfma_f32_16x16x32_bf16 v[28:31], v[160:163], v[194:197], v[28:31]
	v_mfma_f32_16x16x32_bf16 v[28:31], v[164:167], v[198:201], v[28:31]
	v_mfma_f32_16x16x32_bf16 v[24:27], v[168:171], v[194:197], v[24:27]
	v_mfma_f32_16x16x32_bf16 v[24:27], v[172:175], v[198:201], v[24:27]
	v_mfma_f32_16x16x32_bf16 v[12:15], v[160:163], v[202:205], v[12:15]
	v_mfma_f32_16x16x32_bf16 v[12:15], v[164:167], v[206:209], v[12:15]
	v_mfma_f32_16x16x32_bf16 v[8:11], v[168:171], v[202:205], v[8:11]
	v_mfma_f32_16x16x32_bf16 v[8:11], v[172:175], v[206:209], v[8:11]
	v_mfma_f32_16x16x32_bf16 v[4:7], v[160:163], v[210:213], v[4:7]
	v_mfma_f32_16x16x32_bf16 v[4:7], v[164:167], v[214:217], v[4:7]
	v_mfma_f32_16x16x32_bf16 v[0:3], v[168:171], v[210:213], v[0:3]
	v_mfma_f32_16x16x32_bf16 v[0:3], v[172:175], v[214:217], v[0:3]
	s_setprio 0
	s_barrier
	ds_read_b128 v[144:147], v141
	ds_read_b128 v[148:151], v141 offset:1024
	ds_read_b128 v[152:155], v141 offset:2048
	ds_read_b128 v[156:159], v141 offset:3072
	ds_read_b128 v[160:163], v142
	ds_read_b128 v[164:167], v142 offset:1024
	ds_read_b128 v[168:171], v142 offset:2048
	ds_read_b128 v[172:175], v142 offset:3072
	s_mov_b32 m0, s22
	v_lshl_add_u64 v[226:227], s[16:17], 0, v[134:135]
	ds_read_b128 v[176:179], v140 offset:32768
	ds_read_b128 v[180:183], v140 offset:33792
	ds_read_b128 v[194:197], v140 offset:34816
	ds_read_b128 v[198:201], v140 offset:35840
	ds_read_b128 v[202:205], v140 offset:36864
	ds_read_b128 v[206:209], v140 offset:37888
	ds_read_b128 v[210:213], v140 offset:38912
	ds_read_b128 v[214:217], v140 offset:39936
	global_load_lds_dwordx4 v[226:227], off
	v_lshl_add_u64 v[226:227], s[16:17], 0, v[130:131]
	s_mov_b32 m0, s29
	s_nop 0
	global_load_lds_dwordx4 v[226:227], off
	s_waitcnt vmcnt(8)
	s_waitcnt lgkmcnt(0)
	s_barrier
	s_setprio 1
	s_waitcnt lgkmcnt(0)
	v_mfma_f32_16x16x32_bf16 v[124:127], v[144:147], v[176:179], v[124:127]
	v_mfma_f32_16x16x32_bf16 v[124:127], v[148:151], v[180:183], v[124:127]
	v_mfma_f32_16x16x32_bf16 v[120:123], v[152:155], v[176:179], v[120:123]
	v_mfma_f32_16x16x32_bf16 v[120:123], v[156:159], v[180:183], v[120:123]
	v_mfma_f32_16x16x32_bf16 v[116:119], v[144:147], v[194:197], v[116:119]
	v_mfma_f32_16x16x32_bf16 v[116:119], v[148:151], v[198:201], v[116:119]
	v_mfma_f32_16x16x32_bf16 v[108:111], v[152:155], v[194:197], v[108:111]
	v_mfma_f32_16x16x32_bf16 v[108:111], v[156:159], v[198:201], v[108:111]
	v_mfma_f32_16x16x32_bf16 v[100:103], v[144:147], v[202:205], v[100:103]
	v_mfma_f32_16x16x32_bf16 v[100:103], v[148:151], v[206:209], v[100:103]
	v_mfma_f32_16x16x32_bf16 v[96:99], v[152:155], v[202:205], v[96:99]
	v_mfma_f32_16x16x32_bf16 v[96:99], v[156:159], v[206:209], v[96:99]
	v_mfma_f32_16x16x32_bf16 v[84:87], v[144:147], v[210:213], v[84:87]
	v_mfma_f32_16x16x32_bf16 v[84:87], v[148:151], v[214:217], v[84:87]
	v_mfma_f32_16x16x32_bf16 v[80:83], v[152:155], v[210:213], v[80:83]
	v_mfma_f32_16x16x32_bf16 v[80:83], v[156:159], v[214:217], v[80:83]
	s_setprio 0
	s_setprio 1
	v_mfma_f32_16x16x32_bf16 v[112:115], v[160:163], v[176:179], v[112:115]
	v_mfma_f32_16x16x32_bf16 v[112:115], v[164:167], v[180:183], v[112:115]
	v_mfma_f32_16x16x32_bf16 v[104:107], v[168:171], v[176:179], v[104:107]
	v_mfma_f32_16x16x32_bf16 v[104:107], v[172:175], v[180:183], v[104:107]
	v_mfma_f32_16x16x32_bf16 v[92:95], v[160:163], v[194:197], v[92:95]
	v_mfma_f32_16x16x32_bf16 v[92:95], v[164:167], v[198:201], v[92:95]
	v_mfma_f32_16x16x32_bf16 v[88:91], v[168:171], v[194:197], v[88:91]
	v_mfma_f32_16x16x32_bf16 v[88:91], v[172:175], v[198:201], v[88:91]
	v_mfma_f32_16x16x32_bf16 v[76:79], v[160:163], v[202:205], v[76:79]
	v_mfma_f32_16x16x32_bf16 v[76:79], v[164:167], v[206:209], v[76:79]
	v_mfma_f32_16x16x32_bf16 v[72:75], v[168:171], v[202:205], v[72:75]
	v_mfma_f32_16x16x32_bf16 v[72:75], v[172:175], v[206:209], v[72:75]
	v_mfma_f32_16x16x32_bf16 v[68:71], v[160:163], v[210:213], v[68:71]
	v_mfma_f32_16x16x32_bf16 v[68:71], v[164:167], v[214:217], v[68:71]
	v_mfma_f32_16x16x32_bf16 v[64:67], v[168:171], v[210:213], v[64:67]
	v_mfma_f32_16x16x32_bf16 v[64:67], v[172:175], v[214:217], v[64:67]
	s_setprio 0
	s_barrier
; #define PG8_STAGE(bufoff, gbase, voff) do { _Pragma("unroll") for (int _i = 0; _i < 2; ++_i) \
;         __builtin_amdgcn_global_load_lds((const unsigned*)((const char*)(gbase) + (voff)[_i]), (LAS unsigned*)(lds + (bufoff) + ldsw + _i * 8192), 16, 0, 0); } while (0)
; #define PG8_LDA(dst, b, h) do { _Pragma("unroll") for (int m = 0; m < 4; ++m) _Pragma("unroll") for (int k = 0; k < 2; ++k) dst[m][k] = *(const LAS bf16x8*)(lds + PG8_SA(b, h) + aoff + m * 2048 + k * 1024); } while (0)
; #define PG8_MMA(ai, bj, At, Bt) do { __builtin_amdgcn_s_setprio(1); _Pragma("unroll") for (int m = 0; m < 4; ++m) _Pragma("unroll") for (int n = 0; n < 2; ++n) _Pragma("unroll") for (int k = 0; k < 2; ++k) \
;         acc[ai][bj][m][n] = __builtin_amdgcn_mfma_f32_16x16x32_bf16(Bt[n][k], At[m][k], acc[ai][bj][m][n], 0, 0, 0); __builtin_amdgcn_s_setprio(0); } while (0)
; #define PG8_WAIT_V(n) asm volatile("s_waitcnt vmcnt(" #n ")" ::: "memory")
; #define PG8_WAIT_L(n) asm volatile("s_waitcnt lgkmcnt(" #n ")" ::: "memory")
; #define PG8_BAR __builtin_amdgcn_s_barrier()
; #define PG8_SCHED __builtin_amdgcn_sched_barrier(0)
; template <bool ALIGN_EPI, class Epi, class Sched>
; __device__ __forceinline__ void gemm_phase(LAS unsigned char* lds, const int lda, const int ldb, const int K, const Sched& S, const Epi& E, const size_t kstepA = (size_t)(BK * 2), const size_t kstepB = (size_t)(BK * 2)) {
;     ...
;             PG8_LDA(At, 1, 1); PG8_STAGE(PG8_SB(1, 0), b3, voffB); PG8_STAGE(PG8_SB(1, 1), b3 + hstepB, voffB); PG8_STAGE(PG8_SA(1, 0), a3, voffA);
;             PG8_WAIT_V(8); PG8_WAIT_L(0); PG8_BAR; PG8_MMA(1, 0, At, B0); PG8_MMA(1, 1, At, B1); PG8_BAR; PG8_SCHED;
;         }
	s_mov_b32 m0, s56
	v_lshl_add_u64 v[218:219], v[218:219], 0, s[10:11]
	ds_read_b128 v[176:179], v140 offset:49152
	ds_read_b128 v[180:183], v140 offset:50176
	ds_read_b128 v[194:197], v140 offset:51200
	ds_read_b128 v[198:201], v140 offset:52224
	ds_read_b128 v[202:205], v140 offset:53248
	ds_read_b128 v[206:209], v140 offset:54272
	ds_read_b128 v[210:213], v140 offset:55296
	ds_read_b128 v[214:217], v140 offset:56320
	global_load_lds_dwordx4 v[218:219], off
	v_lshl_add_u64 v[218:219], v[220:221], 0, s[10:11]
	s_mov_b32 m0, s57
	s_nop 0
	global_load_lds_dwordx4 v[218:219], off
	v_lshl_add_u64 v[218:219], s[14:15], 0, v[132:133]
	s_mov_b32 m0, s58
	s_nop 0
	global_load_lds_dwordx4 v[218:219], off
	v_lshl_add_u64 v[218:219], s[14:15], 0, v[128:129]
	s_mov_b32 m0, s59
	s_nop 0
	global_load_lds_dwordx4 v[218:219], off
	v_lshl_add_u64 v[218:219], v[222:223], 0, s[10:11]
	s_mov_b32 m0, s31
	s_nop 0
	global_load_lds_dwordx4 v[218:219], off
	v_lshl_add_u64 v[218:219], v[224:225], 0, s[10:11]
	s_mov_b32 m0, s33
	s_nop 0
	global_load_lds_dwordx4 v[218:219], off
	s_waitcnt vmcnt(8)
	s_waitcnt lgkmcnt(0)
	s_barrier
	s_setprio 1
	s_waitcnt lgkmcnt(0)
	v_mfma_f32_16x16x32_bf16 v[60:63], v[144:147], v[176:179], v[60:63]
	v_mfma_f32_16x16x32_bf16 v[60:63], v[148:151], v[180:183], v[60:63]
	v_mfma_f32_16x16x32_bf16 v[56:59], v[152:155], v[176:179], v[56:59]
	v_mfma_f32_16x16x32_bf16 v[56:59], v[156:159], v[180:183], v[56:59]
	v_mfma_f32_16x16x32_bf16 v[52:55], v[144:147], v[194:197], v[52:55]
	v_mfma_f32_16x16x32_bf16 v[52:55], v[148:151], v[198:201], v[52:55]
	v_mfma_f32_16x16x32_bf16 v[48:51], v[152:155], v[194:197], v[48:51]
	v_mfma_f32_16x16x32_bf16 v[48:51], v[156:159], v[198:201], v[48:51]
	v_mfma_f32_16x16x32_bf16 v[36:39], v[144:147], v[202:205], v[36:39]
	v_mfma_f32_16x16x32_bf16 v[36:39], v[148:151], v[206:209], v[36:39]
	v_mfma_f32_16x16x32_bf16 v[32:35], v[152:155], v[202:205], v[32:35]
	v_mfma_f32_16x16x32_bf16 v[32:35], v[156:159], v[206:209], v[32:35]
	v_mfma_f32_16x16x32_bf16 v[20:23], v[144:147], v[210:213], v[20:23]
	v_mfma_f32_16x16x32_bf16 v[20:23], v[148:151], v[214:217], v[20:23]
	v_mfma_f32_16x16x32_bf16 v[16:19], v[152:155], v[210:213], v[16:19]
	v_mfma_f32_16x16x32_bf16 v[16:19], v[156:159], v[214:217], v[16:19]
	s_setprio 0
	s_setprio 1
	v_mfma_f32_16x16x32_bf16 v[44:47], v[160:163], v[176:179], v[44:47]
	v_mfma_f32_16x16x32_bf16 v[44:47], v[164:167], v[180:183], v[44:47]
	v_mfma_f32_16x16x32_bf16 v[40:43], v[168:171], v[176:179], v[40:43]
	v_mfma_f32_16x16x32_bf16 v[40:43], v[172:175], v[180:183], v[40:43]
	v_mfma_f32_16x16x32_bf16 v[28:31], v[160:163], v[194:197], v[28:31]
	v_mfma_f32_16x16x32_bf16 v[28:31], v[164:167], v[198:201], v[28:31]
	v_mfma_f32_16x16x32_bf16 v[24:27], v[168:171], v[194:197], v[24:27]
	v_mfma_f32_16x16x32_bf16 v[24:27], v[172:175], v[198:201], v[24:27]
	v_mfma_f32_16x16x32_bf16 v[12:15], v[160:163], v[202:205], v[12:15]
	v_mfma_f32_16x16x32_bf16 v[12:15], v[164:167], v[206:209], v[12:15]
	v_mfma_f32_16x16x32_bf16 v[8:11], v[168:171], v[202:205], v[8:11]
	v_mfma_f32_16x16x32_bf16 v[8:11], v[172:175], v[206:209], v[8:11]
	v_mfma_f32_16x16x32_bf16 v[4:7], v[160:163], v[210:213], v[4:7]
	v_mfma_f32_16x16x32_bf16 v[4:7], v[164:167], v[214:217], v[4:7]
	v_mfma_f32_16x16x32_bf16 v[0:3], v[168:171], v[210:213], v[0:3]
	v_mfma_f32_16x16x32_bf16 v[0:3], v[172:175], v[214:217], v[0:3]
	s_setprio 0
	s_barrier
	s_andn2_b64 vcc, exec, s[12:13]
	s_mov_b64 s[14:15], -1
	s_mov_b64 s[12:13], 0
	s_mov_b64 s[16:17], 0x100
	s_cbranch_vccz .LBB0_261
	s_cmpk_lt_u32 s18, 0x100
	s_cbranch_scc0 .LBB0_264
	s_barrier

; #define PG8_STAGE(bufoff, gbase, voff) do { _Pragma("unroll") for (int _i = 0; _i < 2; ++_i) \
;         __builtin_amdgcn_global_load_lds((const unsigned*)((const char*)(gbase) + (voff)[_i]), (LAS unsigned*)(lds + (bufoff) + ldsw + _i * 8192), 16, 0, 0); } while (0)
; #define PG8_LDA(dst, b, h) do { _Pragma("unroll") for (int m = 0; m < 4; ++m) _Pragma("unroll") for (int k = 0; k < 2; ++k) dst[m][k] = *(const LAS bf16x8*)(lds + PG8_SA(b, h) + aoff + m * 2048 + k * 1024); } while (0)
; #define PG8_LDB(dst, b, h) do { _Pragma("unroll") for (int n = 0; n < 2; ++n) _Pragma("unroll") for (int k = 0; k < 2; ++k) dst[n][k] = *(const LAS bf16x8*)(lds + PG8_SB(b, h) + boff + n * 2048 + k * 1024); } while (0)
; #define PG8_MMA(ai, bj, At, Bt) do { __builtin_amdgcn_s_setprio(1); _Pragma("unroll") for (int m = 0; m < 4; ++m) _Pragma("unroll") for (int n = 0; n < 2; ++n) _Pragma("unroll") for (int k = 0; k < 2; ++k) \
;         acc[ai][bj][m][n] = __builtin_amdgcn_mfma_f32_16x16x32_bf16(Bt[n][k], At[m][k], acc[ai][bj][m][n], 0, 0, 0); __builtin_amdgcn_s_setprio(0); } while (0)
; #define PG8_WAIT_V(n) asm volatile("s_waitcnt vmcnt(" #n ")" ::: "memory")
; #define PG8_WAIT_L(n) asm volatile("s_waitcnt lgkmcnt(" #n ")" ::: "memory")
; #define PG8_BAR __builtin_amdgcn_s_barrier()
; #define PG8_SCHED __builtin_amdgcn_sched_barrier(0)
; template <bool ALIGN_EPI, class Epi, class Sched>
; __device__ __forceinline__ void gemm_phase(LAS unsigned char* lds, const int lda, const int ldb, const int K, const Sched& S, const Epi& E, const size_t kstepA = (size_t)(BK * 2), const size_t kstepB = (size_t)(BK * 2)) {
;     ...
;         for (int t = 0; t < nt; t += 2) {
;             const bool last = (t == nt - 2);
;             const char* a1 = cA + (size_t)(t + 1) * kstepA;
;             const char* a2 = last ? nA : cA + (size_t)(t + 2) * kstepA; const char* b2 = last ? nB : cB + (size_t)(t + 2) * kstep;
;             const char* a3 = a2 + kstepA; const char* b3 = b2 + kstep;
;             PG8_LDB(B0, 0, 0); PG8_LDB(B1, 0, 1); PG8_SCHED; PG8_LDA(At, 0, 0); PG8_STAGE(PG8_SA(1, 1), a1 + hstepA, voffA);
;             PG8_WAIT_V(8); PG8_WAIT_L(0); PG8_BAR; PG8_MMA(0, 0, At, B0); PG8_MMA(0, 1, At, B1); PG8_BAR; PG8_SCHED;
;             PG8_LDA(At, 0, 1); PG8_STAGE(PG8_SB(0, 0), b2, voffB); PG8_STAGE(PG8_SB(0, 1), b2 + hstepB, voffB); PG8_STAGE(PG8_SA(0, 0), a2, voffA);
.LBB0_347:
	ds_read_b128 v[158:161], v195
	ds_read_b128 v[162:165], v195 offset:1024
	ds_read_b128 v[166:169], v195 offset:2048
	ds_read_b128 v[198:201], v195 offset:3072
	ds_read_b128 v[202:205], v196
	ds_read_b128 v[206:209], v196 offset:1024
	ds_read_b128 v[210:213], v196 offset:2048
	ds_read_b128 v[214:217], v196 offset:3072
	s_add_u32 s59, s16, 0x1fc000
	s_addc_u32 s60, s17, 0
	s_cmp_eq_u32 s58, 28
	s_cselect_b32 s94, s6, s59
	s_cselect_b32 s95, s7, s60
	s_cselect_b32 s92, s14, s55
	s_cselect_b32 s93, s15, s57
	s_add_u32 s82, s94, 0x200000
	s_addc_u32 s83, s95, 0
	v_lshl_add_u64 v[170:171], s[16:17], 0, v[150:151]
	s_add_i32 m0, s20, 0xc000
	ds_read_b128 v[218:221], v193
	ds_read_b128 v[222:225], v193 offset:1024
	ds_read_b128 v[226:229], v193 offset:2048
	ds_read_b128 v[230:233], v193 offset:3072
	ds_read_b128 v[234:237], v193 offset:4096
	ds_read_b128 v[238:241], v193 offset:5120
	ds_read_b128 v[242:245], v193 offset:6144
	ds_read_b128 v[246:249], v193 offset:7168
	global_load_lds_dwordx4 v[170:171], off
	v_lshl_add_u64 v[170:171], s[16:17], 0, v[152:153]
	s_add_i32 m0, s20, 0xe000
	s_nop 0
	global_load_lds_dwordx4 v[170:171], off
	s_waitcnt vmcnt(8)
	s_waitcnt lgkmcnt(0)
	s_barrier
	s_setprio 1
	s_waitcnt lgkmcnt(0)
	v_mfma_f32_16x16x32_bf16 v[124:127], v[158:161], v[218:221], v[124:127]
	v_mfma_f32_16x16x32_bf16 v[124:127], v[162:165], v[222:225], v[124:127]
	v_mfma_f32_16x16x32_bf16 v[120:123], v[166:169], v[218:221], v[120:123]
	v_mfma_f32_16x16x32_bf16 v[120:123], v[198:201], v[222:225], v[120:123]
	v_mfma_f32_16x16x32_bf16 v[108:111], v[158:161], v[226:229], v[108:111]
	v_mfma_f32_16x16x32_bf16 v[108:111], v[162:165], v[230:233], v[108:111]
	v_mfma_f32_16x16x32_bf16 v[104:107], v[166:169], v[226:229], v[104:107]
	v_mfma_f32_16x16x32_bf16 v[104:107], v[198:201], v[230:233], v[104:107]
	v_mfma_f32_16x16x32_bf16 v[92:95], v[158:161], v[234:237], v[92:95]
	v_mfma_f32_16x16x32_bf16 v[92:95], v[162:165], v[238:241], v[92:95]
	v_mfma_f32_16x16x32_bf16 v[88:91], v[166:169], v[234:237], v[88:91]
	v_mfma_f32_16x16x32_bf16 v[88:91], v[198:201], v[238:241], v[88:91]
	v_mfma_f32_16x16x32_bf16 v[76:79], v[158:161], v[242:245], v[76:79]
	v_mfma_f32_16x16x32_bf16 v[76:79], v[162:165], v[246:249], v[76:79]
	v_mfma_f32_16x16x32_bf16 v[72:75], v[166:169], v[242:245], v[72:75]
	v_mfma_f32_16x16x32_bf16 v[72:75], v[198:201], v[246:249], v[72:75]
	s_setprio 0
	s_setprio 1
	v_mfma_f32_16x16x32_bf16 v[116:119], v[202:205], v[218:221], v[116:119]
	v_mfma_f32_16x16x32_bf16 v[116:119], v[206:209], v[222:225], v[116:119]
	v_mfma_f32_16x16x32_bf16 v[112:115], v[210:213], v[218:221], v[112:115]
	v_mfma_f32_16x16x32_bf16 v[112:115], v[214:217], v[222:225], v[112:115]
	v_mfma_f32_16x16x32_bf16 v[100:103], v[202:205], v[226:229], v[100:103]
	v_mfma_f32_16x16x32_bf16 v[100:103], v[206:209], v[230:233], v[100:103]
	v_mfma_f32_16x16x32_bf16 v[96:99], v[210:213], v[226:229], v[96:99]
	v_mfma_f32_16x16x32_bf16 v[96:99], v[214:217], v[230:233], v[96:99]
	v_mfma_f32_16x16x32_bf16 v[84:87], v[202:205], v[234:237], v[84:87]
	v_mfma_f32_16x16x32_bf16 v[84:87], v[206:209], v[238:241], v[84:87]
	v_mfma_f32_16x16x32_bf16 v[80:83], v[210:213], v[234:237], v[80:83]
	v_mfma_f32_16x16x32_bf16 v[80:83], v[214:217], v[238:241], v[80:83]
	v_mfma_f32_16x16x32_bf16 v[68:71], v[202:205], v[242:245], v[68:71]
	v_mfma_f32_16x16x32_bf16 v[68:71], v[206:209], v[246:249], v[68:71]
	v_mfma_f32_16x16x32_bf16 v[64:67], v[210:213], v[242:245], v[64:67]
	v_mfma_f32_16x16x32_bf16 v[64:67], v[214:217], v[246:249], v[64:67]
	s_setprio 0
	s_barrier
	s_add_i32 s59, s42, s19
	v_lshl_add_u64 v[170:171], s[92:93], 0, v[130:131]
	s_mov_b32 m0, s59
	ds_read_b128 v[218:221], v193 offset:16384
	ds_read_b128 v[222:225], v193 offset:17408
	ds_read_b128 v[226:229], v193 offset:18432
	ds_read_b128 v[230:233], v193 offset:19456
	ds_read_b128 v[234:237], v193 offset:20480
	ds_read_b128 v[238:241], v193 offset:21504
	ds_read_b128 v[242:245], v193 offset:22528
	ds_read_b128 v[246:249], v193 offset:23552
	global_load_lds_dwordx4 v[170:171], off
	s_add_i32 m0, s59, 0x2000
	s_add_u32 s60, s92, 0x4000
	v_lshl_add_u64 v[170:171], s[92:93], 0, v[134:135]
	s_addc_u32 s61, s93, 0
	s_add_i32 s59, s43, s19
	global_load_lds_dwordx4 v[170:171], off
	v_lshl_add_u64 v[170:171], s[60:61], 0, v[130:131]
	s_mov_b32 m0, s59
	s_nop 0
	global_load_lds_dwordx4 v[170:171], off
	v_lshl_add_u64 v[170:171], s[60:61], 0, v[134:135]
	s_add_i32 m0, s59, 0x2000
	s_nop 0
	global_load_lds_dwordx4 v[170:171], off
	v_lshl_add_u64 v[170:171], s[94:95], 0, v[128:129]
	s_mov_b32 m0, s20
	s_nop 0
	global_load_lds_dwordx4 v[170:171], off
	v_lshl_add_u64 v[170:171], s[94:95], 0, v[132:133]
	s_mov_b32 m0, s21
	s_nop 0
	global_load_lds_dwordx4 v[170:171], off
	s_waitcnt vmcnt(8)
	s_waitcnt lgkmcnt(0)
	s_barrier
; #define PG8_STAGE(bufoff, gbase, voff) do { _Pragma("unroll") for (int _i = 0; _i < 2; ++_i) \
;         __builtin_amdgcn_global_load_lds((const unsigned*)((const char*)(gbase) + (voff)[_i]), (LAS unsigned*)(lds + (bufoff) + ldsw + _i * 8192), 16, 0, 0); } while (0)
; #define PG8_LDA(dst, b, h) do { _Pragma("unroll") for (int m = 0; m < 4; ++m) _Pragma("unroll") for (int k = 0; k < 2; ++k) dst[m][k] = *(const LAS bf16x8*)(lds + PG8_SA(b, h) + aoff + m * 2048 + k * 1024); } while (0)
; #define PG8_LDB(dst, b, h) do { _Pragma("unroll") for (int n = 0; n < 2; ++n) _Pragma("unroll") for (int k = 0; k < 2; ++k) dst[n][k] = *(const LAS bf16x8*)(lds + PG8_SB(b, h) + boff + n * 2048 + k * 1024); } while (0)
; #define PG8_MMA(ai, bj, At, Bt) do { __builtin_amdgcn_s_setprio(1); _Pragma("unroll") for (int m = 0; m < 4; ++m) _Pragma("unroll") for (int n = 0; n < 2; ++n) _Pragma("unroll") for (int k = 0; k < 2; ++k) \
;         acc[ai][bj][m][n] = __builtin_amdgcn_mfma_f32_16x16x32_bf16(Bt[n][k], At[m][k], acc[ai][bj][m][n], 0, 0, 0); __builtin_amdgcn_s_setprio(0); } while (0)
; #define PG8_WAIT_V(n) asm volatile("s_waitcnt vmcnt(" #n ")" ::: "memory")
; #define PG8_WAIT_L(n) asm volatile("s_waitcnt lgkmcnt(" #n ")" ::: "memory")
; #define PG8_BAR __builtin_amdgcn_s_barrier()
; #define PG8_SCHED __builtin_amdgcn_sched_barrier(0)
; template <bool ALIGN_EPI, class Epi, class Sched>
; __device__ __forceinline__ void gemm_phase(LAS unsigned char* lds, const int lda, const int ldb, const int K, const Sched& S, const Epi& E, const size_t kstepA = (size_t)(BK * 2), const size_t kstepB = (size_t)(BK * 2)) {
;     ...
;             PG8_WAIT_V(8); PG8_WAIT_L(0); PG8_BAR; PG8_MMA(1, 0, At, B0); PG8_MMA(1, 1, At, B1); PG8_BAR; PG8_SCHED;
;             PG8_LDB(B0, 1, 0); PG8_LDB(B1, 1, 1); PG8_SCHED; PG8_LDA(At, 1, 0); PG8_STAGE(PG8_SA(0, 1), a2 + hstepA, voffA);
;             PG8_WAIT_V(8); PG8_WAIT_L(0); PG8_BAR; PG8_MMA(0, 0, At, B0); PG8_MMA(0, 1, At, B1); PG8_BAR; PG8_SCHED;
	s_setprio 1
	s_waitcnt lgkmcnt(0)
	v_mfma_f32_16x16x32_bf16 v[60:63], v[158:161], v[218:221], v[60:63]
	v_mfma_f32_16x16x32_bf16 v[60:63], v[162:165], v[222:225], v[60:63]
	v_mfma_f32_16x16x32_bf16 v[56:59], v[166:169], v[218:221], v[56:59]
	v_mfma_f32_16x16x32_bf16 v[56:59], v[198:201], v[222:225], v[56:59]
	v_mfma_f32_16x16x32_bf16 v[44:47], v[158:161], v[226:229], v[44:47]
	v_mfma_f32_16x16x32_bf16 v[44:47], v[162:165], v[230:233], v[44:47]
	v_mfma_f32_16x16x32_bf16 v[40:43], v[166:169], v[226:229], v[40:43]
	v_mfma_f32_16x16x32_bf16 v[40:43], v[198:201], v[230:233], v[40:43]
	v_mfma_f32_16x16x32_bf16 v[28:31], v[158:161], v[234:237], v[28:31]
	v_mfma_f32_16x16x32_bf16 v[28:31], v[162:165], v[238:241], v[28:31]
	v_mfma_f32_16x16x32_bf16 v[24:27], v[166:169], v[234:237], v[24:27]
	v_mfma_f32_16x16x32_bf16 v[24:27], v[198:201], v[238:241], v[24:27]
	v_mfma_f32_16x16x32_bf16 v[12:15], v[158:161], v[242:245], v[12:15]
	v_mfma_f32_16x16x32_bf16 v[12:15], v[162:165], v[246:249], v[12:15]
	v_mfma_f32_16x16x32_bf16 v[8:11], v[166:169], v[242:245], v[8:11]
	v_mfma_f32_16x16x32_bf16 v[8:11], v[198:201], v[246:249], v[8:11]
	s_setprio 0
	s_setprio 1
	v_mfma_f32_16x16x32_bf16 v[52:55], v[202:205], v[218:221], v[52:55]
	v_mfma_f32_16x16x32_bf16 v[52:55], v[206:209], v[222:225], v[52:55]
	v_mfma_f32_16x16x32_bf16 v[48:51], v[210:213], v[218:221], v[48:51]
	v_mfma_f32_16x16x32_bf16 v[48:51], v[214:217], v[222:225], v[48:51]
	v_mfma_f32_16x16x32_bf16 v[36:39], v[202:205], v[226:229], v[36:39]
	v_mfma_f32_16x16x32_bf16 v[36:39], v[206:209], v[230:233], v[36:39]
	v_mfma_f32_16x16x32_bf16 v[32:35], v[210:213], v[226:229], v[32:35]
	v_mfma_f32_16x16x32_bf16 v[32:35], v[214:217], v[230:233], v[32:35]
	v_mfma_f32_16x16x32_bf16 v[20:23], v[202:205], v[234:237], v[20:23]
	v_mfma_f32_16x16x32_bf16 v[20:23], v[206:209], v[238:241], v[20:23]
	v_mfma_f32_16x16x32_bf16 v[16:19], v[210:213], v[234:237], v[16:19]
	v_mfma_f32_16x16x32_bf16 v[16:19], v[214:217], v[238:241], v[16:19]
	v_mfma_f32_16x16x32_bf16 v[4:7], v[202:205], v[242:245], v[4:7]
	v_mfma_f32_16x16x32_bf16 v[4:7], v[206:209], v[246:249], v[4:7]
	v_mfma_f32_16x16x32_bf16 v[0:3], v[210:213], v[242:245], v[0:3]
	v_mfma_f32_16x16x32_bf16 v[0:3], v[214:217], v[246:249], v[0:3]
	s_setprio 0
	s_barrier
	s_add_i32 s59, 0, 0x18000
	v_add_u32_e32 v136, s59, v141
	s_add_i32 s64, 0, 0x1c000
	ds_read_b128 v[158:161], v136
	ds_read_b128 v[162:165], v136 offset:1024
	ds_read_b128 v[166:169], v136 offset:2048
	ds_read_b128 v[198:201], v136 offset:3072
	v_add_u32_e32 v136, s64, v141
	ds_read_b128 v[202:205], v136
	ds_read_b128 v[206:209], v136 offset:1024
	ds_read_b128 v[210:213], v136 offset:2048
	ds_read_b128 v[214:217], v136 offset:3072
	s_add_u32 s60, s94, 0x4000
	s_addc_u32 s61, s95, 0
	s_mov_b32 m0, s22
	v_lshl_add_u64 v[170:171], s[60:61], 0, v[128:129]
	ds_read_b128 v[218:221], v193 offset:32768
	ds_read_b128 v[222:225], v193 offset:33792
	ds_read_b128 v[226:229], v193 offset:34816
	ds_read_b128 v[230:233], v193 offset:35840
	ds_read_b128 v[234:237], v193 offset:36864
	ds_read_b128 v[238:241], v193 offset:37888
	ds_read_b128 v[242:245], v193 offset:38912
	ds_read_b128 v[246:249], v193 offset:39936
	global_load_lds_dwordx4 v[170:171], off
	v_lshl_add_u64 v[170:171], s[60:61], 0, v[132:133]
	s_mov_b32 m0, s23
	s_nop 0
	global_load_lds_dwordx4 v[170:171], off
	s_waitcnt vmcnt(8)
	s_waitcnt lgkmcnt(0)
	s_barrier
	s_setprio 1
	s_waitcnt lgkmcnt(0)
	v_mfma_f32_16x16x32_bf16 v[124:127], v[158:161], v[218:221], v[124:127]
	v_mfma_f32_16x16x32_bf16 v[124:127], v[162:165], v[222:225], v[124:127]
	v_mfma_f32_16x16x32_bf16 v[120:123], v[166:169], v[218:221], v[120:123]
	v_mfma_f32_16x16x32_bf16 v[120:123], v[198:201], v[222:225], v[120:123]
	v_mfma_f32_16x16x32_bf16 v[108:111], v[158:161], v[226:229], v[108:111]
	v_mfma_f32_16x16x32_bf16 v[108:111], v[162:165], v[230:233], v[108:111]
	v_mfma_f32_16x16x32_bf16 v[104:107], v[166:169], v[226:229], v[104:107]
	v_mfma_f32_16x16x32_bf16 v[104:107], v[198:201], v[230:233], v[104:107]
	v_mfma_f32_16x16x32_bf16 v[92:95], v[158:161], v[234:237], v[92:95]
	v_mfma_f32_16x16x32_bf16 v[92:95], v[162:165], v[238:241], v[92:95]
	v_mfma_f32_16x16x32_bf16 v[88:91], v[166:169], v[234:237], v[88:91]
	v_mfma_f32_16x16x32_bf16 v[88:91], v[198:201], v[238:241], v[88:91]
	v_mfma_f32_16x16x32_bf16 v[76:79], v[158:161], v[242:245], v[76:79]
	v_mfma_f32_16x16x32_bf16 v[76:79], v[162:165], v[246:249], v[76:79]
	v_mfma_f32_16x16x32_bf16 v[72:75], v[166:169], v[242:245], v[72:75]
	v_mfma_f32_16x16x32_bf16 v[72:75], v[198:201], v[246:249], v[72:75]
	s_setprio 0
	s_setprio 1
	v_mfma_f32_16x16x32_bf16 v[116:119], v[202:205], v[218:221], v[116:119]
	v_mfma_f32_16x16x32_bf16 v[116:119], v[206:209], v[222:225], v[116:119]
	v_mfma_f32_16x16x32_bf16 v[112:115], v[210:213], v[218:221], v[112:115]
	v_mfma_f32_16x16x32_bf16 v[112:115], v[214:217], v[222:225], v[112:115]
	v_mfma_f32_16x16x32_bf16 v[100:103], v[202:205], v[226:229], v[100:103]
	v_mfma_f32_16x16x32_bf16 v[100:103], v[206:209], v[230:233], v[100:103]
	v_mfma_f32_16x16x32_bf16 v[96:99], v[210:213], v[226:229], v[96:99]
	v_mfma_f32_16x16x32_bf16 v[96:99], v[214:217], v[230:233], v[96:99]
	v_mfma_f32_16x16x32_bf16 v[84:87], v[202:205], v[234:237], v[84:87]
	v_mfma_f32_16x16x32_bf16 v[84:87], v[206:209], v[238:241], v[84:87]
	v_mfma_f32_16x16x32_bf16 v[80:83], v[210:213], v[234:237], v[80:83]
	v_mfma_f32_16x16x32_bf16 v[80:83], v[214:217], v[238:241], v[80:83]
	v_mfma_f32_16x16x32_bf16 v[68:71], v[202:205], v[242:245], v[68:71]
	v_mfma_f32_16x16x32_bf16 v[68:71], v[206:209], v[246:249], v[68:71]
	v_mfma_f32_16x16x32_bf16 v[64:67], v[210:213], v[242:245], v[64:67]
	v_mfma_f32_16x16x32_bf16 v[64:67], v[214:217], v[246:249], v[64:67]
	s_setprio 0
	s_barrier
; #define PG8_STAGE(bufoff, gbase, voff) do { _Pragma("unroll") for (int _i = 0; _i < 2; ++_i) \
;         __builtin_amdgcn_global_load_lds((const unsigned*)((const char*)(gbase) + (voff)[_i]), (LAS unsigned*)(lds + (bufoff) + ldsw + _i * 8192), 16, 0, 0); } while (0)
; #define PG8_LDA(dst, b, h) do { _Pragma("unroll") for (int m = 0; m < 4; ++m) _Pragma("unroll") for (int k = 0; k < 2; ++k) dst[m][k] = *(const LAS bf16x8*)(lds + PG8_SA(b, h) + aoff + m * 2048 + k * 1024); } while (0)
; #define PG8_MMA(ai, bj, At, Bt) do { __builtin_amdgcn_s_setprio(1); _Pragma("unroll") for (int m = 0; m < 4; ++m) _Pragma("unroll") for (int n = 0; n < 2; ++n) _Pragma("unroll") for (int k = 0; k < 2; ++k) \
;         acc[ai][bj][m][n] = __builtin_amdgcn_mfma_f32_16x16x32_bf16(Bt[n][k], At[m][k], acc[ai][bj][m][n], 0, 0, 0); __builtin_amdgcn_s_setprio(0); } while (0)
; #define PG8_WAIT_V(n) asm volatile("s_waitcnt vmcnt(" #n ")" ::: "memory")
; #define PG8_WAIT_L(n) asm volatile("s_waitcnt lgkmcnt(" #n ")" ::: "memory")
; #define PG8_BAR __builtin_amdgcn_s_barrier()
; #define PG8_SCHED __builtin_amdgcn_sched_barrier(0)
; template <bool ALIGN_EPI, class Epi, class Sched>
; __device__ __forceinline__ void gemm_phase(LAS unsigned char* lds, const int lda, const int ldb, const int K, const Sched& S, const Epi& E, const size_t kstepA = (size_t)(BK * 2), const size_t kstepB = (size_t)(BK * 2)) {
;     ...
;             PG8_LDA(At, 1, 1); PG8_STAGE(PG8_SB(1, 0), b3, voffB); PG8_STAGE(PG8_SB(1, 1), b3 + hstepB, voffB); PG8_STAGE(PG8_SA(1, 0), a3, voffA);
;             PG8_WAIT_V(8); PG8_WAIT_L(0); PG8_BAR; PG8_MMA(1, 0, At, B0); PG8_MMA(1, 1, At, B1); PG8_BAR; PG8_SCHED;
;         }
	s_add_u32 s60, s92, 0x80000
	s_addc_u32 s61, s93, 0
	s_add_i32 s59, s59, s19
	v_lshl_add_u64 v[170:171], s[60:61], 0, v[130:131]
	s_mov_b32 m0, s59
	ds_read_b128 v[218:221], v193 offset:49152
	ds_read_b128 v[222:225], v193 offset:50176
	ds_read_b128 v[226:229], v193 offset:51200
	ds_read_b128 v[230:233], v193 offset:52224
	ds_read_b128 v[234:237], v193 offset:53248
	ds_read_b128 v[238:241], v193 offset:54272
	ds_read_b128 v[242:245], v193 offset:55296
	ds_read_b128 v[246:249], v193 offset:56320
	global_load_lds_dwordx4 v[170:171], off
	s_add_i32 m0, s59, 0x2000
	v_lshl_add_u64 v[170:171], s[60:61], 0, v[134:135]
	s_add_u32 s60, s92, 0x84000
	s_addc_u32 s61, s93, 0
	s_add_i32 s59, s64, s19
	global_load_lds_dwordx4 v[170:171], off
	v_lshl_add_u64 v[170:171], s[60:61], 0, v[130:131]
	s_mov_b32 m0, s59
	s_nop 0
	global_load_lds_dwordx4 v[170:171], off
	v_lshl_add_u64 v[170:171], s[60:61], 0, v[134:135]
	s_add_i32 m0, s59, 0x2000
	s_nop 0
	global_load_lds_dwordx4 v[170:171], off
	v_lshl_add_u64 v[170:171], s[82:83], 0, v[128:129]
	s_mov_b32 m0, s30
	s_nop 0
	global_load_lds_dwordx4 v[170:171], off
	v_lshl_add_u64 v[170:171], s[82:83], 0, v[132:133]
	s_mov_b32 m0, s31
	s_nop 0
	global_load_lds_dwordx4 v[170:171], off
	s_waitcnt vmcnt(8)
	s_waitcnt lgkmcnt(0)
	s_barrier
	s_setprio 1
	s_waitcnt lgkmcnt(0)
	v_mfma_f32_16x16x32_bf16 v[60:63], v[158:161], v[218:221], v[60:63]
	v_mfma_f32_16x16x32_bf16 v[60:63], v[162:165], v[222:225], v[60:63]
	v_mfma_f32_16x16x32_bf16 v[56:59], v[166:169], v[218:221], v[56:59]
	v_mfma_f32_16x16x32_bf16 v[56:59], v[198:201], v[222:225], v[56:59]
	v_mfma_f32_16x16x32_bf16 v[44:47], v[158:161], v[226:229], v[44:47]
	v_mfma_f32_16x16x32_bf16 v[44:47], v[162:165], v[230:233], v[44:47]
	v_mfma_f32_16x16x32_bf16 v[40:43], v[166:169], v[226:229], v[40:43]
	v_mfma_f32_16x16x32_bf16 v[40:43], v[198:201], v[230:233], v[40:43]
	v_mfma_f32_16x16x32_bf16 v[28:31], v[158:161], v[234:237], v[28:31]
	v_mfma_f32_16x16x32_bf16 v[28:31], v[162:165], v[238:241], v[28:31]
	v_mfma_f32_16x16x32_bf16 v[24:27], v[166:169], v[234:237], v[24:27]
	v_mfma_f32_16x16x32_bf16 v[24:27], v[198:201], v[238:241], v[24:27]
	v_mfma_f32_16x16x32_bf16 v[12:15], v[158:161], v[242:245], v[12:15]
	v_mfma_f32_16x16x32_bf16 v[12:15], v[162:165], v[246:249], v[12:15]
	v_mfma_f32_16x16x32_bf16 v[8:11], v[166:169], v[242:245], v[8:11]
	v_mfma_f32_16x16x32_bf16 v[8:11], v[198:201], v[246:249], v[8:11]
	s_setprio 0
	s_setprio 1
	v_mfma_f32_16x16x32_bf16 v[52:55], v[202:205], v[218:221], v[52:55]
	v_mfma_f32_16x16x32_bf16 v[52:55], v[206:209], v[222:225], v[52:55]
	v_mfma_f32_16x16x32_bf16 v[48:51], v[210:213], v[218:221], v[48:51]
	v_mfma_f32_16x16x32_bf16 v[48:51], v[214:217], v[222:225], v[48:51]
	v_mfma_f32_16x16x32_bf16 v[36:39], v[202:205], v[226:229], v[36:39]
	v_mfma_f32_16x16x32_bf16 v[36:39], v[206:209], v[230:233], v[36:39]
	v_mfma_f32_16x16x32_bf16 v[32:35], v[210:213], v[226:229], v[32:35]
	v_mfma_f32_16x16x32_bf16 v[32:35], v[214:217], v[230:233], v[32:35]
	v_mfma_f32_16x16x32_bf16 v[20:23], v[202:205], v[234:237], v[20:23]
	v_mfma_f32_16x16x32_bf16 v[20:23], v[206:209], v[238:241], v[20:23]
	v_mfma_f32_16x16x32_bf16 v[16:19], v[210:213], v[234:237], v[16:19]
	v_mfma_f32_16x16x32_bf16 v[16:19], v[214:217], v[238:241], v[16:19]
	v_mfma_f32_16x16x32_bf16 v[4:7], v[202:205], v[242:245], v[4:7]
	v_mfma_f32_16x16x32_bf16 v[4:7], v[206:209], v[246:249], v[4:7]
	v_mfma_f32_16x16x32_bf16 v[0:3], v[210:213], v[242:245], v[0:3]
	v_mfma_f32_16x16x32_bf16 v[0:3], v[214:217], v[246:249], v[0:3]
	s_setprio 0
	s_barrier
	s_add_i32 s58, s58, 2
	s_add_u32 s55, s55, 0x100000
	s_addc_u32 s57, s57, 0
	s_add_u32 s16, s16, 0x400000
	s_addc_u32 s17, s17, 0
	s_cmp_gt_u32 s58, 29
	s_cbranch_scc0 .LBB0_347
	s_and_b64 vcc, exec, s[68:69]
	s_cbranch_vccz .LBB0_350
	s_barrier

; #define PG8_STAGE(bufoff, gbase, voff) do { _Pragma("unroll") for (int _i = 0; _i < 2; ++_i) \
;         __builtin_amdgcn_global_load_lds((const unsigned*)((const char*)(gbase) + (voff)[_i]), (LAS unsigned*)(lds + (bufoff) + ldsw + _i * 8192), 16, 0, 0); } while (0)
; #define PG8_LDA(dst, b, h) do { _Pragma("unroll") for (int m = 0; m < 4; ++m) _Pragma("unroll") for (int k = 0; k < 2; ++k) dst[m][k] = *(const LAS bf16x8*)(lds + PG8_SA(b, h) + aoff + m * 2048 + k * 1024); } while (0)
; #define PG8_LDB(dst, b, h) do { _Pragma("unroll") for (int n = 0; n < 2; ++n) _Pragma("unroll") for (int k = 0; k < 2; ++k) dst[n][k] = *(const LAS bf16x8*)(lds + PG8_SB(b, h) + boff + n * 2048 + k * 1024); } while (0)
; #define PG8_MMA(ai, bj, At, Bt) do { __builtin_amdgcn_s_setprio(1); _Pragma("unroll") for (int m = 0; m < 4; ++m) _Pragma("unroll") for (int n = 0; n < 2; ++n) _Pragma("unroll") for (int k = 0; k < 2; ++k) \
;         acc[ai][bj][m][n] = __builtin_amdgcn_mfma_f32_16x16x32_bf16(Bt[n][k], At[m][k], acc[ai][bj][m][n], 0, 0, 0); __builtin_amdgcn_s_setprio(0); } while (0)
; #define PG8_WAIT_V(n) asm volatile("s_waitcnt vmcnt(" #n ")" ::: "memory")
; #define PG8_WAIT_L(n) asm volatile("s_waitcnt lgkmcnt(" #n ")" ::: "memory")
; #define PG8_BAR __builtin_amdgcn_s_barrier()
; #define PG8_SCHED __builtin_amdgcn_sched_barrier(0)
; template <bool ALIGN_EPI, class Epi, class Sched>
; __device__ __forceinline__ void gemm_phase(LAS unsigned char* lds, const int lda, const int ldb, const int K, const Sched& S, const Epi& E, const size_t kstepA = (size_t)(BK * 2), const size_t kstepB = (size_t)(BK * 2)) {
;     ...
;             const char* a1 = cA + (size_t)(t + 1) * kstepA;
;             const char* a2 = last ? nA : cA + (size_t)(t + 2) * kstepA; const char* b2 = last ? nB : cB + (size_t)(t + 2) * kstep;
;             const char* a3 = a2 + kstepA; const char* b3 = b2 + kstep;
;             PG8_LDB(B0, 0, 0); PG8_LDB(B1, 0, 1); PG8_SCHED; PG8_LDA(At, 0, 0); PG8_STAGE(PG8_SA(1, 1), a1 + hstepA, voffA);
;             PG8_WAIT_V(8); PG8_WAIT_L(0); PG8_BAR; PG8_MMA(0, 0, At, B0); PG8_MMA(0, 1, At, B1); PG8_BAR; PG8_SCHED;
;             PG8_LDA(At, 0, 1); PG8_STAGE(PG8_SB(0, 0), b2, voffB); PG8_STAGE(PG8_SB(0, 1), b2 + hstepB, voffB); PG8_STAGE(PG8_SA(0, 0), a2, voffA);
.LBB0_523:
	ds_read_b128 v[152:155], v141
	ds_read_b128 v[156:159], v141 offset:1024
	ds_read_b128 v[160:163], v141 offset:2048
	ds_read_b128 v[164:167], v141 offset:3072
	ds_read_b128 v[168:171], v147
	ds_read_b128 v[172:175], v147 offset:1024
	ds_read_b128 v[176:179], v147 offset:2048
	ds_read_b128 v[180:183], v147 offset:3072
	s_add_u32 s14, s10, s12
	s_addc_u32 s15, s11, s13
	s_add_u32 s14, s14, 0x984100
	s_addc_u32 s15, s15, 0
	s_add_u32 s61, s46, s12
	s_addc_u32 s62, s47, s13
	s_cmpk_eq_i32 s12, 0xf00
	s_cselect_b32 s17, s1, s15
	s_cselect_b32 s16, s0, s14
	s_cselect_b32 s15, s7, s62
	s_cselect_b32 s14, s6, s61
	s_mov_b32 m0, s51
	v_lshl_add_u64 v[222:223], v[142:143], 0, s[12:13]
	ds_read_b128 v[190:193], v148
	ds_read_b128 v[194:197], v148 offset:1024
	ds_read_b128 v[198:201], v148 offset:2048
	ds_read_b128 v[202:205], v148 offset:3072
	ds_read_b128 v[206:209], v148 offset:4096
	ds_read_b128 v[210:213], v148 offset:5120
	ds_read_b128 v[214:217], v148 offset:6144
	ds_read_b128 v[218:221], v148 offset:7168
	global_load_lds_dwordx4 v[222:223], off
	v_lshl_add_u64 v[222:223], v[144:145], 0, s[12:13]
	s_mov_b32 m0, s52
	s_nop 0
	global_load_lds_dwordx4 v[222:223], off
	s_waitcnt vmcnt(8)
	s_waitcnt lgkmcnt(0)
	s_barrier
	s_setprio 1
	s_waitcnt lgkmcnt(0)
	v_mfma_f32_16x16x32_bf16 v[124:127], v[152:155], v[190:193], v[124:127]
	v_mfma_f32_16x16x32_bf16 v[124:127], v[156:159], v[194:197], v[124:127]
	v_mfma_f32_16x16x32_bf16 v[120:123], v[160:163], v[190:193], v[120:123]
	v_mfma_f32_16x16x32_bf16 v[120:123], v[164:167], v[194:197], v[120:123]
	v_mfma_f32_16x16x32_bf16 v[116:119], v[152:155], v[198:201], v[116:119]
	v_mfma_f32_16x16x32_bf16 v[116:119], v[156:159], v[202:205], v[116:119]
	v_mfma_f32_16x16x32_bf16 v[112:115], v[160:163], v[198:201], v[112:115]
	v_mfma_f32_16x16x32_bf16 v[112:115], v[164:167], v[202:205], v[112:115]
	v_mfma_f32_16x16x32_bf16 v[100:103], v[152:155], v[206:209], v[100:103]
	v_mfma_f32_16x16x32_bf16 v[100:103], v[156:159], v[210:213], v[100:103]
	v_mfma_f32_16x16x32_bf16 v[96:99], v[160:163], v[206:209], v[96:99]
	v_mfma_f32_16x16x32_bf16 v[96:99], v[164:167], v[210:213], v[96:99]
	v_mfma_f32_16x16x32_bf16 v[84:87], v[152:155], v[214:217], v[84:87]
	v_mfma_f32_16x16x32_bf16 v[84:87], v[156:159], v[218:221], v[84:87]
	v_mfma_f32_16x16x32_bf16 v[80:83], v[160:163], v[214:217], v[80:83]
	v_mfma_f32_16x16x32_bf16 v[80:83], v[164:167], v[218:221], v[80:83]
	s_setprio 0
	s_setprio 1
	v_mfma_f32_16x16x32_bf16 v[108:111], v[168:171], v[190:193], v[108:111]
	v_mfma_f32_16x16x32_bf16 v[108:111], v[172:175], v[194:197], v[108:111]
	v_mfma_f32_16x16x32_bf16 v[104:107], v[176:179], v[190:193], v[104:107]
	v_mfma_f32_16x16x32_bf16 v[104:107], v[180:183], v[194:197], v[104:107]
	v_mfma_f32_16x16x32_bf16 v[92:95], v[168:171], v[198:201], v[92:95]
	v_mfma_f32_16x16x32_bf16 v[92:95], v[172:175], v[202:205], v[92:95]
	v_mfma_f32_16x16x32_bf16 v[88:91], v[176:179], v[198:201], v[88:91]
	v_mfma_f32_16x16x32_bf16 v[88:91], v[180:183], v[202:205], v[88:91]
	v_mfma_f32_16x16x32_bf16 v[76:79], v[168:171], v[206:209], v[76:79]
	v_mfma_f32_16x16x32_bf16 v[76:79], v[172:175], v[210:213], v[76:79]
	v_mfma_f32_16x16x32_bf16 v[72:75], v[176:179], v[206:209], v[72:75]
	v_mfma_f32_16x16x32_bf16 v[72:75], v[180:183], v[210:213], v[72:75]
	v_mfma_f32_16x16x32_bf16 v[68:71], v[168:171], v[214:217], v[68:71]
	v_mfma_f32_16x16x32_bf16 v[68:71], v[172:175], v[218:221], v[68:71]
	v_mfma_f32_16x16x32_bf16 v[64:67], v[176:179], v[214:217], v[64:67]
	v_mfma_f32_16x16x32_bf16 v[64:67], v[180:183], v[218:221], v[64:67]
	s_setprio 0
	s_barrier
	s_mov_b32 m0, s53
	v_lshl_add_u64 v[222:223], s[14:15], 0, v[136:137]
	s_add_u32 s62, s14, 0x80000
	ds_read_b128 v[190:193], v148 offset:16384
	ds_read_b128 v[194:197], v148 offset:17408
	ds_read_b128 v[198:201], v148 offset:18432
	ds_read_b128 v[202:205], v148 offset:19456
	ds_read_b128 v[206:209], v148 offset:20480
	ds_read_b128 v[210:213], v148 offset:21504
	ds_read_b128 v[214:217], v148 offset:22528
	ds_read_b128 v[218:221], v148 offset:23552
	global_load_lds_dwordx4 v[222:223], off
	v_lshl_add_u64 v[224:225], s[14:15], 0, v[132:133]
	s_mov_b32 m0, s54
	s_addc_u32 s63, s15, 0
	global_load_lds_dwordx4 v[224:225], off
	v_lshl_add_u64 v[226:227], s[62:63], 0, v[136:137]
	s_mov_b32 m0, s55
	v_lshl_add_u64 v[228:229], s[16:17], 0, v[134:135]
	global_load_lds_dwordx4 v[226:227], off
	v_lshl_add_u64 v[226:227], s[62:63], 0, v[132:133]
	s_mov_b32 m0, s56
	s_nop 0
	global_load_lds_dwordx4 v[226:227], off
	v_lshl_add_u64 v[226:227], s[16:17], 0, v[138:139]
	s_mov_b32 m0, s22
	s_nop 0
	global_load_lds_dwordx4 v[226:227], off
	s_mov_b32 m0, s30
	s_nop 0
	global_load_lds_dwordx4 v[228:229], off
	s_waitcnt vmcnt(8)
	s_waitcnt lgkmcnt(0)
	s_barrier
; #define PG8_STAGE(bufoff, gbase, voff) do { _Pragma("unroll") for (int _i = 0; _i < 2; ++_i) \
;         __builtin_amdgcn_global_load_lds((const unsigned*)((const char*)(gbase) + (voff)[_i]), (LAS unsigned*)(lds + (bufoff) + ldsw + _i * 8192), 16, 0, 0); } while (0)
; #define PG8_LDA(dst, b, h) do { _Pragma("unroll") for (int m = 0; m < 4; ++m) _Pragma("unroll") for (int k = 0; k < 2; ++k) dst[m][k] = *(const LAS bf16x8*)(lds + PG8_SA(b, h) + aoff + m * 2048 + k * 1024); } while (0)
; #define PG8_LDB(dst, b, h) do { _Pragma("unroll") for (int n = 0; n < 2; ++n) _Pragma("unroll") for (int k = 0; k < 2; ++k) dst[n][k] = *(const LAS bf16x8*)(lds + PG8_SB(b, h) + boff + n * 2048 + k * 1024); } while (0)
; #define PG8_MMA(ai, bj, At, Bt) do { __builtin_amdgcn_s_setprio(1); _Pragma("unroll") for (int m = 0; m < 4; ++m) _Pragma("unroll") for (int n = 0; n < 2; ++n) _Pragma("unroll") for (int k = 0; k < 2; ++k) \
;         acc[ai][bj][m][n] = __builtin_amdgcn_mfma_f32_16x16x32_bf16(Bt[n][k], At[m][k], acc[ai][bj][m][n], 0, 0, 0); __builtin_amdgcn_s_setprio(0); } while (0)
; #define PG8_WAIT_V(n) asm volatile("s_waitcnt vmcnt(" #n ")" ::: "memory")
; #define PG8_WAIT_L(n) asm volatile("s_waitcnt lgkmcnt(" #n ")" ::: "memory")
; #define PG8_BAR __builtin_amdgcn_s_barrier()
; #define PG8_SCHED __builtin_amdgcn_sched_barrier(0)
; template <bool ALIGN_EPI, class Epi, class Sched>
; __device__ __forceinline__ void gemm_phase(LAS unsigned char* lds, const int lda, const int ldb, const int K, const Sched& S, const Epi& E, const size_t kstepA = (size_t)(BK * 2), const size_t kstepB = (size_t)(BK * 2)) {
;     ...
;             PG8_WAIT_V(8); PG8_WAIT_L(0); PG8_BAR; PG8_MMA(1, 0, At, B0); PG8_MMA(1, 1, At, B1); PG8_BAR; PG8_SCHED;
;             PG8_LDB(B0, 1, 0); PG8_LDB(B1, 1, 1); PG8_SCHED; PG8_LDA(At, 1, 0); PG8_STAGE(PG8_SA(0, 1), a2 + hstepA, voffA);
;             PG8_WAIT_V(8); PG8_WAIT_L(0); PG8_BAR; PG8_MMA(0, 0, At, B0); PG8_MMA(0, 1, At, B1); PG8_BAR; PG8_SCHED;
	s_setprio 1
	s_waitcnt lgkmcnt(0)
	v_mfma_f32_16x16x32_bf16 v[60:63], v[152:155], v[190:193], v[60:63]
	v_mfma_f32_16x16x32_bf16 v[60:63], v[156:159], v[194:197], v[60:63]
	v_mfma_f32_16x16x32_bf16 v[56:59], v[160:163], v[190:193], v[56:59]
	v_mfma_f32_16x16x32_bf16 v[56:59], v[164:167], v[194:197], v[56:59]
	v_mfma_f32_16x16x32_bf16 v[52:55], v[152:155], v[198:201], v[52:55]
	v_mfma_f32_16x16x32_bf16 v[52:55], v[156:159], v[202:205], v[52:55]
	v_mfma_f32_16x16x32_bf16 v[48:51], v[160:163], v[198:201], v[48:51]
	v_mfma_f32_16x16x32_bf16 v[48:51], v[164:167], v[202:205], v[48:51]
	v_mfma_f32_16x16x32_bf16 v[36:39], v[152:155], v[206:209], v[36:39]
	v_mfma_f32_16x16x32_bf16 v[36:39], v[156:159], v[210:213], v[36:39]
	v_mfma_f32_16x16x32_bf16 v[32:35], v[160:163], v[206:209], v[32:35]
	v_mfma_f32_16x16x32_bf16 v[32:35], v[164:167], v[210:213], v[32:35]
	v_mfma_f32_16x16x32_bf16 v[20:23], v[152:155], v[214:217], v[20:23]
	v_mfma_f32_16x16x32_bf16 v[20:23], v[156:159], v[218:221], v[20:23]
	v_mfma_f32_16x16x32_bf16 v[16:19], v[160:163], v[214:217], v[16:19]
	v_mfma_f32_16x16x32_bf16 v[16:19], v[164:167], v[218:221], v[16:19]
	s_setprio 0
	s_setprio 1
	v_mfma_f32_16x16x32_bf16 v[44:47], v[168:171], v[190:193], v[44:47]
	v_mfma_f32_16x16x32_bf16 v[44:47], v[172:175], v[194:197], v[44:47]
	v_mfma_f32_16x16x32_bf16 v[40:43], v[176:179], v[190:193], v[40:43]
	v_mfma_f32_16x16x32_bf16 v[40:43], v[180:183], v[194:197], v[40:43]
	v_mfma_f32_16x16x32_bf16 v[28:31], v[168:171], v[198:201], v[28:31]
	v_mfma_f32_16x16x32_bf16 v[28:31], v[172:175], v[202:205], v[28:31]
	v_mfma_f32_16x16x32_bf16 v[24:27], v[176:179], v[198:201], v[24:27]
	v_mfma_f32_16x16x32_bf16 v[24:27], v[180:183], v[202:205], v[24:27]
	v_mfma_f32_16x16x32_bf16 v[12:15], v[168:171], v[206:209], v[12:15]
	v_mfma_f32_16x16x32_bf16 v[12:15], v[172:175], v[210:213], v[12:15]
	v_mfma_f32_16x16x32_bf16 v[8:11], v[176:179], v[206:209], v[8:11]
	v_mfma_f32_16x16x32_bf16 v[8:11], v[180:183], v[210:213], v[8:11]
	v_mfma_f32_16x16x32_bf16 v[4:7], v[168:171], v[214:217], v[4:7]
	v_mfma_f32_16x16x32_bf16 v[4:7], v[172:175], v[218:221], v[4:7]
	v_mfma_f32_16x16x32_bf16 v[0:3], v[176:179], v[214:217], v[0:3]
	v_mfma_f32_16x16x32_bf16 v[0:3], v[180:183], v[218:221], v[0:3]
	s_setprio 0
	s_barrier
	ds_read_b128 v[152:155], v149
	ds_read_b128 v[156:159], v149 offset:1024
	ds_read_b128 v[160:163], v149 offset:2048
	ds_read_b128 v[164:167], v149 offset:3072
	ds_read_b128 v[168:171], v150
	ds_read_b128 v[172:175], v150 offset:1024
	ds_read_b128 v[176:179], v150 offset:2048
	ds_read_b128 v[180:183], v150 offset:3072
	s_add_u32 s16, s16, 0x80000
	s_addc_u32 s17, s17, 0
	s_mov_b32 m0, s31
	v_lshl_add_u64 v[230:231], s[16:17], 0, v[138:139]
	ds_read_b128 v[190:193], v148 offset:32768
	ds_read_b128 v[194:197], v148 offset:33792
	ds_read_b128 v[198:201], v148 offset:34816
	ds_read_b128 v[202:205], v148 offset:35840
	ds_read_b128 v[206:209], v148 offset:36864
	ds_read_b128 v[210:213], v148 offset:37888
	ds_read_b128 v[214:217], v148 offset:38912
	ds_read_b128 v[218:221], v148 offset:39936
	global_load_lds_dwordx4 v[230:231], off
	v_lshl_add_u64 v[230:231], s[16:17], 0, v[134:135]
	s_mov_b32 m0, s33
	s_nop 0
	global_load_lds_dwordx4 v[230:231], off
	s_waitcnt vmcnt(8)
	s_waitcnt lgkmcnt(0)
	s_barrier
	s_setprio 1
	s_waitcnt lgkmcnt(0)
	v_mfma_f32_16x16x32_bf16 v[124:127], v[152:155], v[190:193], v[124:127]
	v_mfma_f32_16x16x32_bf16 v[124:127], v[156:159], v[194:197], v[124:127]
	v_mfma_f32_16x16x32_bf16 v[120:123], v[160:163], v[190:193], v[120:123]
	v_mfma_f32_16x16x32_bf16 v[120:123], v[164:167], v[194:197], v[120:123]
	v_mfma_f32_16x16x32_bf16 v[116:119], v[152:155], v[198:201], v[116:119]
	v_mfma_f32_16x16x32_bf16 v[116:119], v[156:159], v[202:205], v[116:119]
	v_mfma_f32_16x16x32_bf16 v[112:115], v[160:163], v[198:201], v[112:115]
	v_mfma_f32_16x16x32_bf16 v[112:115], v[164:167], v[202:205], v[112:115]
	v_mfma_f32_16x16x32_bf16 v[100:103], v[152:155], v[206:209], v[100:103]
	v_mfma_f32_16x16x32_bf16 v[100:103], v[156:159], v[210:213], v[100:103]
	v_mfma_f32_16x16x32_bf16 v[96:99], v[160:163], v[206:209], v[96:99]
	v_mfma_f32_16x16x32_bf16 v[96:99], v[164:167], v[210:213], v[96:99]
	v_mfma_f32_16x16x32_bf16 v[84:87], v[152:155], v[214:217], v[84:87]
	v_mfma_f32_16x16x32_bf16 v[84:87], v[156:159], v[218:221], v[84:87]
	v_mfma_f32_16x16x32_bf16 v[80:83], v[160:163], v[214:217], v[80:83]
	v_mfma_f32_16x16x32_bf16 v[80:83], v[164:167], v[218:221], v[80:83]
	s_setprio 0
	s_setprio 1
	v_mfma_f32_16x16x32_bf16 v[108:111], v[168:171], v[190:193], v[108:111]
	v_mfma_f32_16x16x32_bf16 v[108:111], v[172:175], v[194:197], v[108:111]
	v_mfma_f32_16x16x32_bf16 v[104:107], v[176:179], v[190:193], v[104:107]
	v_mfma_f32_16x16x32_bf16 v[104:107], v[180:183], v[194:197], v[104:107]
	v_mfma_f32_16x16x32_bf16 v[92:95], v[168:171], v[198:201], v[92:95]
	v_mfma_f32_16x16x32_bf16 v[92:95], v[172:175], v[202:205], v[92:95]
	v_mfma_f32_16x16x32_bf16 v[88:91], v[176:179], v[198:201], v[88:91]
	v_mfma_f32_16x16x32_bf16 v[88:91], v[180:183], v[202:205], v[88:91]
	v_mfma_f32_16x16x32_bf16 v[76:79], v[168:171], v[206:209], v[76:79]
	v_mfma_f32_16x16x32_bf16 v[76:79], v[172:175], v[210:213], v[76:79]
	v_mfma_f32_16x16x32_bf16 v[72:75], v[176:179], v[206:209], v[72:75]
	v_mfma_f32_16x16x32_bf16 v[72:75], v[180:183], v[210:213], v[72:75]
	v_mfma_f32_16x16x32_bf16 v[68:71], v[168:171], v[214:217], v[68:71]
	v_mfma_f32_16x16x32_bf16 v[68:71], v[172:175], v[218:221], v[68:71]
	v_mfma_f32_16x16x32_bf16 v[64:67], v[176:179], v[214:217], v[64:67]
	v_mfma_f32_16x16x32_bf16 v[64:67], v[180:183], v[218:221], v[64:67]
	s_setprio 0
	s_barrier
; #define PG8_STAGE(bufoff, gbase, voff) do { _Pragma("unroll") for (int _i = 0; _i < 2; ++_i) \
;         __builtin_amdgcn_global_load_lds((const unsigned*)((const char*)(gbase) + (voff)[_i]), (LAS unsigned*)(lds + (bufoff) + ldsw + _i * 8192), 16, 0, 0); } while (0)
; #define PG8_LDA(dst, b, h) do { _Pragma("unroll") for (int m = 0; m < 4; ++m) _Pragma("unroll") for (int k = 0; k < 2; ++k) dst[m][k] = *(const LAS bf16x8*)(lds + PG8_SA(b, h) + aoff + m * 2048 + k * 1024); } while (0)
; #define PG8_MMA(ai, bj, At, Bt) do { __builtin_amdgcn_s_setprio(1); _Pragma("unroll") for (int m = 0; m < 4; ++m) _Pragma("unroll") for (int n = 0; n < 2; ++n) _Pragma("unroll") for (int k = 0; k < 2; ++k) \
;         acc[ai][bj][m][n] = __builtin_amdgcn_mfma_f32_16x16x32_bf16(Bt[n][k], At[m][k], acc[ai][bj][m][n], 0, 0, 0); __builtin_amdgcn_s_setprio(0); } while (0)
; #define PG8_WAIT_V(n) asm volatile("s_waitcnt vmcnt(" #n ")" ::: "memory")
; #define PG8_WAIT_L(n) asm volatile("s_waitcnt lgkmcnt(" #n ")" ::: "memory")
; #define PG8_BAR __builtin_amdgcn_s_barrier()
; #define PG8_SCHED __builtin_amdgcn_sched_barrier(0)
; template <bool ALIGN_EPI, class Epi, class Sched>
; __device__ __forceinline__ void gemm_phase(LAS unsigned char* lds, const int lda, const int ldb, const int K, const Sched& S, const Epi& E, const size_t kstepA = (size_t)(BK * 2), const size_t kstepB = (size_t)(BK * 2)) {
;     ...
;             PG8_LDA(At, 1, 1); PG8_STAGE(PG8_SB(1, 0), b3, voffB); PG8_STAGE(PG8_SB(1, 1), b3 + hstepB, voffB); PG8_STAGE(PG8_SA(1, 0), a3, voffA);
;             PG8_WAIT_V(8); PG8_WAIT_L(0); PG8_BAR; PG8_MMA(1, 0, At, B0); PG8_MMA(1, 1, At, B1); PG8_BAR; PG8_SCHED;
;         }
	s_mov_b32 m0, s57
	v_lshl_add_u64 v[222:223], v[222:223], 0, s[8:9]
	s_add_u32 s14, s14, 0x80080
	ds_read_b128 v[190:193], v148 offset:49152
	ds_read_b128 v[194:197], v148 offset:50176
	ds_read_b128 v[198:201], v148 offset:51200
	ds_read_b128 v[202:205], v148 offset:52224
	ds_read_b128 v[206:209], v148 offset:53248
	ds_read_b128 v[210:213], v148 offset:54272
	ds_read_b128 v[214:217], v148 offset:55296
	ds_read_b128 v[218:221], v148 offset:56320
	global_load_lds_dwordx4 v[222:223], off
	v_lshl_add_u64 v[222:223], v[224:225], 0, s[8:9]
	s_mov_b32 m0, s58
	s_addc_u32 s15, s15, 0
	global_load_lds_dwordx4 v[222:223], off
	v_lshl_add_u64 v[222:223], s[14:15], 0, v[136:137]
	s_mov_b32 m0, s59
	s_nop 0
	global_load_lds_dwordx4 v[222:223], off
	v_lshl_add_u64 v[222:223], s[14:15], 0, v[132:133]
	s_mov_b32 m0, s60
	s_nop 0
	global_load_lds_dwordx4 v[222:223], off
	v_lshl_add_u64 v[222:223], v[226:227], 0, s[8:9]
	s_mov_b32 m0, s42
	s_nop 0
	global_load_lds_dwordx4 v[222:223], off
	v_lshl_add_u64 v[222:223], v[228:229], 0, s[8:9]
	s_mov_b32 m0, s43
	s_nop 0
	global_load_lds_dwordx4 v[222:223], off
	s_waitcnt vmcnt(8)
	s_waitcnt lgkmcnt(0)
	s_barrier
	s_setprio 1
	s_waitcnt lgkmcnt(0)
	v_mfma_f32_16x16x32_bf16 v[60:63], v[152:155], v[190:193], v[60:63]
	v_mfma_f32_16x16x32_bf16 v[60:63], v[156:159], v[194:197], v[60:63]
	v_mfma_f32_16x16x32_bf16 v[56:59], v[160:163], v[190:193], v[56:59]
	v_mfma_f32_16x16x32_bf16 v[56:59], v[164:167], v[194:197], v[56:59]
	v_mfma_f32_16x16x32_bf16 v[52:55], v[152:155], v[198:201], v[52:55]
	v_mfma_f32_16x16x32_bf16 v[52:55], v[156:159], v[202:205], v[52:55]
	v_mfma_f32_16x16x32_bf16 v[48:51], v[160:163], v[198:201], v[48:51]
	v_mfma_f32_16x16x32_bf16 v[48:51], v[164:167], v[202:205], v[48:51]
	v_mfma_f32_16x16x32_bf16 v[36:39], v[152:155], v[206:209], v[36:39]
	v_mfma_f32_16x16x32_bf16 v[36:39], v[156:159], v[210:213], v[36:39]
	v_mfma_f32_16x16x32_bf16 v[32:35], v[160:163], v[206:209], v[32:35]
	v_mfma_f32_16x16x32_bf16 v[32:35], v[164:167], v[210:213], v[32:35]
	v_mfma_f32_16x16x32_bf16 v[20:23], v[152:155], v[214:217], v[20:23]
	v_mfma_f32_16x16x32_bf16 v[20:23], v[156:159], v[218:221], v[20:23]
	v_mfma_f32_16x16x32_bf16 v[16:19], v[160:163], v[214:217], v[16:19]
	v_mfma_f32_16x16x32_bf16 v[16:19], v[164:167], v[218:221], v[16:19]
	s_setprio 0
	s_setprio 1
	v_mfma_f32_16x16x32_bf16 v[44:47], v[168:171], v[190:193], v[44:47]
	v_mfma_f32_16x16x32_bf16 v[44:47], v[172:175], v[194:197], v[44:47]
	v_mfma_f32_16x16x32_bf16 v[40:43], v[176:179], v[190:193], v[40:43]
	v_mfma_f32_16x16x32_bf16 v[40:43], v[180:183], v[194:197], v[40:43]
	v_mfma_f32_16x16x32_bf16 v[28:31], v[168:171], v[198:201], v[28:31]
	v_mfma_f32_16x16x32_bf16 v[28:31], v[172:175], v[202:205], v[28:31]
	v_mfma_f32_16x16x32_bf16 v[24:27], v[176:179], v[198:201], v[24:27]
	v_mfma_f32_16x16x32_bf16 v[24:27], v[180:183], v[202:205], v[24:27]
	v_mfma_f32_16x16x32_bf16 v[12:15], v[168:171], v[206:209], v[12:15]
	v_mfma_f32_16x16x32_bf16 v[12:15], v[172:175], v[210:213], v[12:15]
	v_mfma_f32_16x16x32_bf16 v[8:11], v[176:179], v[206:209], v[8:11]
	v_mfma_f32_16x16x32_bf16 v[8:11], v[180:183], v[210:213], v[8:11]
	v_mfma_f32_16x16x32_bf16 v[4:7], v[168:171], v[214:217], v[4:7]
	v_mfma_f32_16x16x32_bf16 v[4:7], v[172:175], v[218:221], v[4:7]
	v_mfma_f32_16x16x32_bf16 v[0:3], v[176:179], v[214:217], v[0:3]
	v_mfma_f32_16x16x32_bf16 v[0:3], v[180:183], v[218:221], v[0:3]
	s_setprio 0
	s_barrier
	s_add_i32 s50, s50, 2
	s_add_u32 s12, s12, 0x100
	s_addc_u32 s13, s13, 0
	s_cmp_gt_u32 s50, 29
	s_cbranch_scc0 .LBB0_523
	s_cmpk_lt_u32 s21, 0x100
	s_cbranch_scc0 .LBB0_526
	s_barrier

; #define PG8_STAGE(bufoff, gbase, voff) do { _Pragma("unroll") for (int _i = 0; _i < 2; ++_i) \
;         __builtin_amdgcn_global_load_lds((const unsigned*)((const char*)(gbase) + (voff)[_i]), (LAS unsigned*)(lds + (bufoff) + ldsw + _i * 8192), 16, 0, 0); } while (0)
; #define PG8_LDA(dst, b, h) do { _Pragma("unroll") for (int m = 0; m < 4; ++m) _Pragma("unroll") for (int k = 0; k < 2; ++k) dst[m][k] = *(const LAS bf16x8*)(lds + PG8_SA(b, h) + aoff + m * 2048 + k * 1024); } while (0)
; #define PG8_LDB(dst, b, h) do { _Pragma("unroll") for (int n = 0; n < 2; ++n) _Pragma("unroll") for (int k = 0; k < 2; ++k) dst[n][k] = *(const LAS bf16x8*)(lds + PG8_SB(b, h) + boff + n * 2048 + k * 1024); } while (0)
; #define PG8_MMA(ai, bj, At, Bt) do { __builtin_amdgcn_s_setprio(1); _Pragma("unroll") for (int m = 0; m < 4; ++m) _Pragma("unroll") for (int n = 0; n < 2; ++n) _Pragma("unroll") for (int k = 0; k < 2; ++k) \
;         acc[ai][bj][m][n] = __builtin_amdgcn_mfma_f32_16x16x32_bf16(Bt[n][k], At[m][k], acc[ai][bj][m][n], 0, 0, 0); __builtin_amdgcn_s_setprio(0); } while (0)
; #define PG8_WAIT_V(n) asm volatile("s_waitcnt vmcnt(" #n ")" ::: "memory")
; #define PG8_WAIT_L(n) asm volatile("s_waitcnt lgkmcnt(" #n ")" ::: "memory")
; #define PG8_BAR __builtin_amdgcn_s_barrier()
; #define PG8_SCHED __builtin_amdgcn_sched_barrier(0)
; template <bool ALIGN_EPI, class Epi, class Sched>
; __device__ __forceinline__ void gemm_phase(LAS unsigned char* lds, const int lda, const int ldb, const int K, const Sched& S, const Epi& E, const size_t kstepA = (size_t)(BK * 2), const size_t kstepB = (size_t)(BK * 2)) {
;     ...
;             const char* a1 = cA + (size_t)(t + 1) * kstepA;
;             const char* a2 = last ? nA : cA + (size_t)(t + 2) * kstepA; const char* b2 = last ? nB : cB + (size_t)(t + 2) * kstep;
;             const char* a3 = a2 + kstepA; const char* b3 = b2 + kstep;
;             PG8_LDB(B0, 0, 0); PG8_LDB(B1, 0, 1); PG8_SCHED; PG8_LDA(At, 0, 0); PG8_STAGE(PG8_SA(1, 1), a1 + hstepA, voffA);
;             PG8_WAIT_V(8); PG8_WAIT_L(0); PG8_BAR; PG8_MMA(0, 0, At, B0); PG8_MMA(0, 1, At, B1); PG8_BAR; PG8_SCHED;
;             PG8_LDA(At, 0, 1); PG8_STAGE(PG8_SB(0, 0), b2, voffB); PG8_STAGE(PG8_SB(0, 1), b2 + hstepB, voffB); PG8_STAGE(PG8_SA(0, 0), a2, voffA);
.LBB0_586:
	ds_read_b128 v[152:155], v146
	ds_read_b128 v[156:159], v146 offset:1024
	ds_read_b128 v[160:163], v146 offset:2048
	ds_read_b128 v[164:167], v146 offset:3072
	ds_read_b128 v[168:171], v147
	ds_read_b128 v[172:175], v147 offset:1024
	ds_read_b128 v[176:179], v147 offset:2048
	ds_read_b128 v[180:183], v147 offset:3072
	s_add_u32 s14, s10, s12
	s_addc_u32 s15, s11, s13
	s_add_u32 s14, s14, 0xb84100
	s_addc_u32 s15, s15, 0
	s_add_u32 s60, s43, s12
	s_addc_u32 s61, s46, s13
	s_cmpk_eq_i32 s12, 0x300
	s_cselect_b32 s17, s1, s15
	s_cselect_b32 s16, s0, s14
	s_cselect_b32 s15, s7, s61
	s_cselect_b32 s14, s6, s60
	s_mov_b32 m0, s50
	v_lshl_add_u64 v[222:223], v[140:141], 0, s[12:13]
	ds_read_b128 v[190:193], v148
	ds_read_b128 v[194:197], v148 offset:1024
	ds_read_b128 v[198:201], v148 offset:2048
	ds_read_b128 v[202:205], v148 offset:3072
	ds_read_b128 v[206:209], v148 offset:4096
	ds_read_b128 v[210:213], v148 offset:5120
	ds_read_b128 v[214:217], v148 offset:6144
	ds_read_b128 v[218:221], v148 offset:7168
	global_load_lds_dwordx4 v[222:223], off
	v_lshl_add_u64 v[222:223], v[142:143], 0, s[12:13]
	s_mov_b32 m0, s51
	s_nop 0
	global_load_lds_dwordx4 v[222:223], off
	s_waitcnt vmcnt(8)
	s_waitcnt lgkmcnt(0)
	s_barrier
	s_setprio 1
	s_waitcnt lgkmcnt(0)
	v_mfma_f32_16x16x32_bf16 v[124:127], v[152:155], v[190:193], v[124:127]
	v_mfma_f32_16x16x32_bf16 v[124:127], v[156:159], v[194:197], v[124:127]
	v_mfma_f32_16x16x32_bf16 v[120:123], v[160:163], v[190:193], v[120:123]
	v_mfma_f32_16x16x32_bf16 v[120:123], v[164:167], v[194:197], v[120:123]
	v_mfma_f32_16x16x32_bf16 v[116:119], v[152:155], v[198:201], v[116:119]
	v_mfma_f32_16x16x32_bf16 v[116:119], v[156:159], v[202:205], v[116:119]
	v_mfma_f32_16x16x32_bf16 v[108:111], v[160:163], v[198:201], v[108:111]
	v_mfma_f32_16x16x32_bf16 v[108:111], v[164:167], v[202:205], v[108:111]
	v_mfma_f32_16x16x32_bf16 v[100:103], v[152:155], v[206:209], v[100:103]
	v_mfma_f32_16x16x32_bf16 v[100:103], v[156:159], v[210:213], v[100:103]
	v_mfma_f32_16x16x32_bf16 v[96:99], v[160:163], v[206:209], v[96:99]
	v_mfma_f32_16x16x32_bf16 v[96:99], v[164:167], v[210:213], v[96:99]
	v_mfma_f32_16x16x32_bf16 v[84:87], v[152:155], v[214:217], v[84:87]
	v_mfma_f32_16x16x32_bf16 v[84:87], v[156:159], v[218:221], v[84:87]
	v_mfma_f32_16x16x32_bf16 v[80:83], v[160:163], v[214:217], v[80:83]
	v_mfma_f32_16x16x32_bf16 v[80:83], v[164:167], v[218:221], v[80:83]
	s_setprio 0
	s_setprio 1
	v_mfma_f32_16x16x32_bf16 v[112:115], v[168:171], v[190:193], v[112:115]
	v_mfma_f32_16x16x32_bf16 v[112:115], v[172:175], v[194:197], v[112:115]
	v_mfma_f32_16x16x32_bf16 v[104:107], v[176:179], v[190:193], v[104:107]
	v_mfma_f32_16x16x32_bf16 v[104:107], v[180:183], v[194:197], v[104:107]
	v_mfma_f32_16x16x32_bf16 v[92:95], v[168:171], v[198:201], v[92:95]
	v_mfma_f32_16x16x32_bf16 v[92:95], v[172:175], v[202:205], v[92:95]
	v_mfma_f32_16x16x32_bf16 v[88:91], v[176:179], v[198:201], v[88:91]
	v_mfma_f32_16x16x32_bf16 v[88:91], v[180:183], v[202:205], v[88:91]
	v_mfma_f32_16x16x32_bf16 v[76:79], v[168:171], v[206:209], v[76:79]
	v_mfma_f32_16x16x32_bf16 v[76:79], v[172:175], v[210:213], v[76:79]
	v_mfma_f32_16x16x32_bf16 v[72:75], v[176:179], v[206:209], v[72:75]
	v_mfma_f32_16x16x32_bf16 v[72:75], v[180:183], v[210:213], v[72:75]
	v_mfma_f32_16x16x32_bf16 v[68:71], v[168:171], v[214:217], v[68:71]
	v_mfma_f32_16x16x32_bf16 v[68:71], v[172:175], v[218:221], v[68:71]
	v_mfma_f32_16x16x32_bf16 v[64:67], v[176:179], v[214:217], v[64:67]
	v_mfma_f32_16x16x32_bf16 v[64:67], v[180:183], v[218:221], v[64:67]
	s_setprio 0
	s_barrier
	s_mov_b32 m0, s52
	v_lshl_add_u64 v[222:223], s[14:15], 0, v[136:137]
	s_add_u32 s60, s14, 0x80000
	ds_read_b128 v[190:193], v148 offset:16384
	ds_read_b128 v[194:197], v148 offset:17408
	ds_read_b128 v[198:201], v148 offset:18432
	ds_read_b128 v[202:205], v148 offset:19456
	ds_read_b128 v[206:209], v148 offset:20480
	ds_read_b128 v[210:213], v148 offset:21504
	ds_read_b128 v[214:217], v148 offset:22528
	ds_read_b128 v[218:221], v148 offset:23552
	global_load_lds_dwordx4 v[222:223], off
	v_lshl_add_u64 v[224:225], s[14:15], 0, v[132:133]
	s_mov_b32 m0, s53
	s_addc_u32 s61, s15, 0
	global_load_lds_dwordx4 v[224:225], off
	v_lshl_add_u64 v[226:227], s[60:61], 0, v[136:137]
	s_mov_b32 m0, s54
	v_lshl_add_u64 v[228:229], s[16:17], 0, v[134:135]
	global_load_lds_dwordx4 v[226:227], off
	v_lshl_add_u64 v[226:227], s[60:61], 0, v[132:133]
	s_mov_b32 m0, s55
	s_nop 0
	global_load_lds_dwordx4 v[226:227], off
	v_lshl_add_u64 v[226:227], s[16:17], 0, v[138:139]
	s_mov_b32 m0, s21
	s_nop 0
	global_load_lds_dwordx4 v[226:227], off
	s_mov_b32 m0, s22
	s_nop 0
	global_load_lds_dwordx4 v[228:229], off
	s_waitcnt vmcnt(8)
	s_waitcnt lgkmcnt(0)
	s_barrier
; #define PG8_STAGE(bufoff, gbase, voff) do { _Pragma("unroll") for (int _i = 0; _i < 2; ++_i) \
;         __builtin_amdgcn_global_load_lds((const unsigned*)((const char*)(gbase) + (voff)[_i]), (LAS unsigned*)(lds + (bufoff) + ldsw + _i * 8192), 16, 0, 0); } while (0)
; #define PG8_LDA(dst, b, h) do { _Pragma("unroll") for (int m = 0; m < 4; ++m) _Pragma("unroll") for (int k = 0; k < 2; ++k) dst[m][k] = *(const LAS bf16x8*)(lds + PG8_SA(b, h) + aoff + m * 2048 + k * 1024); } while (0)
; #define PG8_LDB(dst, b, h) do { _Pragma("unroll") for (int n = 0; n < 2; ++n) _Pragma("unroll") for (int k = 0; k < 2; ++k) dst[n][k] = *(const LAS bf16x8*)(lds + PG8_SB(b, h) + boff + n * 2048 + k * 1024); } while (0)
; #define PG8_MMA(ai, bj, At, Bt) do { __builtin_amdgcn_s_setprio(1); _Pragma("unroll") for (int m = 0; m < 4; ++m) _Pragma("unroll") for (int n = 0; n < 2; ++n) _Pragma("unroll") for (int k = 0; k < 2; ++k) \
;         acc[ai][bj][m][n] = __builtin_amdgcn_mfma_f32_16x16x32_bf16(Bt[n][k], At[m][k], acc[ai][bj][m][n], 0, 0, 0); __builtin_amdgcn_s_setprio(0); } while (0)
; #define PG8_WAIT_V(n) asm volatile("s_waitcnt vmcnt(" #n ")" ::: "memory")
; #define PG8_WAIT_L(n) asm volatile("s_waitcnt lgkmcnt(" #n ")" ::: "memory")
; #define PG8_BAR __builtin_amdgcn_s_barrier()
; #define PG8_SCHED __builtin_amdgcn_sched_barrier(0)
; template <bool ALIGN_EPI, class Epi, class Sched>
; __device__ __forceinline__ void gemm_phase(LAS unsigned char* lds, const int lda, const int ldb, const int K, const Sched& S, const Epi& E, const size_t kstepA = (size_t)(BK * 2), const size_t kstepB = (size_t)(BK * 2)) {
;     ...
;             PG8_WAIT_V(8); PG8_WAIT_L(0); PG8_BAR; PG8_MMA(1, 0, At, B0); PG8_MMA(1, 1, At, B1); PG8_BAR; PG8_SCHED;
;             PG8_LDB(B0, 1, 0); PG8_LDB(B1, 1, 1); PG8_SCHED; PG8_LDA(At, 1, 0); PG8_STAGE(PG8_SA(0, 1), a2 + hstepA, voffA);
;             PG8_WAIT_V(8); PG8_WAIT_L(0); PG8_BAR; PG8_MMA(0, 0, At, B0); PG8_MMA(0, 1, At, B1); PG8_BAR; PG8_SCHED;
	s_setprio 1
	s_waitcnt lgkmcnt(0)
	v_mfma_f32_16x16x32_bf16 v[60:63], v[152:155], v[190:193], v[60:63]
	v_mfma_f32_16x16x32_bf16 v[60:63], v[156:159], v[194:197], v[60:63]
	v_mfma_f32_16x16x32_bf16 v[56:59], v[160:163], v[190:193], v[56:59]
	v_mfma_f32_16x16x32_bf16 v[56:59], v[164:167], v[194:197], v[56:59]
	v_mfma_f32_16x16x32_bf16 v[52:55], v[152:155], v[198:201], v[52:55]
	v_mfma_f32_16x16x32_bf16 v[52:55], v[156:159], v[202:205], v[52:55]
	v_mfma_f32_16x16x32_bf16 v[48:51], v[160:163], v[198:201], v[48:51]
	v_mfma_f32_16x16x32_bf16 v[48:51], v[164:167], v[202:205], v[48:51]
	v_mfma_f32_16x16x32_bf16 v[36:39], v[152:155], v[206:209], v[36:39]
	v_mfma_f32_16x16x32_bf16 v[36:39], v[156:159], v[210:213], v[36:39]
	v_mfma_f32_16x16x32_bf16 v[32:35], v[160:163], v[206:209], v[32:35]
	v_mfma_f32_16x16x32_bf16 v[32:35], v[164:167], v[210:213], v[32:35]
	v_mfma_f32_16x16x32_bf16 v[20:23], v[152:155], v[214:217], v[20:23]
	v_mfma_f32_16x16x32_bf16 v[20:23], v[156:159], v[218:221], v[20:23]
	v_mfma_f32_16x16x32_bf16 v[16:19], v[160:163], v[214:217], v[16:19]
	v_mfma_f32_16x16x32_bf16 v[16:19], v[164:167], v[218:221], v[16:19]
	s_setprio 0
	s_setprio 1
	v_mfma_f32_16x16x32_bf16 v[44:47], v[168:171], v[190:193], v[44:47]
	v_mfma_f32_16x16x32_bf16 v[44:47], v[172:175], v[194:197], v[44:47]
	v_mfma_f32_16x16x32_bf16 v[40:43], v[176:179], v[190:193], v[40:43]
	v_mfma_f32_16x16x32_bf16 v[40:43], v[180:183], v[194:197], v[40:43]
	v_mfma_f32_16x16x32_bf16 v[28:31], v[168:171], v[198:201], v[28:31]
	v_mfma_f32_16x16x32_bf16 v[28:31], v[172:175], v[202:205], v[28:31]
	v_mfma_f32_16x16x32_bf16 v[24:27], v[176:179], v[198:201], v[24:27]
	v_mfma_f32_16x16x32_bf16 v[24:27], v[180:183], v[202:205], v[24:27]
	v_mfma_f32_16x16x32_bf16 v[12:15], v[168:171], v[206:209], v[12:15]
	v_mfma_f32_16x16x32_bf16 v[12:15], v[172:175], v[210:213], v[12:15]
	v_mfma_f32_16x16x32_bf16 v[8:11], v[176:179], v[206:209], v[8:11]
	v_mfma_f32_16x16x32_bf16 v[8:11], v[180:183], v[210:213], v[8:11]
	v_mfma_f32_16x16x32_bf16 v[4:7], v[168:171], v[214:217], v[4:7]
	v_mfma_f32_16x16x32_bf16 v[4:7], v[172:175], v[218:221], v[4:7]
	v_mfma_f32_16x16x32_bf16 v[0:3], v[176:179], v[214:217], v[0:3]
	v_mfma_f32_16x16x32_bf16 v[0:3], v[180:183], v[218:221], v[0:3]
	s_setprio 0
	s_barrier
	ds_read_b128 v[152:155], v149
	ds_read_b128 v[156:159], v149 offset:1024
	ds_read_b128 v[160:163], v149 offset:2048
	ds_read_b128 v[164:167], v149 offset:3072
	ds_read_b128 v[168:171], v150
	ds_read_b128 v[172:175], v150 offset:1024
	ds_read_b128 v[176:179], v150 offset:2048
	ds_read_b128 v[180:183], v150 offset:3072
	s_add_u32 s16, s16, 0x20000
	s_addc_u32 s17, s17, 0
	s_mov_b32 m0, s29
	v_lshl_add_u64 v[230:231], s[16:17], 0, v[138:139]
	ds_read_b128 v[190:193], v148 offset:32768
	ds_read_b128 v[194:197], v148 offset:33792
	ds_read_b128 v[198:201], v148 offset:34816
	ds_read_b128 v[202:205], v148 offset:35840
	ds_read_b128 v[206:209], v148 offset:36864
	ds_read_b128 v[210:213], v148 offset:37888
	ds_read_b128 v[214:217], v148 offset:38912
	ds_read_b128 v[218:221], v148 offset:39936
	global_load_lds_dwordx4 v[230:231], off
	v_lshl_add_u64 v[230:231], s[16:17], 0, v[134:135]
	s_mov_b32 m0, s30
	s_nop 0
	global_load_lds_dwordx4 v[230:231], off
	s_waitcnt vmcnt(8)
	s_waitcnt lgkmcnt(0)
	s_barrier
	s_setprio 1
	s_waitcnt lgkmcnt(0)
	v_mfma_f32_16x16x32_bf16 v[124:127], v[152:155], v[190:193], v[124:127]
	v_mfma_f32_16x16x32_bf16 v[124:127], v[156:159], v[194:197], v[124:127]
	v_mfma_f32_16x16x32_bf16 v[120:123], v[160:163], v[190:193], v[120:123]
	v_mfma_f32_16x16x32_bf16 v[120:123], v[164:167], v[194:197], v[120:123]
	v_mfma_f32_16x16x32_bf16 v[116:119], v[152:155], v[198:201], v[116:119]
	v_mfma_f32_16x16x32_bf16 v[116:119], v[156:159], v[202:205], v[116:119]
	v_mfma_f32_16x16x32_bf16 v[108:111], v[160:163], v[198:201], v[108:111]
	v_mfma_f32_16x16x32_bf16 v[108:111], v[164:167], v[202:205], v[108:111]
	v_mfma_f32_16x16x32_bf16 v[100:103], v[152:155], v[206:209], v[100:103]
	v_mfma_f32_16x16x32_bf16 v[100:103], v[156:159], v[210:213], v[100:103]
	v_mfma_f32_16x16x32_bf16 v[96:99], v[160:163], v[206:209], v[96:99]
	v_mfma_f32_16x16x32_bf16 v[96:99], v[164:167], v[210:213], v[96:99]
	v_mfma_f32_16x16x32_bf16 v[84:87], v[152:155], v[214:217], v[84:87]
	v_mfma_f32_16x16x32_bf16 v[84:87], v[156:159], v[218:221], v[84:87]
	v_mfma_f32_16x16x32_bf16 v[80:83], v[160:163], v[214:217], v[80:83]
	v_mfma_f32_16x16x32_bf16 v[80:83], v[164:167], v[218:221], v[80:83]
	s_setprio 0
	s_setprio 1
	v_mfma_f32_16x16x32_bf16 v[112:115], v[168:171], v[190:193], v[112:115]
	v_mfma_f32_16x16x32_bf16 v[112:115], v[172:175], v[194:197], v[112:115]
	v_mfma_f32_16x16x32_bf16 v[104:107], v[176:179], v[190:193], v[104:107]
	v_mfma_f32_16x16x32_bf16 v[104:107], v[180:183], v[194:197], v[104:107]
	v_mfma_f32_16x16x32_bf16 v[92:95], v[168:171], v[198:201], v[92:95]
	v_mfma_f32_16x16x32_bf16 v[92:95], v[172:175], v[202:205], v[92:95]
	v_mfma_f32_16x16x32_bf16 v[88:91], v[176:179], v[198:201], v[88:91]
	v_mfma_f32_16x16x32_bf16 v[88:91], v[180:183], v[202:205], v[88:91]
	v_mfma_f32_16x16x32_bf16 v[76:79], v[168:171], v[206:209], v[76:79]
	v_mfma_f32_16x16x32_bf16 v[76:79], v[172:175], v[210:213], v[76:79]
	v_mfma_f32_16x16x32_bf16 v[72:75], v[176:179], v[206:209], v[72:75]
	v_mfma_f32_16x16x32_bf16 v[72:75], v[180:183], v[210:213], v[72:75]
	v_mfma_f32_16x16x32_bf16 v[68:71], v[168:171], v[214:217], v[68:71]
	v_mfma_f32_16x16x32_bf16 v[68:71], v[172:175], v[218:221], v[68:71]
	v_mfma_f32_16x16x32_bf16 v[64:67], v[176:179], v[214:217], v[64:67]
	v_mfma_f32_16x16x32_bf16 v[64:67], v[180:183], v[218:221], v[64:67]
	s_setprio 0
	s_barrier
; #define PG8_STAGE(bufoff, gbase, voff) do { _Pragma("unroll") for (int _i = 0; _i < 2; ++_i) \
;         __builtin_amdgcn_global_load_lds((const unsigned*)((const char*)(gbase) + (voff)[_i]), (LAS unsigned*)(lds + (bufoff) + ldsw + _i * 8192), 16, 0, 0); } while (0)
; #define PG8_LDA(dst, b, h) do { _Pragma("unroll") for (int m = 0; m < 4; ++m) _Pragma("unroll") for (int k = 0; k < 2; ++k) dst[m][k] = *(const LAS bf16x8*)(lds + PG8_SA(b, h) + aoff + m * 2048 + k * 1024); } while (0)
; #define PG8_MMA(ai, bj, At, Bt) do { __builtin_amdgcn_s_setprio(1); _Pragma("unroll") for (int m = 0; m < 4; ++m) _Pragma("unroll") for (int n = 0; n < 2; ++n) _Pragma("unroll") for (int k = 0; k < 2; ++k) \
;         acc[ai][bj][m][n] = __builtin_amdgcn_mfma_f32_16x16x32_bf16(Bt[n][k], At[m][k], acc[ai][bj][m][n], 0, 0, 0); __builtin_amdgcn_s_setprio(0); } while (0)
; #define PG8_WAIT_V(n) asm volatile("s_waitcnt vmcnt(" #n ")" ::: "memory")
; #define PG8_WAIT_L(n) asm volatile("s_waitcnt lgkmcnt(" #n ")" ::: "memory")
; #define PG8_BAR __builtin_amdgcn_s_barrier()
; #define PG8_SCHED __builtin_amdgcn_sched_barrier(0)
; template <bool ALIGN_EPI, class Epi, class Sched>
; __device__ __forceinline__ void gemm_phase(LAS unsigned char* lds, const int lda, const int ldb, const int K, const Sched& S, const Epi& E, const size_t kstepA = (size_t)(BK * 2), const size_t kstepB = (size_t)(BK * 2)) {
;     ...
;             PG8_LDA(At, 1, 1); PG8_STAGE(PG8_SB(1, 0), b3, voffB); PG8_STAGE(PG8_SB(1, 1), b3 + hstepB, voffB); PG8_STAGE(PG8_SA(1, 0), a3, voffA);
;             PG8_WAIT_V(8); PG8_WAIT_L(0); PG8_BAR; PG8_MMA(1, 0, At, B0); PG8_MMA(1, 1, At, B1); PG8_BAR; PG8_SCHED;
;         }
	s_mov_b32 m0, s56
	v_lshl_add_u64 v[222:223], v[222:223], 0, s[8:9]
	s_add_u32 s14, s14, 0x80080
	ds_read_b128 v[190:193], v148 offset:49152
	ds_read_b128 v[194:197], v148 offset:50176
	ds_read_b128 v[198:201], v148 offset:51200
	ds_read_b128 v[202:205], v148 offset:52224
	ds_read_b128 v[206:209], v148 offset:53248
	ds_read_b128 v[210:213], v148 offset:54272
	ds_read_b128 v[214:217], v148 offset:55296
	ds_read_b128 v[218:221], v148 offset:56320
	global_load_lds_dwordx4 v[222:223], off
	v_lshl_add_u64 v[222:223], v[224:225], 0, s[8:9]
	s_mov_b32 m0, s57
	s_addc_u32 s15, s15, 0
	global_load_lds_dwordx4 v[222:223], off
	v_lshl_add_u64 v[222:223], s[14:15], 0, v[136:137]
	s_mov_b32 m0, s58
	s_nop 0
	global_load_lds_dwordx4 v[222:223], off
	v_lshl_add_u64 v[222:223], s[14:15], 0, v[132:133]
	s_mov_b32 m0, s59
	s_nop 0
	global_load_lds_dwordx4 v[222:223], off
	v_lshl_add_u64 v[222:223], v[226:227], 0, s[8:9]
	s_mov_b32 m0, s33
	s_nop 0
	global_load_lds_dwordx4 v[222:223], off
	v_lshl_add_u64 v[222:223], v[228:229], 0, s[8:9]
	s_mov_b32 m0, s42
	s_nop 0
	global_load_lds_dwordx4 v[222:223], off
	s_waitcnt vmcnt(8)
	s_waitcnt lgkmcnt(0)
	s_barrier
	s_setprio 1
	s_waitcnt lgkmcnt(0)
	v_mfma_f32_16x16x32_bf16 v[60:63], v[152:155], v[190:193], v[60:63]
	v_mfma_f32_16x16x32_bf16 v[60:63], v[156:159], v[194:197], v[60:63]
	v_mfma_f32_16x16x32_bf16 v[56:59], v[160:163], v[190:193], v[56:59]
	v_mfma_f32_16x16x32_bf16 v[56:59], v[164:167], v[194:197], v[56:59]
	v_mfma_f32_16x16x32_bf16 v[52:55], v[152:155], v[198:201], v[52:55]
	v_mfma_f32_16x16x32_bf16 v[52:55], v[156:159], v[202:205], v[52:55]
	v_mfma_f32_16x16x32_bf16 v[48:51], v[160:163], v[198:201], v[48:51]
	v_mfma_f32_16x16x32_bf16 v[48:51], v[164:167], v[202:205], v[48:51]
	v_mfma_f32_16x16x32_bf16 v[36:39], v[152:155], v[206:209], v[36:39]
	v_mfma_f32_16x16x32_bf16 v[36:39], v[156:159], v[210:213], v[36:39]
	v_mfma_f32_16x16x32_bf16 v[32:35], v[160:163], v[206:209], v[32:35]
	v_mfma_f32_16x16x32_bf16 v[32:35], v[164:167], v[210:213], v[32:35]
	v_mfma_f32_16x16x32_bf16 v[20:23], v[152:155], v[214:217], v[20:23]
	v_mfma_f32_16x16x32_bf16 v[20:23], v[156:159], v[218:221], v[20:23]
	v_mfma_f32_16x16x32_bf16 v[16:19], v[160:163], v[214:217], v[16:19]
	v_mfma_f32_16x16x32_bf16 v[16:19], v[164:167], v[218:221], v[16:19]
	s_setprio 0
	s_setprio 1
	v_mfma_f32_16x16x32_bf16 v[44:47], v[168:171], v[190:193], v[44:47]
	v_mfma_f32_16x16x32_bf16 v[44:47], v[172:175], v[194:197], v[44:47]
	v_mfma_f32_16x16x32_bf16 v[40:43], v[176:179], v[190:193], v[40:43]
	v_mfma_f32_16x16x32_bf16 v[40:43], v[180:183], v[194:197], v[40:43]
	v_mfma_f32_16x16x32_bf16 v[28:31], v[168:171], v[198:201], v[28:31]
	v_mfma_f32_16x16x32_bf16 v[28:31], v[172:175], v[202:205], v[28:31]
	v_mfma_f32_16x16x32_bf16 v[24:27], v[176:179], v[198:201], v[24:27]
	v_mfma_f32_16x16x32_bf16 v[24:27], v[180:183], v[202:205], v[24:27]
	v_mfma_f32_16x16x32_bf16 v[12:15], v[168:171], v[206:209], v[12:15]
	v_mfma_f32_16x16x32_bf16 v[12:15], v[172:175], v[210:213], v[12:15]
	v_mfma_f32_16x16x32_bf16 v[8:11], v[176:179], v[206:209], v[8:11]
	v_mfma_f32_16x16x32_bf16 v[8:11], v[180:183], v[210:213], v[8:11]
	v_mfma_f32_16x16x32_bf16 v[4:7], v[168:171], v[214:217], v[4:7]
	v_mfma_f32_16x16x32_bf16 v[4:7], v[172:175], v[218:221], v[4:7]
	v_mfma_f32_16x16x32_bf16 v[0:3], v[176:179], v[214:217], v[0:3]
	v_mfma_f32_16x16x32_bf16 v[0:3], v[180:183], v[218:221], v[0:3]
	s_setprio 0
	s_barrier
	s_add_i32 s47, s47, 2
	s_add_u32 s12, s12, 0x100
	s_addc_u32 s13, s13, 0
	s_cmp_gt_u32 s47, 5
	s_cbranch_scc0 .LBB0_586
	s_cmpk_lt_u32 s18, 0x100
	s_cbranch_scc0 .LBB0_589
	s_barrier

; #define PG8_STAGE(bufoff, gbase, voff) do { _Pragma("unroll") for (int _i = 0; _i < 2; ++_i) \
;         __builtin_amdgcn_global_load_lds((const unsigned*)((const char*)(gbase) + (voff)[_i]), (LAS unsigned*)(lds + (bufoff) + ldsw + _i * 8192), 16, 0, 0); } while (0)
; #define PG8_LDA(dst, b, h) do { _Pragma("unroll") for (int m = 0; m < 4; ++m) _Pragma("unroll") for (int k = 0; k < 2; ++k) dst[m][k] = *(const LAS bf16x8*)(lds + PG8_SA(b, h) + aoff + m * 2048 + k * 1024); } while (0)
; #define PG8_LDB(dst, b, h) do { _Pragma("unroll") for (int n = 0; n < 2; ++n) _Pragma("unroll") for (int k = 0; k < 2; ++k) dst[n][k] = *(const LAS bf16x8*)(lds + PG8_SB(b, h) + boff + n * 2048 + k * 1024); } while (0)
; #define PG8_MMA(ai, bj, At, Bt) do { __builtin_amdgcn_s_setprio(1); _Pragma("unroll") for (int m = 0; m < 4; ++m) _Pragma("unroll") for (int n = 0; n < 2; ++n) _Pragma("unroll") for (int k = 0; k < 2; ++k) \
;         acc[ai][bj][m][n] = __builtin_amdgcn_mfma_f32_16x16x32_bf16(Bt[n][k], At[m][k], acc[ai][bj][m][n], 0, 0, 0); __builtin_amdgcn_s_setprio(0); } while (0)
; #define PG8_WAIT_V(n) asm volatile("s_waitcnt vmcnt(" #n ")" ::: "memory")
; #define PG8_WAIT_L(n) asm volatile("s_waitcnt lgkmcnt(" #n ")" ::: "memory")
; #define PG8_BAR __builtin_amdgcn_s_barrier()
; #define PG8_SCHED __builtin_amdgcn_sched_barrier(0)
; template <bool ALIGN_EPI, class Epi, class Sched>
; __device__ __forceinline__ void gemm_phase(LAS unsigned char* lds, const int lda, const int ldb, const int K, const Sched& S, const Epi& E, const size_t kstepA = (size_t)(BK * 2), const size_t kstepB = (size_t)(BK * 2)) {
;     ...
;             const char* a1 = cA + (size_t)(t + 1) * kstepA;
;             const char* a2 = last ? nA : cA + (size_t)(t + 2) * kstepA; const char* b2 = last ? nB : cB + (size_t)(t + 2) * kstep;
;             const char* a3 = a2 + kstepA; const char* b3 = b2 + kstep;
;             PG8_LDB(B0, 0, 0); PG8_LDB(B1, 0, 1); PG8_SCHED; PG8_LDA(At, 0, 0); PG8_STAGE(PG8_SA(1, 1), a1 + hstepA, voffA);
;             PG8_WAIT_V(8); PG8_WAIT_L(0); PG8_BAR; PG8_MMA(0, 0, At, B0); PG8_MMA(0, 1, At, B1); PG8_BAR; PG8_SCHED;
;             PG8_LDA(At, 0, 1); PG8_STAGE(PG8_SB(0, 0), b2, voffB); PG8_STAGE(PG8_SB(0, 1), b2 + hstepB, voffB); PG8_STAGE(PG8_SA(0, 0), a2, voffA);
.LBB0_594:
	ds_read_b128 v[152:155], v146
	ds_read_b128 v[156:159], v146 offset:1024
	ds_read_b128 v[160:163], v146 offset:2048
	ds_read_b128 v[164:167], v146 offset:3072
	ds_read_b128 v[168:171], v147
	ds_read_b128 v[172:175], v147 offset:1024
	ds_read_b128 v[176:179], v147 offset:2048
	ds_read_b128 v[180:183], v147 offset:3072
	s_add_u32 s14, s10, s12
	s_addc_u32 s15, s11, s13
	s_add_u32 s14, s14, 0xc414100
	s_addc_u32 s15, s15, 0
	s_add_u32 s63, s50, s12
	s_addc_u32 s64, s51, s13
	s_cmpk_eq_i32 s12, 0x300
	s_cselect_b32 s17, s1, s15
	s_cselect_b32 s16, s0, s14
	s_cselect_b32 s15, s7, s64
	s_cselect_b32 s14, s6, s63
	s_mov_b32 m0, s53
	v_lshl_add_u64 v[222:223], v[140:141], 0, s[12:13]
	ds_read_b128 v[190:193], v148
	ds_read_b128 v[194:197], v148 offset:1024
	ds_read_b128 v[198:201], v148 offset:2048
	ds_read_b128 v[202:205], v148 offset:3072
	ds_read_b128 v[206:209], v148 offset:4096
	ds_read_b128 v[210:213], v148 offset:5120
	ds_read_b128 v[214:217], v148 offset:6144
	ds_read_b128 v[218:221], v148 offset:7168
	global_load_lds_dwordx4 v[222:223], off
	v_lshl_add_u64 v[222:223], v[142:143], 0, s[12:13]
	s_mov_b32 m0, s54
	s_nop 0
	global_load_lds_dwordx4 v[222:223], off
	s_waitcnt vmcnt(8)
	s_waitcnt lgkmcnt(0)
	s_barrier
	s_setprio 1
	s_waitcnt lgkmcnt(0)
	v_mfma_f32_16x16x32_bf16 v[124:127], v[152:155], v[190:193], v[124:127]
	v_mfma_f32_16x16x32_bf16 v[124:127], v[156:159], v[194:197], v[124:127]
	v_mfma_f32_16x16x32_bf16 v[120:123], v[160:163], v[190:193], v[120:123]
	v_mfma_f32_16x16x32_bf16 v[120:123], v[164:167], v[194:197], v[120:123]
	v_mfma_f32_16x16x32_bf16 v[116:119], v[152:155], v[198:201], v[116:119]
	v_mfma_f32_16x16x32_bf16 v[116:119], v[156:159], v[202:205], v[116:119]
	v_mfma_f32_16x16x32_bf16 v[108:111], v[160:163], v[198:201], v[108:111]
	v_mfma_f32_16x16x32_bf16 v[108:111], v[164:167], v[202:205], v[108:111]
	v_mfma_f32_16x16x32_bf16 v[100:103], v[152:155], v[206:209], v[100:103]
	v_mfma_f32_16x16x32_bf16 v[100:103], v[156:159], v[210:213], v[100:103]
	v_mfma_f32_16x16x32_bf16 v[96:99], v[160:163], v[206:209], v[96:99]
	v_mfma_f32_16x16x32_bf16 v[96:99], v[164:167], v[210:213], v[96:99]
	v_mfma_f32_16x16x32_bf16 v[84:87], v[152:155], v[214:217], v[84:87]
	v_mfma_f32_16x16x32_bf16 v[84:87], v[156:159], v[218:221], v[84:87]
	v_mfma_f32_16x16x32_bf16 v[80:83], v[160:163], v[214:217], v[80:83]
	v_mfma_f32_16x16x32_bf16 v[80:83], v[164:167], v[218:221], v[80:83]
	s_setprio 0
	s_setprio 1
	v_mfma_f32_16x16x32_bf16 v[112:115], v[168:171], v[190:193], v[112:115]
	v_mfma_f32_16x16x32_bf16 v[112:115], v[172:175], v[194:197], v[112:115]
	v_mfma_f32_16x16x32_bf16 v[104:107], v[176:179], v[190:193], v[104:107]
	v_mfma_f32_16x16x32_bf16 v[104:107], v[180:183], v[194:197], v[104:107]
	v_mfma_f32_16x16x32_bf16 v[92:95], v[168:171], v[198:201], v[92:95]
	v_mfma_f32_16x16x32_bf16 v[92:95], v[172:175], v[202:205], v[92:95]
	v_mfma_f32_16x16x32_bf16 v[88:91], v[176:179], v[198:201], v[88:91]
	v_mfma_f32_16x16x32_bf16 v[88:91], v[180:183], v[202:205], v[88:91]
	v_mfma_f32_16x16x32_bf16 v[76:79], v[168:171], v[206:209], v[76:79]
	v_mfma_f32_16x16x32_bf16 v[76:79], v[172:175], v[210:213], v[76:79]
	v_mfma_f32_16x16x32_bf16 v[72:75], v[176:179], v[206:209], v[72:75]
	v_mfma_f32_16x16x32_bf16 v[72:75], v[180:183], v[210:213], v[72:75]
	v_mfma_f32_16x16x32_bf16 v[68:71], v[168:171], v[214:217], v[68:71]
	v_mfma_f32_16x16x32_bf16 v[68:71], v[172:175], v[218:221], v[68:71]
	v_mfma_f32_16x16x32_bf16 v[64:67], v[176:179], v[214:217], v[64:67]
	v_mfma_f32_16x16x32_bf16 v[64:67], v[180:183], v[218:221], v[64:67]
	s_setprio 0
	s_barrier
	s_mov_b32 m0, s55
	v_lshl_add_u64 v[222:223], s[14:15], 0, v[136:137]
	s_add_u32 s64, s14, 0x20000
	ds_read_b128 v[190:193], v148 offset:16384
	ds_read_b128 v[194:197], v148 offset:17408
	ds_read_b128 v[198:201], v148 offset:18432
	ds_read_b128 v[202:205], v148 offset:19456
	ds_read_b128 v[206:209], v148 offset:20480
	ds_read_b128 v[210:213], v148 offset:21504
	ds_read_b128 v[214:217], v148 offset:22528
	ds_read_b128 v[218:221], v148 offset:23552
	global_load_lds_dwordx4 v[222:223], off
	v_lshl_add_u64 v[224:225], s[14:15], 0, v[132:133]
	s_mov_b32 m0, s56
	s_addc_u32 s65, s15, 0
	global_load_lds_dwordx4 v[224:225], off
	v_lshl_add_u64 v[226:227], s[64:65], 0, v[136:137]
	s_mov_b32 m0, s57
	v_lshl_add_u64 v[228:229], s[16:17], 0, v[134:135]
	global_load_lds_dwordx4 v[226:227], off
	v_lshl_add_u64 v[226:227], s[64:65], 0, v[132:133]
	s_mov_b32 m0, s58
	s_nop 0
	global_load_lds_dwordx4 v[226:227], off
	v_lshl_add_u64 v[226:227], s[16:17], 0, v[138:139]
	s_mov_b32 m0, s21
	s_nop 0
	global_load_lds_dwordx4 v[226:227], off
	s_mov_b32 m0, s22
	s_nop 0
	global_load_lds_dwordx4 v[228:229], off
	s_waitcnt vmcnt(8)
	s_waitcnt lgkmcnt(0)
	s_barrier
; #define PG8_STAGE(bufoff, gbase, voff) do { _Pragma("unroll") for (int _i = 0; _i < 2; ++_i) \
;         __builtin_amdgcn_global_load_lds((const unsigned*)((const char*)(gbase) + (voff)[_i]), (LAS unsigned*)(lds + (bufoff) + ldsw + _i * 8192), 16, 0, 0); } while (0)
; #define PG8_LDA(dst, b, h) do { _Pragma("unroll") for (int m = 0; m < 4; ++m) _Pragma("unroll") for (int k = 0; k < 2; ++k) dst[m][k] = *(const LAS bf16x8*)(lds + PG8_SA(b, h) + aoff + m * 2048 + k * 1024); } while (0)
; #define PG8_LDB(dst, b, h) do { _Pragma("unroll") for (int n = 0; n < 2; ++n) _Pragma("unroll") for (int k = 0; k < 2; ++k) dst[n][k] = *(const LAS bf16x8*)(lds + PG8_SB(b, h) + boff + n * 2048 + k * 1024); } while (0)
; #define PG8_MMA(ai, bj, At, Bt) do { __builtin_amdgcn_s_setprio(1); _Pragma("unroll") for (int m = 0; m < 4; ++m) _Pragma("unroll") for (int n = 0; n < 2; ++n) _Pragma("unroll") for (int k = 0; k < 2; ++k) \
;         acc[ai][bj][m][n] = __builtin_amdgcn_mfma_f32_16x16x32_bf16(Bt[n][k], At[m][k], acc[ai][bj][m][n], 0, 0, 0); __builtin_amdgcn_s_setprio(0); } while (0)
; #define PG8_WAIT_V(n) asm volatile("s_waitcnt vmcnt(" #n ")" ::: "memory")
; #define PG8_WAIT_L(n) asm volatile("s_waitcnt lgkmcnt(" #n ")" ::: "memory")
; #define PG8_BAR __builtin_amdgcn_s_barrier()
; #define PG8_SCHED __builtin_amdgcn_sched_barrier(0)
; template <bool ALIGN_EPI, class Epi, class Sched>
; __device__ __forceinline__ void gemm_phase(LAS unsigned char* lds, const int lda, const int ldb, const int K, const Sched& S, const Epi& E, const size_t kstepA = (size_t)(BK * 2), const size_t kstepB = (size_t)(BK * 2)) {
;     ...
;             PG8_WAIT_V(8); PG8_WAIT_L(0); PG8_BAR; PG8_MMA(1, 0, At, B0); PG8_MMA(1, 1, At, B1); PG8_BAR; PG8_SCHED;
;             PG8_LDB(B0, 1, 0); PG8_LDB(B1, 1, 1); PG8_SCHED; PG8_LDA(At, 1, 0); PG8_STAGE(PG8_SA(0, 1), a2 + hstepA, voffA);
;             PG8_WAIT_V(8); PG8_WAIT_L(0); PG8_BAR; PG8_MMA(0, 0, At, B0); PG8_MMA(0, 1, At, B1); PG8_BAR; PG8_SCHED;
	s_setprio 1
	s_waitcnt lgkmcnt(0)
	v_mfma_f32_16x16x32_bf16 v[60:63], v[152:155], v[190:193], v[60:63]
	v_mfma_f32_16x16x32_bf16 v[60:63], v[156:159], v[194:197], v[60:63]
	v_mfma_f32_16x16x32_bf16 v[56:59], v[160:163], v[190:193], v[56:59]
	v_mfma_f32_16x16x32_bf16 v[56:59], v[164:167], v[194:197], v[56:59]
	v_mfma_f32_16x16x32_bf16 v[52:55], v[152:155], v[198:201], v[52:55]
	v_mfma_f32_16x16x32_bf16 v[52:55], v[156:159], v[202:205], v[52:55]
	v_mfma_f32_16x16x32_bf16 v[48:51], v[160:163], v[198:201], v[48:51]
	v_mfma_f32_16x16x32_bf16 v[48:51], v[164:167], v[202:205], v[48:51]
	v_mfma_f32_16x16x32_bf16 v[36:39], v[152:155], v[206:209], v[36:39]
	v_mfma_f32_16x16x32_bf16 v[36:39], v[156:159], v[210:213], v[36:39]
	v_mfma_f32_16x16x32_bf16 v[32:35], v[160:163], v[206:209], v[32:35]
	v_mfma_f32_16x16x32_bf16 v[32:35], v[164:167], v[210:213], v[32:35]
	v_mfma_f32_16x16x32_bf16 v[20:23], v[152:155], v[214:217], v[20:23]
	v_mfma_f32_16x16x32_bf16 v[20:23], v[156:159], v[218:221], v[20:23]
	v_mfma_f32_16x16x32_bf16 v[16:19], v[160:163], v[214:217], v[16:19]
	v_mfma_f32_16x16x32_bf16 v[16:19], v[164:167], v[218:221], v[16:19]
	s_setprio 0
	s_setprio 1
	v_mfma_f32_16x16x32_bf16 v[44:47], v[168:171], v[190:193], v[44:47]
	v_mfma_f32_16x16x32_bf16 v[44:47], v[172:175], v[194:197], v[44:47]
	v_mfma_f32_16x16x32_bf16 v[40:43], v[176:179], v[190:193], v[40:43]
	v_mfma_f32_16x16x32_bf16 v[40:43], v[180:183], v[194:197], v[40:43]
	v_mfma_f32_16x16x32_bf16 v[28:31], v[168:171], v[198:201], v[28:31]
	v_mfma_f32_16x16x32_bf16 v[28:31], v[172:175], v[202:205], v[28:31]
	v_mfma_f32_16x16x32_bf16 v[24:27], v[176:179], v[198:201], v[24:27]
	v_mfma_f32_16x16x32_bf16 v[24:27], v[180:183], v[202:205], v[24:27]
	v_mfma_f32_16x16x32_bf16 v[12:15], v[168:171], v[206:209], v[12:15]
	v_mfma_f32_16x16x32_bf16 v[12:15], v[172:175], v[210:213], v[12:15]
	v_mfma_f32_16x16x32_bf16 v[8:11], v[176:179], v[206:209], v[8:11]
	v_mfma_f32_16x16x32_bf16 v[8:11], v[180:183], v[210:213], v[8:11]
	v_mfma_f32_16x16x32_bf16 v[4:7], v[168:171], v[214:217], v[4:7]
	v_mfma_f32_16x16x32_bf16 v[4:7], v[172:175], v[218:221], v[4:7]
	v_mfma_f32_16x16x32_bf16 v[0:3], v[176:179], v[214:217], v[0:3]
	v_mfma_f32_16x16x32_bf16 v[0:3], v[180:183], v[218:221], v[0:3]
	s_setprio 0
	s_barrier
	ds_read_b128 v[152:155], v149
	ds_read_b128 v[156:159], v149 offset:1024
	ds_read_b128 v[160:163], v149 offset:2048
	ds_read_b128 v[164:167], v149 offset:3072
	ds_read_b128 v[168:171], v150
	ds_read_b128 v[172:175], v150 offset:1024
	ds_read_b128 v[176:179], v150 offset:2048
	ds_read_b128 v[180:183], v150 offset:3072
	s_add_u32 s16, s16, 0x80000
	s_addc_u32 s17, s17, 0
	s_mov_b32 m0, s33
	v_lshl_add_u64 v[230:231], s[16:17], 0, v[138:139]
	ds_read_b128 v[190:193], v148 offset:32768
	ds_read_b128 v[194:197], v148 offset:33792
	ds_read_b128 v[198:201], v148 offset:34816
	ds_read_b128 v[202:205], v148 offset:35840
	ds_read_b128 v[206:209], v148 offset:36864
	ds_read_b128 v[210:213], v148 offset:37888
	ds_read_b128 v[214:217], v148 offset:38912
	ds_read_b128 v[218:221], v148 offset:39936
	global_load_lds_dwordx4 v[230:231], off
	v_lshl_add_u64 v[230:231], s[16:17], 0, v[134:135]
	s_mov_b32 m0, s42
	s_nop 0
	global_load_lds_dwordx4 v[230:231], off
	s_waitcnt vmcnt(8)
	s_waitcnt lgkmcnt(0)
	s_barrier
	s_setprio 1
	s_waitcnt lgkmcnt(0)
	v_mfma_f32_16x16x32_bf16 v[124:127], v[152:155], v[190:193], v[124:127]
	v_mfma_f32_16x16x32_bf16 v[124:127], v[156:159], v[194:197], v[124:127]
	v_mfma_f32_16x16x32_bf16 v[120:123], v[160:163], v[190:193], v[120:123]
	v_mfma_f32_16x16x32_bf16 v[120:123], v[164:167], v[194:197], v[120:123]
	v_mfma_f32_16x16x32_bf16 v[116:119], v[152:155], v[198:201], v[116:119]
	v_mfma_f32_16x16x32_bf16 v[116:119], v[156:159], v[202:205], v[116:119]
	v_mfma_f32_16x16x32_bf16 v[108:111], v[160:163], v[198:201], v[108:111]
	v_mfma_f32_16x16x32_bf16 v[108:111], v[164:167], v[202:205], v[108:111]
	v_mfma_f32_16x16x32_bf16 v[100:103], v[152:155], v[206:209], v[100:103]
	v_mfma_f32_16x16x32_bf16 v[100:103], v[156:159], v[210:213], v[100:103]
	v_mfma_f32_16x16x32_bf16 v[96:99], v[160:163], v[206:209], v[96:99]
	v_mfma_f32_16x16x32_bf16 v[96:99], v[164:167], v[210:213], v[96:99]
	v_mfma_f32_16x16x32_bf16 v[84:87], v[152:155], v[214:217], v[84:87]
	v_mfma_f32_16x16x32_bf16 v[84:87], v[156:159], v[218:221], v[84:87]
	v_mfma_f32_16x16x32_bf16 v[80:83], v[160:163], v[214:217], v[80:83]
	v_mfma_f32_16x16x32_bf16 v[80:83], v[164:167], v[218:221], v[80:83]
	s_setprio 0
	s_setprio 1
	v_mfma_f32_16x16x32_bf16 v[112:115], v[168:171], v[190:193], v[112:115]
	v_mfma_f32_16x16x32_bf16 v[112:115], v[172:175], v[194:197], v[112:115]
	v_mfma_f32_16x16x32_bf16 v[104:107], v[176:179], v[190:193], v[104:107]
	v_mfma_f32_16x16x32_bf16 v[104:107], v[180:183], v[194:197], v[104:107]
	v_mfma_f32_16x16x32_bf16 v[92:95], v[168:171], v[198:201], v[92:95]
	v_mfma_f32_16x16x32_bf16 v[92:95], v[172:175], v[202:205], v[92:95]
	v_mfma_f32_16x16x32_bf16 v[88:91], v[176:179], v[198:201], v[88:91]
	v_mfma_f32_16x16x32_bf16 v[88:91], v[180:183], v[202:205], v[88:91]
	v_mfma_f32_16x16x32_bf16 v[76:79], v[168:171], v[206:209], v[76:79]
	v_mfma_f32_16x16x32_bf16 v[76:79], v[172:175], v[210:213], v[76:79]
	v_mfma_f32_16x16x32_bf16 v[72:75], v[176:179], v[206:209], v[72:75]
	v_mfma_f32_16x16x32_bf16 v[72:75], v[180:183], v[210:213], v[72:75]
	v_mfma_f32_16x16x32_bf16 v[68:71], v[168:171], v[214:217], v[68:71]
	v_mfma_f32_16x16x32_bf16 v[68:71], v[172:175], v[218:221], v[68:71]
	v_mfma_f32_16x16x32_bf16 v[64:67], v[176:179], v[214:217], v[64:67]
	v_mfma_f32_16x16x32_bf16 v[64:67], v[180:183], v[218:221], v[64:67]
	s_setprio 0
	s_barrier
; #define PG8_STAGE(bufoff, gbase, voff) do { _Pragma("unroll") for (int _i = 0; _i < 2; ++_i) \
;         __builtin_amdgcn_global_load_lds((const unsigned*)((const char*)(gbase) + (voff)[_i]), (LAS unsigned*)(lds + (bufoff) + ldsw + _i * 8192), 16, 0, 0); } while (0)
; #define PG8_LDA(dst, b, h) do { _Pragma("unroll") for (int m = 0; m < 4; ++m) _Pragma("unroll") for (int k = 0; k < 2; ++k) dst[m][k] = *(const LAS bf16x8*)(lds + PG8_SA(b, h) + aoff + m * 2048 + k * 1024); } while (0)
; #define PG8_MMA(ai, bj, At, Bt) do { __builtin_amdgcn_s_setprio(1); _Pragma("unroll") for (int m = 0; m < 4; ++m) _Pragma("unroll") for (int n = 0; n < 2; ++n) _Pragma("unroll") for (int k = 0; k < 2; ++k) \
;         acc[ai][bj][m][n] = __builtin_amdgcn_mfma_f32_16x16x32_bf16(Bt[n][k], At[m][k], acc[ai][bj][m][n], 0, 0, 0); __builtin_amdgcn_s_setprio(0); } while (0)
; #define PG8_WAIT_V(n) asm volatile("s_waitcnt vmcnt(" #n ")" ::: "memory")
; #define PG8_WAIT_L(n) asm volatile("s_waitcnt lgkmcnt(" #n ")" ::: "memory")
; #define PG8_BAR __builtin_amdgcn_s_barrier()
; #define PG8_SCHED __builtin_amdgcn_sched_barrier(0)
; template <bool ALIGN_EPI, class Epi, class Sched>
; __device__ __forceinline__ void gemm_phase(LAS unsigned char* lds, const int lda, const int ldb, const int K, const Sched& S, const Epi& E, const size_t kstepA = (size_t)(BK * 2), const size_t kstepB = (size_t)(BK * 2)) {
;     ...
;             PG8_LDA(At, 1, 1); PG8_STAGE(PG8_SB(1, 0), b3, voffB); PG8_STAGE(PG8_SB(1, 1), b3 + hstepB, voffB); PG8_STAGE(PG8_SA(1, 0), a3, voffA);
;             PG8_WAIT_V(8); PG8_WAIT_L(0); PG8_BAR; PG8_MMA(1, 0, At, B0); PG8_MMA(1, 1, At, B1); PG8_BAR; PG8_SCHED;
;         }
	s_mov_b32 m0, s59
	v_lshl_add_u64 v[222:223], v[222:223], 0, s[8:9]
	s_add_u32 s14, s14, 0x20080
	ds_read_b128 v[190:193], v148 offset:49152
	ds_read_b128 v[194:197], v148 offset:50176
	ds_read_b128 v[198:201], v148 offset:51200
	ds_read_b128 v[202:205], v148 offset:52224
	ds_read_b128 v[206:209], v148 offset:53248
	ds_read_b128 v[210:213], v148 offset:54272
	ds_read_b128 v[214:217], v148 offset:55296
	ds_read_b128 v[218:221], v148 offset:56320
	global_load_lds_dwordx4 v[222:223], off
	v_lshl_add_u64 v[222:223], v[224:225], 0, s[8:9]
	s_mov_b32 m0, s60
	s_addc_u32 s15, s15, 0
	global_load_lds_dwordx4 v[222:223], off
	v_lshl_add_u64 v[222:223], s[14:15], 0, v[136:137]
	s_mov_b32 m0, s61
	s_nop 0
	global_load_lds_dwordx4 v[222:223], off
	v_lshl_add_u64 v[222:223], s[14:15], 0, v[132:133]
	s_mov_b32 m0, s62
	s_nop 0
	global_load_lds_dwordx4 v[222:223], off
	v_lshl_add_u64 v[222:223], v[226:227], 0, s[8:9]
	s_mov_b32 m0, s46
	s_nop 0
	global_load_lds_dwordx4 v[222:223], off
	v_lshl_add_u64 v[222:223], v[228:229], 0, s[8:9]
	s_mov_b32 m0, s47
	s_nop 0
	global_load_lds_dwordx4 v[222:223], off
	s_waitcnt vmcnt(8)
	s_waitcnt lgkmcnt(0)
	s_barrier
	s_setprio 1
	s_waitcnt lgkmcnt(0)
	v_mfma_f32_16x16x32_bf16 v[60:63], v[152:155], v[190:193], v[60:63]
	v_mfma_f32_16x16x32_bf16 v[60:63], v[156:159], v[194:197], v[60:63]
	v_mfma_f32_16x16x32_bf16 v[56:59], v[160:163], v[190:193], v[56:59]
	v_mfma_f32_16x16x32_bf16 v[56:59], v[164:167], v[194:197], v[56:59]
	v_mfma_f32_16x16x32_bf16 v[52:55], v[152:155], v[198:201], v[52:55]
	v_mfma_f32_16x16x32_bf16 v[52:55], v[156:159], v[202:205], v[52:55]
	v_mfma_f32_16x16x32_bf16 v[48:51], v[160:163], v[198:201], v[48:51]
	v_mfma_f32_16x16x32_bf16 v[48:51], v[164:167], v[202:205], v[48:51]
	v_mfma_f32_16x16x32_bf16 v[36:39], v[152:155], v[206:209], v[36:39]
	v_mfma_f32_16x16x32_bf16 v[36:39], v[156:159], v[210:213], v[36:39]
	v_mfma_f32_16x16x32_bf16 v[32:35], v[160:163], v[206:209], v[32:35]
	v_mfma_f32_16x16x32_bf16 v[32:35], v[164:167], v[210:213], v[32:35]
	v_mfma_f32_16x16x32_bf16 v[20:23], v[152:155], v[214:217], v[20:23]
	v_mfma_f32_16x16x32_bf16 v[20:23], v[156:159], v[218:221], v[20:23]
	v_mfma_f32_16x16x32_bf16 v[16:19], v[160:163], v[214:217], v[16:19]
	v_mfma_f32_16x16x32_bf16 v[16:19], v[164:167], v[218:221], v[16:19]
	s_setprio 0
	s_setprio 1
	v_mfma_f32_16x16x32_bf16 v[44:47], v[168:171], v[190:193], v[44:47]
	v_mfma_f32_16x16x32_bf16 v[44:47], v[172:175], v[194:197], v[44:47]
	v_mfma_f32_16x16x32_bf16 v[40:43], v[176:179], v[190:193], v[40:43]
	v_mfma_f32_16x16x32_bf16 v[40:43], v[180:183], v[194:197], v[40:43]
	v_mfma_f32_16x16x32_bf16 v[28:31], v[168:171], v[198:201], v[28:31]
	v_mfma_f32_16x16x32_bf16 v[28:31], v[172:175], v[202:205], v[28:31]
	v_mfma_f32_16x16x32_bf16 v[24:27], v[176:179], v[198:201], v[24:27]
	v_mfma_f32_16x16x32_bf16 v[24:27], v[180:183], v[202:205], v[24:27]
	v_mfma_f32_16x16x32_bf16 v[12:15], v[168:171], v[206:209], v[12:15]
	v_mfma_f32_16x16x32_bf16 v[12:15], v[172:175], v[210:213], v[12:15]
	v_mfma_f32_16x16x32_bf16 v[8:11], v[176:179], v[206:209], v[8:11]
	v_mfma_f32_16x16x32_bf16 v[8:11], v[180:183], v[210:213], v[8:11]
	v_mfma_f32_16x16x32_bf16 v[4:7], v[168:171], v[214:217], v[4:7]
	v_mfma_f32_16x16x32_bf16 v[4:7], v[172:175], v[218:221], v[4:7]
	v_mfma_f32_16x16x32_bf16 v[0:3], v[176:179], v[214:217], v[0:3]
	v_mfma_f32_16x16x32_bf16 v[0:3], v[180:183], v[218:221], v[0:3]
	s_setprio 0
	s_barrier
	s_add_i32 s52, s52, 2
	s_add_u32 s12, s12, 0x100
	s_addc_u32 s13, s13, 0
	s_cmp_gt_u32 s52, 5
	s_cbranch_scc0 .LBB0_594
	s_cmpk_lt_u32 s18, 0x100
	s_cbranch_scc0 .LBB0_597
	s_barrier

; #define PG8_STAGE(bufoff, gbase, voff) do { _Pragma("unroll") for (int _i = 0; _i < 2; ++_i) \
;         __builtin_amdgcn_global_load_lds((const unsigned*)((const char*)(gbase) + (voff)[_i]), (LAS unsigned*)(lds + (bufoff) + ldsw + _i * 8192), 16, 0, 0); } while (0)
; #define PG8_LDA(dst, b, h) do { _Pragma("unroll") for (int m = 0; m < 4; ++m) _Pragma("unroll") for (int k = 0; k < 2; ++k) dst[m][k] = *(const LAS bf16x8*)(lds + PG8_SA(b, h) + aoff + m * 2048 + k * 1024); } while (0)
; #define PG8_LDB(dst, b, h) do { _Pragma("unroll") for (int n = 0; n < 2; ++n) _Pragma("unroll") for (int k = 0; k < 2; ++k) dst[n][k] = *(const LAS bf16x8*)(lds + PG8_SB(b, h) + boff + n * 2048 + k * 1024); } while (0)
; #define PG8_MMA(ai, bj, At, Bt) do { __builtin_amdgcn_s_setprio(1); _Pragma("unroll") for (int m = 0; m < 4; ++m) _Pragma("unroll") for (int n = 0; n < 2; ++n) _Pragma("unroll") for (int k = 0; k < 2; ++k) \
;         acc[ai][bj][m][n] = __builtin_amdgcn_mfma_f32_16x16x32_bf16(Bt[n][k], At[m][k], acc[ai][bj][m][n], 0, 0, 0); __builtin_amdgcn_s_setprio(0); } while (0)
; #define PG8_WAIT_V(n) asm volatile("s_waitcnt vmcnt(" #n ")" ::: "memory")
; #define PG8_WAIT_L(n) asm volatile("s_waitcnt lgkmcnt(" #n ")" ::: "memory")
; #define PG8_BAR __builtin_amdgcn_s_barrier()
; #define PG8_SCHED __builtin_amdgcn_sched_barrier(0)
; template <bool ALIGN_EPI, class Epi, class Sched>
; __device__ __forceinline__ void gemm_phase(LAS unsigned char* lds, const int lda, const int ldb, const int K, const Sched& S, const Epi& E, const size_t kstepA = (size_t)(BK * 2), const size_t kstepB = (size_t)(BK * 2)) {
;     ...
;             const char* a1 = cA + (size_t)(t + 1) * kstepA;
;             const char* a2 = last ? nA : cA + (size_t)(t + 2) * kstepA; const char* b2 = last ? nB : cB + (size_t)(t + 2) * kstep;
;             const char* a3 = a2 + kstepA; const char* b3 = b2 + kstep;
;             PG8_LDB(B0, 0, 0); PG8_LDB(B1, 0, 1); PG8_SCHED; PG8_LDA(At, 0, 0); PG8_STAGE(PG8_SA(1, 1), a1 + hstepA, voffA);
;             PG8_WAIT_V(8); PG8_WAIT_L(0); PG8_BAR; PG8_MMA(0, 0, At, B0); PG8_MMA(0, 1, At, B1); PG8_BAR; PG8_SCHED;
;             PG8_LDA(At, 0, 1); PG8_STAGE(PG8_SB(0, 0), b2, voffB); PG8_STAGE(PG8_SB(0, 1), b2 + hstepB, voffB); PG8_STAGE(PG8_SA(0, 0), a2, voffA);
.LBB0_726:
	ds_read_b128 v[88:91], v219
	ds_read_b128 v[92:95], v219 offset:1024
	ds_read_b128 v[112:115], v219 offset:2048
	ds_read_b128 v[116:119], v219 offset:3072
	ds_read_b128 v[144:147], v220
	ds_read_b128 v[148:151], v220 offset:1024
	ds_read_b128 v[152:155], v220 offset:2048
	ds_read_b128 v[156:159], v220 offset:3072
	s_add_u32 s14, s12, 0x1fc000
	s_addc_u32 s15, s13, 0
	s_cmp_eq_u32 s67, 28
	s_cselect_b32 s20, s0, s14
	s_cselect_b32 s21, s1, s15
	s_cselect_b32 s16, s6, s22
	s_cselect_b32 s17, s7, s23
	s_add_u32 s14, s20, 0x200000
	s_addc_u32 s15, s21, 0
	v_lshl_add_u64 v[212:213], s[12:13], 0, v[178:179]
	s_add_i32 m0, s19, 0xc000
	ds_read_b128 v[160:163], v221
	ds_read_b128 v[164:167], v221 offset:1024
	ds_read_b128 v[188:191], v221 offset:2048
	ds_read_b128 v[192:195], v221 offset:3072
	ds_read_b128 v[196:199], v221 offset:4096
	ds_read_b128 v[200:203], v221 offset:5120
	ds_read_b128 v[204:207], v221 offset:6144
	ds_read_b128 v[208:211], v221 offset:7168
	global_load_lds_dwordx4 v[212:213], off
	v_lshl_add_u64 v[212:213], s[12:13], 0, v[180:181]
	s_add_i32 m0, s19, 0xe000
	s_nop 0
	global_load_lds_dwordx4 v[212:213], off
	s_waitcnt vmcnt(8)
	s_waitcnt lgkmcnt(0)
	s_barrier
	s_setprio 1
	s_waitcnt lgkmcnt(0)
	v_mfma_f32_16x16x32_bf16 v[140:143], v[88:91], v[160:163], v[140:143]
	v_mfma_f32_16x16x32_bf16 v[140:143], v[92:95], v[164:167], v[140:143]
	v_mfma_f32_16x16x32_bf16 v[136:139], v[112:115], v[160:163], v[136:139]
	v_mfma_f32_16x16x32_bf16 v[136:139], v[116:119], v[164:167], v[136:139]
	v_mfma_f32_16x16x32_bf16 v[124:127], v[88:91], v[188:191], v[124:127]
	v_mfma_f32_16x16x32_bf16 v[124:127], v[92:95], v[192:195], v[124:127]
	v_mfma_f32_16x16x32_bf16 v[120:123], v[112:115], v[188:191], v[120:123]
	v_mfma_f32_16x16x32_bf16 v[120:123], v[116:119], v[192:195], v[120:123]
	v_mfma_f32_16x16x32_bf16 v[100:103], v[88:91], v[196:199], v[100:103]
	v_mfma_f32_16x16x32_bf16 v[100:103], v[92:95], v[200:203], v[100:103]
	v_mfma_f32_16x16x32_bf16 v[96:99], v[112:115], v[196:199], v[96:99]
	v_mfma_f32_16x16x32_bf16 v[96:99], v[116:119], v[200:203], v[96:99]
	v_mfma_f32_16x16x32_bf16 v[76:79], v[88:91], v[204:207], v[76:79]
	v_mfma_f32_16x16x32_bf16 v[76:79], v[92:95], v[208:211], v[76:79]
	v_mfma_f32_16x16x32_bf16 v[72:75], v[112:115], v[204:207], v[72:75]
	v_mfma_f32_16x16x32_bf16 v[72:75], v[116:119], v[208:211], v[72:75]
	s_setprio 0
	s_setprio 1
	v_mfma_f32_16x16x32_bf16 v[132:135], v[144:147], v[160:163], v[132:135]
	v_mfma_f32_16x16x32_bf16 v[132:135], v[148:151], v[164:167], v[132:135]
	v_mfma_f32_16x16x32_bf16 v[128:131], v[152:155], v[160:163], v[128:131]
	v_mfma_f32_16x16x32_bf16 v[128:131], v[156:159], v[164:167], v[128:131]
	v_mfma_f32_16x16x32_bf16 v[108:111], v[144:147], v[188:191], v[108:111]
	v_mfma_f32_16x16x32_bf16 v[108:111], v[148:151], v[192:195], v[108:111]
	v_mfma_f32_16x16x32_bf16 v[104:107], v[152:155], v[188:191], v[104:107]
	v_mfma_f32_16x16x32_bf16 v[104:107], v[156:159], v[192:195], v[104:107]
	v_mfma_f32_16x16x32_bf16 v[84:87], v[144:147], v[196:199], v[84:87]
	v_mfma_f32_16x16x32_bf16 v[84:87], v[148:151], v[200:203], v[84:87]
	v_mfma_f32_16x16x32_bf16 v[80:83], v[152:155], v[196:199], v[80:83]
	v_mfma_f32_16x16x32_bf16 v[80:83], v[156:159], v[200:203], v[80:83]
	v_mfma_f32_16x16x32_bf16 v[68:71], v[144:147], v[204:207], v[68:71]
	v_mfma_f32_16x16x32_bf16 v[68:71], v[148:151], v[208:211], v[68:71]
	v_mfma_f32_16x16x32_bf16 v[64:67], v[152:155], v[204:207], v[64:67]
	v_mfma_f32_16x16x32_bf16 v[64:67], v[156:159], v[208:211], v[64:67]
	s_setprio 0
	s_barrier
	s_add_i32 s69, s65, s18
	v_lshl_add_u64 v[212:213], s[16:17], 0, v[170:171]
	s_mov_b32 m0, s69
	ds_read_b128 v[160:163], v221 offset:16384
	ds_read_b128 v[164:167], v221 offset:17408
	ds_read_b128 v[188:191], v221 offset:18432
	ds_read_b128 v[192:195], v221 offset:19456
	ds_read_b128 v[196:199], v221 offset:20480
	ds_read_b128 v[200:203], v221 offset:21504
	ds_read_b128 v[204:207], v221 offset:22528
	ds_read_b128 v[208:211], v221 offset:23552
	global_load_lds_dwordx4 v[212:213], off
	s_add_i32 m0, s69, 0x2000
	s_add_u32 s78, s16, 0x4000
	v_lshl_add_u64 v[212:213], s[16:17], 0, v[174:175]
	s_addc_u32 s79, s17, 0
	s_add_i32 s69, s74, s18
	global_load_lds_dwordx4 v[212:213], off
	v_lshl_add_u64 v[212:213], s[78:79], 0, v[170:171]
	s_mov_b32 m0, s69
	s_nop 0
	global_load_lds_dwordx4 v[212:213], off
	v_lshl_add_u64 v[212:213], s[78:79], 0, v[174:175]
	s_add_i32 m0, s69, 0x2000
	s_nop 0
	global_load_lds_dwordx4 v[212:213], off
	v_lshl_add_u64 v[212:213], s[20:21], 0, v[168:169]
	s_mov_b32 m0, s19
	s_nop 0
	global_load_lds_dwordx4 v[212:213], off
	v_lshl_add_u64 v[212:213], s[20:21], 0, v[172:173]
	s_mov_b32 m0, s30
	s_nop 0
	global_load_lds_dwordx4 v[212:213], off
	s_waitcnt vmcnt(8)
	s_waitcnt lgkmcnt(0)
	s_barrier
; #define PG8_STAGE(bufoff, gbase, voff) do { _Pragma("unroll") for (int _i = 0; _i < 2; ++_i) \
;         __builtin_amdgcn_global_load_lds((const unsigned*)((const char*)(gbase) + (voff)[_i]), (LAS unsigned*)(lds + (bufoff) + ldsw + _i * 8192), 16, 0, 0); } while (0)
; #define PG8_LDA(dst, b, h) do { _Pragma("unroll") for (int m = 0; m < 4; ++m) _Pragma("unroll") for (int k = 0; k < 2; ++k) dst[m][k] = *(const LAS bf16x8*)(lds + PG8_SA(b, h) + aoff + m * 2048 + k * 1024); } while (0)
; #define PG8_LDB(dst, b, h) do { _Pragma("unroll") for (int n = 0; n < 2; ++n) _Pragma("unroll") for (int k = 0; k < 2; ++k) dst[n][k] = *(const LAS bf16x8*)(lds + PG8_SB(b, h) + boff + n * 2048 + k * 1024); } while (0)
; #define PG8_MMA(ai, bj, At, Bt) do { __builtin_amdgcn_s_setprio(1); _Pragma("unroll") for (int m = 0; m < 4; ++m) _Pragma("unroll") for (int n = 0; n < 2; ++n) _Pragma("unroll") for (int k = 0; k < 2; ++k) \
;         acc[ai][bj][m][n] = __builtin_amdgcn_mfma_f32_16x16x32_bf16(Bt[n][k], At[m][k], acc[ai][bj][m][n], 0, 0, 0); __builtin_amdgcn_s_setprio(0); } while (0)
; #define PG8_WAIT_V(n) asm volatile("s_waitcnt vmcnt(" #n ")" ::: "memory")
; #define PG8_WAIT_L(n) asm volatile("s_waitcnt lgkmcnt(" #n ")" ::: "memory")
; #define PG8_BAR __builtin_amdgcn_s_barrier()
; #define PG8_SCHED __builtin_amdgcn_sched_barrier(0)
; template <bool ALIGN_EPI, class Epi, class Sched>
; __device__ __forceinline__ void gemm_phase(LAS unsigned char* lds, const int lda, const int ldb, const int K, const Sched& S, const Epi& E, const size_t kstepA = (size_t)(BK * 2), const size_t kstepB = (size_t)(BK * 2)) {
;     ...
;             PG8_WAIT_V(8); PG8_WAIT_L(0); PG8_BAR; PG8_MMA(1, 0, At, B0); PG8_MMA(1, 1, At, B1); PG8_BAR; PG8_SCHED;
;             PG8_LDB(B0, 1, 0); PG8_LDB(B1, 1, 1); PG8_SCHED; PG8_LDA(At, 1, 0); PG8_STAGE(PG8_SA(0, 1), a2 + hstepA, voffA);
;             PG8_WAIT_V(8); PG8_WAIT_L(0); PG8_BAR; PG8_MMA(0, 0, At, B0); PG8_MMA(0, 1, At, B1); PG8_BAR; PG8_SCHED;
	s_setprio 1
	s_waitcnt lgkmcnt(0)
	v_mfma_f32_16x16x32_bf16 v[60:63], v[88:91], v[160:163], v[60:63]
	v_mfma_f32_16x16x32_bf16 v[60:63], v[92:95], v[164:167], v[60:63]
	v_mfma_f32_16x16x32_bf16 v[56:59], v[112:115], v[160:163], v[56:59]
	v_mfma_f32_16x16x32_bf16 v[56:59], v[116:119], v[164:167], v[56:59]
	v_mfma_f32_16x16x32_bf16 v[44:47], v[88:91], v[188:191], v[44:47]
	v_mfma_f32_16x16x32_bf16 v[44:47], v[92:95], v[192:195], v[44:47]
	v_mfma_f32_16x16x32_bf16 v[40:43], v[112:115], v[188:191], v[40:43]
	v_mfma_f32_16x16x32_bf16 v[40:43], v[116:119], v[192:195], v[40:43]
	v_mfma_f32_16x16x32_bf16 v[28:31], v[88:91], v[196:199], v[28:31]
	v_mfma_f32_16x16x32_bf16 v[28:31], v[92:95], v[200:203], v[28:31]
	v_mfma_f32_16x16x32_bf16 v[24:27], v[112:115], v[196:199], v[24:27]
	v_mfma_f32_16x16x32_bf16 v[24:27], v[116:119], v[200:203], v[24:27]
	v_mfma_f32_16x16x32_bf16 v[12:15], v[88:91], v[204:207], v[12:15]
	v_mfma_f32_16x16x32_bf16 v[12:15], v[92:95], v[208:211], v[12:15]
	v_mfma_f32_16x16x32_bf16 v[8:11], v[112:115], v[204:207], v[8:11]
	v_mfma_f32_16x16x32_bf16 v[8:11], v[116:119], v[208:211], v[8:11]
	s_setprio 0
	s_setprio 1
	v_mfma_f32_16x16x32_bf16 v[52:55], v[144:147], v[160:163], v[52:55]
	v_mfma_f32_16x16x32_bf16 v[52:55], v[148:151], v[164:167], v[52:55]
	v_mfma_f32_16x16x32_bf16 v[48:51], v[152:155], v[160:163], v[48:51]
	v_mfma_f32_16x16x32_bf16 v[48:51], v[156:159], v[164:167], v[48:51]
	v_mfma_f32_16x16x32_bf16 v[36:39], v[144:147], v[188:191], v[36:39]
	v_mfma_f32_16x16x32_bf16 v[36:39], v[148:151], v[192:195], v[36:39]
	v_mfma_f32_16x16x32_bf16 v[32:35], v[152:155], v[188:191], v[32:35]
	v_mfma_f32_16x16x32_bf16 v[32:35], v[156:159], v[192:195], v[32:35]
	v_mfma_f32_16x16x32_bf16 v[20:23], v[144:147], v[196:199], v[20:23]
	v_mfma_f32_16x16x32_bf16 v[20:23], v[148:151], v[200:203], v[20:23]
	v_mfma_f32_16x16x32_bf16 v[16:19], v[152:155], v[196:199], v[16:19]
	v_mfma_f32_16x16x32_bf16 v[16:19], v[156:159], v[200:203], v[16:19]
	v_mfma_f32_16x16x32_bf16 v[4:7], v[144:147], v[204:207], v[4:7]
	v_mfma_f32_16x16x32_bf16 v[4:7], v[148:151], v[208:211], v[4:7]
	v_mfma_f32_16x16x32_bf16 v[0:3], v[152:155], v[204:207], v[0:3]
	v_mfma_f32_16x16x32_bf16 v[0:3], v[156:159], v[208:211], v[0:3]
	s_setprio 0
	s_barrier
	s_add_i32 s69, 0, 0x18000
	s_add_i32 s77, 0, 0x1c000
	v_add_u32_e32 v116, s69, v218
	v_add_u32_e32 v156, s77, v218
	ds_read_b128 v[88:91], v116
	ds_read_b128 v[92:95], v116 offset:1024
	ds_read_b128 v[112:115], v116 offset:2048
	ds_read_b128 v[116:119], v116 offset:3072
	ds_read_b128 v[144:147], v156
	ds_read_b128 v[148:151], v156 offset:1024
	ds_read_b128 v[152:155], v156 offset:2048
	ds_read_b128 v[156:159], v156 offset:3072
	s_add_u32 s20, s20, 0x4000
	s_addc_u32 s21, s21, 0
	s_mov_b32 m0, s33
	v_lshl_add_u64 v[212:213], s[20:21], 0, v[168:169]
	ds_read_b128 v[160:163], v221 offset:32768
	ds_read_b128 v[164:167], v221 offset:33792
	ds_read_b128 v[188:191], v221 offset:34816
	ds_read_b128 v[192:195], v221 offset:35840
	ds_read_b128 v[196:199], v221 offset:36864
	ds_read_b128 v[200:203], v221 offset:37888
	ds_read_b128 v[204:207], v221 offset:38912
	ds_read_b128 v[208:211], v221 offset:39936
	global_load_lds_dwordx4 v[212:213], off
	v_lshl_add_u64 v[212:213], s[20:21], 0, v[172:173]
	s_mov_b32 m0, s42
	s_nop 0
	global_load_lds_dwordx4 v[212:213], off
	s_waitcnt vmcnt(8)
	s_waitcnt lgkmcnt(0)
	s_barrier
	s_setprio 1
	s_waitcnt lgkmcnt(0)
	v_mfma_f32_16x16x32_bf16 v[140:143], v[88:91], v[160:163], v[140:143]
	v_mfma_f32_16x16x32_bf16 v[140:143], v[92:95], v[164:167], v[140:143]
	v_mfma_f32_16x16x32_bf16 v[136:139], v[112:115], v[160:163], v[136:139]
	v_mfma_f32_16x16x32_bf16 v[136:139], v[116:119], v[164:167], v[136:139]
	v_mfma_f32_16x16x32_bf16 v[124:127], v[88:91], v[188:191], v[124:127]
	v_mfma_f32_16x16x32_bf16 v[124:127], v[92:95], v[192:195], v[124:127]
	v_mfma_f32_16x16x32_bf16 v[120:123], v[112:115], v[188:191], v[120:123]
	v_mfma_f32_16x16x32_bf16 v[120:123], v[116:119], v[192:195], v[120:123]
	v_mfma_f32_16x16x32_bf16 v[100:103], v[88:91], v[196:199], v[100:103]
	v_mfma_f32_16x16x32_bf16 v[100:103], v[92:95], v[200:203], v[100:103]
	v_mfma_f32_16x16x32_bf16 v[96:99], v[112:115], v[196:199], v[96:99]
	v_mfma_f32_16x16x32_bf16 v[96:99], v[116:119], v[200:203], v[96:99]
	v_mfma_f32_16x16x32_bf16 v[76:79], v[88:91], v[204:207], v[76:79]
	v_mfma_f32_16x16x32_bf16 v[76:79], v[92:95], v[208:211], v[76:79]
	v_mfma_f32_16x16x32_bf16 v[72:75], v[112:115], v[204:207], v[72:75]
	v_mfma_f32_16x16x32_bf16 v[72:75], v[116:119], v[208:211], v[72:75]
	s_setprio 0
	s_setprio 1
	v_mfma_f32_16x16x32_bf16 v[132:135], v[144:147], v[160:163], v[132:135]
	v_mfma_f32_16x16x32_bf16 v[132:135], v[148:151], v[164:167], v[132:135]
	v_mfma_f32_16x16x32_bf16 v[128:131], v[152:155], v[160:163], v[128:131]
	v_mfma_f32_16x16x32_bf16 v[128:131], v[156:159], v[164:167], v[128:131]
	v_mfma_f32_16x16x32_bf16 v[108:111], v[144:147], v[188:191], v[108:111]
	v_mfma_f32_16x16x32_bf16 v[108:111], v[148:151], v[192:195], v[108:111]
	v_mfma_f32_16x16x32_bf16 v[104:107], v[152:155], v[188:191], v[104:107]
	v_mfma_f32_16x16x32_bf16 v[104:107], v[156:159], v[192:195], v[104:107]
	v_mfma_f32_16x16x32_bf16 v[84:87], v[144:147], v[196:199], v[84:87]
	v_mfma_f32_16x16x32_bf16 v[84:87], v[148:151], v[200:203], v[84:87]
	v_mfma_f32_16x16x32_bf16 v[80:83], v[152:155], v[196:199], v[80:83]
	v_mfma_f32_16x16x32_bf16 v[80:83], v[156:159], v[200:203], v[80:83]
	v_mfma_f32_16x16x32_bf16 v[68:71], v[144:147], v[204:207], v[68:71]
	v_mfma_f32_16x16x32_bf16 v[68:71], v[148:151], v[208:211], v[68:71]
	v_mfma_f32_16x16x32_bf16 v[64:67], v[152:155], v[204:207], v[64:67]
	v_mfma_f32_16x16x32_bf16 v[64:67], v[156:159], v[208:211], v[64:67]
	s_setprio 0
	s_barrier
; #define PG8_STAGE(bufoff, gbase, voff) do { _Pragma("unroll") for (int _i = 0; _i < 2; ++_i) \
;         __builtin_amdgcn_global_load_lds((const unsigned*)((const char*)(gbase) + (voff)[_i]), (LAS unsigned*)(lds + (bufoff) + ldsw + _i * 8192), 16, 0, 0); } while (0)
; #define PG8_LDA(dst, b, h) do { _Pragma("unroll") for (int m = 0; m < 4; ++m) _Pragma("unroll") for (int k = 0; k < 2; ++k) dst[m][k] = *(const LAS bf16x8*)(lds + PG8_SA(b, h) + aoff + m * 2048 + k * 1024); } while (0)
; #define PG8_MMA(ai, bj, At, Bt) do { __builtin_amdgcn_s_setprio(1); _Pragma("unroll") for (int m = 0; m < 4; ++m) _Pragma("unroll") for (int n = 0; n < 2; ++n) _Pragma("unroll") for (int k = 0; k < 2; ++k) \
;         acc[ai][bj][m][n] = __builtin_amdgcn_mfma_f32_16x16x32_bf16(Bt[n][k], At[m][k], acc[ai][bj][m][n], 0, 0, 0); __builtin_amdgcn_s_setprio(0); } while (0)
; #define PG8_WAIT_V(n) asm volatile("s_waitcnt vmcnt(" #n ")" ::: "memory")
; #define PG8_WAIT_L(n) asm volatile("s_waitcnt lgkmcnt(" #n ")" ::: "memory")
; #define PG8_BAR __builtin_amdgcn_s_barrier()
; #define PG8_SCHED __builtin_amdgcn_sched_barrier(0)
; template <bool ALIGN_EPI, class Epi, class Sched>
; __device__ __forceinline__ void gemm_phase(LAS unsigned char* lds, const int lda, const int ldb, const int K, const Sched& S, const Epi& E, const size_t kstepA = (size_t)(BK * 2), const size_t kstepB = (size_t)(BK * 2)) {
;     ...
;             PG8_LDA(At, 1, 1); PG8_STAGE(PG8_SB(1, 0), b3, voffB); PG8_STAGE(PG8_SB(1, 1), b3 + hstepB, voffB); PG8_STAGE(PG8_SA(1, 0), a3, voffA);
;             PG8_WAIT_V(8); PG8_WAIT_L(0); PG8_BAR; PG8_MMA(1, 0, At, B0); PG8_MMA(1, 1, At, B1); PG8_BAR; PG8_SCHED;
;         }
;         if constexpr (ALIGN_EPI) { if (wr == 0) PG8_BAR; }
	s_add_u32 s20, s16, 0x40000
	s_addc_u32 s21, s17, 0
	s_add_i32 s69, s69, s18
	v_lshl_add_u64 v[212:213], s[20:21], 0, v[170:171]
	s_mov_b32 m0, s69
	ds_read_b128 v[160:163], v221 offset:49152
	ds_read_b128 v[164:167], v221 offset:50176
	ds_read_b128 v[188:191], v221 offset:51200
	ds_read_b128 v[192:195], v221 offset:52224
	ds_read_b128 v[196:199], v221 offset:53248
	ds_read_b128 v[200:203], v221 offset:54272
	ds_read_b128 v[204:207], v221 offset:55296
	ds_read_b128 v[208:211], v221 offset:56320
	global_load_lds_dwordx4 v[212:213], off
	s_add_i32 m0, s69, 0x2000
	s_add_u32 s16, s16, 0x44000
	v_lshl_add_u64 v[212:213], s[20:21], 0, v[174:175]
	s_addc_u32 s17, s17, 0
	s_add_i32 s20, s77, s18
	global_load_lds_dwordx4 v[212:213], off
	v_lshl_add_u64 v[212:213], s[16:17], 0, v[170:171]
	s_mov_b32 m0, s20
	s_nop 0
	global_load_lds_dwordx4 v[212:213], off
	v_lshl_add_u64 v[212:213], s[16:17], 0, v[174:175]
	s_add_i32 m0, s20, 0x2000
	s_nop 0
	global_load_lds_dwordx4 v[212:213], off
	v_lshl_add_u64 v[212:213], s[14:15], 0, v[168:169]
	s_mov_b32 m0, s51
	s_nop 0
	global_load_lds_dwordx4 v[212:213], off
	v_lshl_add_u64 v[212:213], s[14:15], 0, v[172:173]
	s_mov_b32 m0, s64
	s_nop 0
	global_load_lds_dwordx4 v[212:213], off
	s_waitcnt vmcnt(8)
	s_waitcnt lgkmcnt(0)
	s_barrier
	s_setprio 1
	s_waitcnt lgkmcnt(0)
	v_mfma_f32_16x16x32_bf16 v[60:63], v[88:91], v[160:163], v[60:63]
	v_mfma_f32_16x16x32_bf16 v[60:63], v[92:95], v[164:167], v[60:63]
	v_mfma_f32_16x16x32_bf16 v[56:59], v[112:115], v[160:163], v[56:59]
	v_mfma_f32_16x16x32_bf16 v[56:59], v[116:119], v[164:167], v[56:59]
	v_mfma_f32_16x16x32_bf16 v[44:47], v[88:91], v[188:191], v[44:47]
	v_mfma_f32_16x16x32_bf16 v[44:47], v[92:95], v[192:195], v[44:47]
	v_mfma_f32_16x16x32_bf16 v[40:43], v[112:115], v[188:191], v[40:43]
	v_mfma_f32_16x16x32_bf16 v[40:43], v[116:119], v[192:195], v[40:43]
	v_mfma_f32_16x16x32_bf16 v[28:31], v[88:91], v[196:199], v[28:31]
	v_mfma_f32_16x16x32_bf16 v[28:31], v[92:95], v[200:203], v[28:31]
	v_mfma_f32_16x16x32_bf16 v[24:27], v[112:115], v[196:199], v[24:27]
	v_mfma_f32_16x16x32_bf16 v[24:27], v[116:119], v[200:203], v[24:27]
	v_mfma_f32_16x16x32_bf16 v[12:15], v[88:91], v[204:207], v[12:15]
	v_mfma_f32_16x16x32_bf16 v[12:15], v[92:95], v[208:211], v[12:15]
	v_mfma_f32_16x16x32_bf16 v[8:11], v[112:115], v[204:207], v[8:11]
	v_mfma_f32_16x16x32_bf16 v[8:11], v[116:119], v[208:211], v[8:11]
	s_setprio 0
	s_setprio 1
	v_mfma_f32_16x16x32_bf16 v[52:55], v[144:147], v[160:163], v[52:55]
	v_mfma_f32_16x16x32_bf16 v[52:55], v[148:151], v[164:167], v[52:55]
	v_mfma_f32_16x16x32_bf16 v[48:51], v[152:155], v[160:163], v[48:51]
	v_mfma_f32_16x16x32_bf16 v[48:51], v[156:159], v[164:167], v[48:51]
	v_mfma_f32_16x16x32_bf16 v[36:39], v[144:147], v[188:191], v[36:39]
	v_mfma_f32_16x16x32_bf16 v[36:39], v[148:151], v[192:195], v[36:39]
	v_mfma_f32_16x16x32_bf16 v[32:35], v[152:155], v[188:191], v[32:35]
	v_mfma_f32_16x16x32_bf16 v[32:35], v[156:159], v[192:195], v[32:35]
	v_mfma_f32_16x16x32_bf16 v[20:23], v[144:147], v[196:199], v[20:23]
	v_mfma_f32_16x16x32_bf16 v[20:23], v[148:151], v[200:203], v[20:23]
	v_mfma_f32_16x16x32_bf16 v[16:19], v[152:155], v[196:199], v[16:19]
	v_mfma_f32_16x16x32_bf16 v[16:19], v[156:159], v[200:203], v[16:19]
	v_mfma_f32_16x16x32_bf16 v[4:7], v[144:147], v[204:207], v[4:7]
	v_mfma_f32_16x16x32_bf16 v[4:7], v[148:151], v[208:211], v[4:7]
	v_mfma_f32_16x16x32_bf16 v[0:3], v[152:155], v[204:207], v[0:3]
	v_mfma_f32_16x16x32_bf16 v[0:3], v[156:159], v[208:211], v[0:3]
	s_setprio 0
	s_barrier
	s_add_i32 s67, s67, 2
	s_add_u32 s22, s22, 0x80000
	s_addc_u32 s23, s23, 0
	s_add_u32 s12, s12, 0x400000
	s_addc_u32 s13, s13, 0
	s_cmp_gt_u32 s67, 29
	s_cbranch_scc0 .LBB0_726
	s_and_b64 vcc, exec, s[56:57]
	s_cbranch_vccz .LBB0_729
	s_barrier

; #define PG8_STAGE(bufoff, gbase, voff) do { _Pragma("unroll") for (int _i = 0; _i < 2; ++_i) \
;         __builtin_amdgcn_global_load_lds((const unsigned*)((const char*)(gbase) + (voff)[_i]), (LAS unsigned*)(lds + (bufoff) + ldsw + _i * 8192), 16, 0, 0); } while (0)
; #define PG8_LDA(dst, b, h) do { _Pragma("unroll") for (int m = 0; m < 4; ++m) _Pragma("unroll") for (int k = 0; k < 2; ++k) dst[m][k] = *(const LAS bf16x8*)(lds + PG8_SA(b, h) + aoff + m * 2048 + k * 1024); } while (0)
; #define PG8_LDB(dst, b, h) do { _Pragma("unroll") for (int n = 0; n < 2; ++n) _Pragma("unroll") for (int k = 0; k < 2; ++k) dst[n][k] = *(const LAS bf16x8*)(lds + PG8_SB(b, h) + boff + n * 2048 + k * 1024); } while (0)
; #define PG8_MMA(ai, bj, At, Bt) do { __builtin_amdgcn_s_setprio(1); _Pragma("unroll") for (int m = 0; m < 4; ++m) _Pragma("unroll") for (int n = 0; n < 2; ++n) _Pragma("unroll") for (int k = 0; k < 2; ++k) \
;         acc[ai][bj][m][n] = __builtin_amdgcn_mfma_f32_16x16x32_bf16(Bt[n][k], At[m][k], acc[ai][bj][m][n], 0, 0, 0); __builtin_amdgcn_s_setprio(0); } while (0)
; #define PG8_WAIT_V(n) asm volatile("s_waitcnt vmcnt(" #n ")" ::: "memory")
; #define PG8_WAIT_L(n) asm volatile("s_waitcnt lgkmcnt(" #n ")" ::: "memory")
; #define PG8_BAR __builtin_amdgcn_s_barrier()
; #define PG8_SCHED __builtin_amdgcn_sched_barrier(0)
; template <bool ALIGN_EPI, class Epi, class Sched>
; __device__ __forceinline__ void gemm_phase(LAS unsigned char* lds, const int lda, const int ldb, const int K, const Sched& S, const Epi& E, const size_t kstepA = (size_t)(BK * 2), const size_t kstepB = (size_t)(BK * 2)) {
;     ...
;             const char* a1 = cA + (size_t)(t + 1) * kstepA;
;             const char* a2 = last ? nA : cA + (size_t)(t + 2) * kstepA; const char* b2 = last ? nB : cB + (size_t)(t + 2) * kstep;
;             const char* a3 = a2 + kstepA; const char* b3 = b2 + kstep;
;             PG8_LDB(B0, 0, 0); PG8_LDB(B1, 0, 1); PG8_SCHED; PG8_LDA(At, 0, 0); PG8_STAGE(PG8_SA(1, 1), a1 + hstepA, voffA);
;             PG8_WAIT_V(8); PG8_WAIT_L(0); PG8_BAR; PG8_MMA(0, 0, At, B0); PG8_MMA(0, 1, At, B1); PG8_BAR; PG8_SCHED;
;             PG8_LDA(At, 0, 1); PG8_STAGE(PG8_SB(0, 0), b2, voffB); PG8_STAGE(PG8_SB(0, 1), b2 + hstepB, voffB); PG8_STAGE(PG8_SA(0, 0), a2, voffA);
.LBB0_813:
	ds_read_b128 v[146:149], v140
	ds_read_b128 v[150:153], v140 offset:1024
	ds_read_b128 v[158:161], v140 offset:2048
	ds_read_b128 v[162:165], v140 offset:3072
	ds_read_b128 v[166:169], v141
	ds_read_b128 v[170:173], v141 offset:1024
	ds_read_b128 v[174:177], v141 offset:2048
	ds_read_b128 v[178:181], v141 offset:3072
	s_add_u32 s14, s8, s12
	s_addc_u32 s15, s9, s13
	s_cmp_eq_u32 s49, 28
	s_cselect_b32 s20, s8, s14
	s_cselect_b32 s21, s9, s15
	s_cselect_b32 s16, s10, s45
	s_cselect_b32 s17, s11, s48
	s_add_u32 s14, s20, 0x200000
	s_addc_u32 s15, s21, 0
	s_mov_b32 m0, s50
	v_lshl_add_u64 v[182:183], s[8:9], 0, v[136:137]
	ds_read_b128 v[186:189], v142
	ds_read_b128 v[190:193], v142 offset:1024
	ds_read_b128 v[194:197], v142 offset:2048
	ds_read_b128 v[198:201], v142 offset:3072
	ds_read_b128 v[202:205], v142 offset:4096
	ds_read_b128 v[206:209], v142 offset:5120
	ds_read_b128 v[210:213], v142 offset:6144
	ds_read_b128 v[214:217], v142 offset:7168
	global_load_lds_dwordx4 v[182:183], off
	v_lshl_add_u64 v[182:183], s[8:9], 0, v[138:139]
	s_mov_b32 m0, s51
	s_nop 0
	global_load_lds_dwordx4 v[182:183], off
	s_waitcnt vmcnt(8)
	s_waitcnt lgkmcnt(0)
	s_barrier
	s_setprio 1
	s_waitcnt lgkmcnt(0)
	v_mfma_f32_16x16x32_bf16 v[124:127], v[146:149], v[186:189], v[124:127]
	v_mfma_f32_16x16x32_bf16 v[124:127], v[150:153], v[190:193], v[124:127]
	v_mfma_f32_16x16x32_bf16 v[120:123], v[158:161], v[186:189], v[120:123]
	v_mfma_f32_16x16x32_bf16 v[120:123], v[162:165], v[190:193], v[120:123]
	v_mfma_f32_16x16x32_bf16 v[108:111], v[146:149], v[194:197], v[108:111]
	v_mfma_f32_16x16x32_bf16 v[108:111], v[150:153], v[198:201], v[108:111]
	v_mfma_f32_16x16x32_bf16 v[104:107], v[158:161], v[194:197], v[104:107]
	v_mfma_f32_16x16x32_bf16 v[104:107], v[162:165], v[198:201], v[104:107]
	v_mfma_f32_16x16x32_bf16 v[92:95], v[146:149], v[202:205], v[92:95]
	v_mfma_f32_16x16x32_bf16 v[92:95], v[150:153], v[206:209], v[92:95]
	v_mfma_f32_16x16x32_bf16 v[88:91], v[158:161], v[202:205], v[88:91]
	v_mfma_f32_16x16x32_bf16 v[88:91], v[162:165], v[206:209], v[88:91]
	v_mfma_f32_16x16x32_bf16 v[76:79], v[146:149], v[210:213], v[76:79]
	v_mfma_f32_16x16x32_bf16 v[76:79], v[150:153], v[214:217], v[76:79]
	v_mfma_f32_16x16x32_bf16 v[72:75], v[158:161], v[210:213], v[72:75]
	v_mfma_f32_16x16x32_bf16 v[72:75], v[162:165], v[214:217], v[72:75]
	s_setprio 0
	s_setprio 1
	v_mfma_f32_16x16x32_bf16 v[116:119], v[166:169], v[186:189], v[116:119]
	v_mfma_f32_16x16x32_bf16 v[116:119], v[170:173], v[190:193], v[116:119]
	v_mfma_f32_16x16x32_bf16 v[112:115], v[174:177], v[186:189], v[112:115]
	v_mfma_f32_16x16x32_bf16 v[112:115], v[178:181], v[190:193], v[112:115]
	v_mfma_f32_16x16x32_bf16 v[100:103], v[166:169], v[194:197], v[100:103]
	v_mfma_f32_16x16x32_bf16 v[100:103], v[170:173], v[198:201], v[100:103]
	v_mfma_f32_16x16x32_bf16 v[96:99], v[174:177], v[194:197], v[96:99]
	v_mfma_f32_16x16x32_bf16 v[96:99], v[178:181], v[198:201], v[96:99]
	v_mfma_f32_16x16x32_bf16 v[84:87], v[166:169], v[202:205], v[84:87]
	v_mfma_f32_16x16x32_bf16 v[84:87], v[170:173], v[206:209], v[84:87]
	v_mfma_f32_16x16x32_bf16 v[80:83], v[174:177], v[202:205], v[80:83]
	v_mfma_f32_16x16x32_bf16 v[80:83], v[178:181], v[206:209], v[80:83]
	v_mfma_f32_16x16x32_bf16 v[68:71], v[166:169], v[210:213], v[68:71]
	v_mfma_f32_16x16x32_bf16 v[68:71], v[170:173], v[214:217], v[68:71]
	v_mfma_f32_16x16x32_bf16 v[64:67], v[174:177], v[210:213], v[64:67]
	v_mfma_f32_16x16x32_bf16 v[64:67], v[178:181], v[214:217], v[64:67]
	s_setprio 0
	s_barrier
	s_mov_b32 m0, s52
	v_lshl_add_u64 v[182:183], s[16:17], 0, v[130:131]
	s_add_u32 s60, s16, 0x4000
	ds_read_b128 v[186:189], v142 offset:16384
	ds_read_b128 v[190:193], v142 offset:17408
	ds_read_b128 v[194:197], v142 offset:18432
	ds_read_b128 v[198:201], v142 offset:19456
	ds_read_b128 v[202:205], v142 offset:20480
	ds_read_b128 v[206:209], v142 offset:21504
	ds_read_b128 v[210:213], v142 offset:22528
	ds_read_b128 v[214:217], v142 offset:23552
	global_load_lds_dwordx4 v[182:183], off
	v_lshl_add_u64 v[182:183], s[16:17], 0, v[134:135]
	s_mov_b32 m0, s53
	s_addc_u32 s61, s17, 0
	global_load_lds_dwordx4 v[182:183], off
	v_lshl_add_u64 v[182:183], s[60:61], 0, v[130:131]
	s_mov_b32 m0, s54
	s_nop 0
	global_load_lds_dwordx4 v[182:183], off
	v_lshl_add_u64 v[182:183], s[60:61], 0, v[134:135]
	s_mov_b32 m0, s55
	s_nop 0
	global_load_lds_dwordx4 v[182:183], off
	v_lshl_add_u64 v[182:183], s[20:21], 0, v[128:129]
	s_mov_b32 m0, s1
	s_nop 0
	global_load_lds_dwordx4 v[182:183], off
	v_lshl_add_u64 v[182:183], s[20:21], 0, v[132:133]
	s_mov_b32 m0, s40
	s_nop 0
	global_load_lds_dwordx4 v[182:183], off
	s_waitcnt vmcnt(8)
	s_waitcnt lgkmcnt(0)
	s_barrier
; #define PG8_STAGE(bufoff, gbase, voff) do { _Pragma("unroll") for (int _i = 0; _i < 2; ++_i) \
;         __builtin_amdgcn_global_load_lds((const unsigned*)((const char*)(gbase) + (voff)[_i]), (LAS unsigned*)(lds + (bufoff) + ldsw + _i * 8192), 16, 0, 0); } while (0)
; #define PG8_LDA(dst, b, h) do { _Pragma("unroll") for (int m = 0; m < 4; ++m) _Pragma("unroll") for (int k = 0; k < 2; ++k) dst[m][k] = *(const LAS bf16x8*)(lds + PG8_SA(b, h) + aoff + m * 2048 + k * 1024); } while (0)
; #define PG8_LDB(dst, b, h) do { _Pragma("unroll") for (int n = 0; n < 2; ++n) _Pragma("unroll") for (int k = 0; k < 2; ++k) dst[n][k] = *(const LAS bf16x8*)(lds + PG8_SB(b, h) + boff + n * 2048 + k * 1024); } while (0)
; #define PG8_MMA(ai, bj, At, Bt) do { __builtin_amdgcn_s_setprio(1); _Pragma("unroll") for (int m = 0; m < 4; ++m) _Pragma("unroll") for (int n = 0; n < 2; ++n) _Pragma("unroll") for (int k = 0; k < 2; ++k) \
;         acc[ai][bj][m][n] = __builtin_amdgcn_mfma_f32_16x16x32_bf16(Bt[n][k], At[m][k], acc[ai][bj][m][n], 0, 0, 0); __builtin_amdgcn_s_setprio(0); } while (0)
; #define PG8_WAIT_V(n) asm volatile("s_waitcnt vmcnt(" #n ")" ::: "memory")
; #define PG8_WAIT_L(n) asm volatile("s_waitcnt lgkmcnt(" #n ")" ::: "memory")
; #define PG8_BAR __builtin_amdgcn_s_barrier()
; #define PG8_SCHED __builtin_amdgcn_sched_barrier(0)
; template <bool ALIGN_EPI, class Epi, class Sched>
; __device__ __forceinline__ void gemm_phase(LAS unsigned char* lds, const int lda, const int ldb, const int K, const Sched& S, const Epi& E, const size_t kstepA = (size_t)(BK * 2), const size_t kstepB = (size_t)(BK * 2)) {
;     ...
;             PG8_WAIT_V(8); PG8_WAIT_L(0); PG8_BAR; PG8_MMA(1, 0, At, B0); PG8_MMA(1, 1, At, B1); PG8_BAR; PG8_SCHED;
;             PG8_LDB(B0, 1, 0); PG8_LDB(B1, 1, 1); PG8_SCHED; PG8_LDA(At, 1, 0); PG8_STAGE(PG8_SA(0, 1), a2 + hstepA, voffA);
;             PG8_WAIT_V(8); PG8_WAIT_L(0); PG8_BAR; PG8_MMA(0, 0, At, B0); PG8_MMA(0, 1, At, B1); PG8_BAR; PG8_SCHED;
	s_setprio 1
	s_waitcnt lgkmcnt(0)
	v_mfma_f32_16x16x32_bf16 v[60:63], v[146:149], v[186:189], v[60:63]
	v_mfma_f32_16x16x32_bf16 v[60:63], v[150:153], v[190:193], v[60:63]
	v_mfma_f32_16x16x32_bf16 v[56:59], v[158:161], v[186:189], v[56:59]
	v_mfma_f32_16x16x32_bf16 v[56:59], v[162:165], v[190:193], v[56:59]
	v_mfma_f32_16x16x32_bf16 v[44:47], v[146:149], v[194:197], v[44:47]
	v_mfma_f32_16x16x32_bf16 v[44:47], v[150:153], v[198:201], v[44:47]
	v_mfma_f32_16x16x32_bf16 v[40:43], v[158:161], v[194:197], v[40:43]
	v_mfma_f32_16x16x32_bf16 v[40:43], v[162:165], v[198:201], v[40:43]
	v_mfma_f32_16x16x32_bf16 v[28:31], v[146:149], v[202:205], v[28:31]
	v_mfma_f32_16x16x32_bf16 v[28:31], v[150:153], v[206:209], v[28:31]
	v_mfma_f32_16x16x32_bf16 v[24:27], v[158:161], v[202:205], v[24:27]
	v_mfma_f32_16x16x32_bf16 v[24:27], v[162:165], v[206:209], v[24:27]
	v_mfma_f32_16x16x32_bf16 v[12:15], v[146:149], v[210:213], v[12:15]
	v_mfma_f32_16x16x32_bf16 v[12:15], v[150:153], v[214:217], v[12:15]
	v_mfma_f32_16x16x32_bf16 v[8:11], v[158:161], v[210:213], v[8:11]
	v_mfma_f32_16x16x32_bf16 v[8:11], v[162:165], v[214:217], v[8:11]
	s_setprio 0
	s_setprio 1
	v_mfma_f32_16x16x32_bf16 v[52:55], v[166:169], v[186:189], v[52:55]
	v_mfma_f32_16x16x32_bf16 v[52:55], v[170:173], v[190:193], v[52:55]
	v_mfma_f32_16x16x32_bf16 v[48:51], v[174:177], v[186:189], v[48:51]
	v_mfma_f32_16x16x32_bf16 v[48:51], v[178:181], v[190:193], v[48:51]
	v_mfma_f32_16x16x32_bf16 v[36:39], v[166:169], v[194:197], v[36:39]
	v_mfma_f32_16x16x32_bf16 v[36:39], v[170:173], v[198:201], v[36:39]
	v_mfma_f32_16x16x32_bf16 v[32:35], v[174:177], v[194:197], v[32:35]
	v_mfma_f32_16x16x32_bf16 v[32:35], v[178:181], v[198:201], v[32:35]
	v_mfma_f32_16x16x32_bf16 v[20:23], v[166:169], v[202:205], v[20:23]
	v_mfma_f32_16x16x32_bf16 v[20:23], v[170:173], v[206:209], v[20:23]
	v_mfma_f32_16x16x32_bf16 v[16:19], v[174:177], v[202:205], v[16:19]
	v_mfma_f32_16x16x32_bf16 v[16:19], v[178:181], v[206:209], v[16:19]
	v_mfma_f32_16x16x32_bf16 v[4:7], v[166:169], v[210:213], v[4:7]
	v_mfma_f32_16x16x32_bf16 v[4:7], v[170:173], v[214:217], v[4:7]
	v_mfma_f32_16x16x32_bf16 v[0:3], v[174:177], v[210:213], v[0:3]
	v_mfma_f32_16x16x32_bf16 v[0:3], v[178:181], v[214:217], v[0:3]
	s_setprio 0
	s_barrier
	ds_read_b128 v[146:149], v143
	ds_read_b128 v[150:153], v143 offset:1024
	ds_read_b128 v[158:161], v143 offset:2048
	ds_read_b128 v[162:165], v143 offset:3072
	ds_read_b128 v[166:169], v144
	ds_read_b128 v[170:173], v144 offset:1024
	ds_read_b128 v[174:177], v144 offset:2048
	ds_read_b128 v[178:181], v144 offset:3072
	s_add_u32 s20, s20, 0x4000
	s_addc_u32 s21, s21, 0
	s_mov_b32 m0, s41
	v_lshl_add_u64 v[182:183], s[20:21], 0, v[128:129]
	ds_read_b128 v[186:189], v142 offset:32768
	ds_read_b128 v[190:193], v142 offset:33792
	ds_read_b128 v[194:197], v142 offset:34816
	ds_read_b128 v[198:201], v142 offset:35840
	ds_read_b128 v[202:205], v142 offset:36864
	ds_read_b128 v[206:209], v142 offset:37888
	ds_read_b128 v[210:213], v142 offset:38912
	ds_read_b128 v[214:217], v142 offset:39936
	global_load_lds_dwordx4 v[182:183], off
	v_lshl_add_u64 v[182:183], s[20:21], 0, v[132:133]
	s_mov_b32 m0, s42
	s_nop 0
	global_load_lds_dwordx4 v[182:183], off
	s_waitcnt vmcnt(8)
	s_waitcnt lgkmcnt(0)
	s_barrier
	s_setprio 1
	s_waitcnt lgkmcnt(0)
	v_mfma_f32_16x16x32_bf16 v[124:127], v[146:149], v[186:189], v[124:127]
	v_mfma_f32_16x16x32_bf16 v[124:127], v[150:153], v[190:193], v[124:127]
	v_mfma_f32_16x16x32_bf16 v[120:123], v[158:161], v[186:189], v[120:123]
	v_mfma_f32_16x16x32_bf16 v[120:123], v[162:165], v[190:193], v[120:123]
	v_mfma_f32_16x16x32_bf16 v[108:111], v[146:149], v[194:197], v[108:111]
	v_mfma_f32_16x16x32_bf16 v[108:111], v[150:153], v[198:201], v[108:111]
	v_mfma_f32_16x16x32_bf16 v[104:107], v[158:161], v[194:197], v[104:107]
	v_mfma_f32_16x16x32_bf16 v[104:107], v[162:165], v[198:201], v[104:107]
	v_mfma_f32_16x16x32_bf16 v[92:95], v[146:149], v[202:205], v[92:95]
	v_mfma_f32_16x16x32_bf16 v[92:95], v[150:153], v[206:209], v[92:95]
	v_mfma_f32_16x16x32_bf16 v[88:91], v[158:161], v[202:205], v[88:91]
	v_mfma_f32_16x16x32_bf16 v[88:91], v[162:165], v[206:209], v[88:91]
	v_mfma_f32_16x16x32_bf16 v[76:79], v[146:149], v[210:213], v[76:79]
	v_mfma_f32_16x16x32_bf16 v[76:79], v[150:153], v[214:217], v[76:79]
	v_mfma_f32_16x16x32_bf16 v[72:75], v[158:161], v[210:213], v[72:75]
	v_mfma_f32_16x16x32_bf16 v[72:75], v[162:165], v[214:217], v[72:75]
	s_setprio 0
	s_setprio 1
	v_mfma_f32_16x16x32_bf16 v[116:119], v[166:169], v[186:189], v[116:119]
	v_mfma_f32_16x16x32_bf16 v[116:119], v[170:173], v[190:193], v[116:119]
	v_mfma_f32_16x16x32_bf16 v[112:115], v[174:177], v[186:189], v[112:115]
	v_mfma_f32_16x16x32_bf16 v[112:115], v[178:181], v[190:193], v[112:115]
	v_mfma_f32_16x16x32_bf16 v[100:103], v[166:169], v[194:197], v[100:103]
	v_mfma_f32_16x16x32_bf16 v[100:103], v[170:173], v[198:201], v[100:103]
	v_mfma_f32_16x16x32_bf16 v[96:99], v[174:177], v[194:197], v[96:99]
	v_mfma_f32_16x16x32_bf16 v[96:99], v[178:181], v[198:201], v[96:99]
	v_mfma_f32_16x16x32_bf16 v[84:87], v[166:169], v[202:205], v[84:87]
	v_mfma_f32_16x16x32_bf16 v[84:87], v[170:173], v[206:209], v[84:87]
	v_mfma_f32_16x16x32_bf16 v[80:83], v[174:177], v[202:205], v[80:83]
	v_mfma_f32_16x16x32_bf16 v[80:83], v[178:181], v[206:209], v[80:83]
	v_mfma_f32_16x16x32_bf16 v[68:71], v[166:169], v[210:213], v[68:71]
	v_mfma_f32_16x16x32_bf16 v[68:71], v[170:173], v[214:217], v[68:71]
	v_mfma_f32_16x16x32_bf16 v[64:67], v[174:177], v[210:213], v[64:67]
	v_mfma_f32_16x16x32_bf16 v[64:67], v[178:181], v[214:217], v[64:67]
	s_setprio 0
	s_barrier
; #define PG8_STAGE(bufoff, gbase, voff) do { _Pragma("unroll") for (int _i = 0; _i < 2; ++_i) \
;         __builtin_amdgcn_global_load_lds((const unsigned*)((const char*)(gbase) + (voff)[_i]), (LAS unsigned*)(lds + (bufoff) + ldsw + _i * 8192), 16, 0, 0); } while (0)
; #define PG8_LDA(dst, b, h) do { _Pragma("unroll") for (int m = 0; m < 4; ++m) _Pragma("unroll") for (int k = 0; k < 2; ++k) dst[m][k] = *(const LAS bf16x8*)(lds + PG8_SA(b, h) + aoff + m * 2048 + k * 1024); } while (0)
; #define PG8_MMA(ai, bj, At, Bt) do { __builtin_amdgcn_s_setprio(1); _Pragma("unroll") for (int m = 0; m < 4; ++m) _Pragma("unroll") for (int n = 0; n < 2; ++n) _Pragma("unroll") for (int k = 0; k < 2; ++k) \
;         acc[ai][bj][m][n] = __builtin_amdgcn_mfma_f32_16x16x32_bf16(Bt[n][k], At[m][k], acc[ai][bj][m][n], 0, 0, 0); __builtin_amdgcn_s_setprio(0); } while (0)
; #define PG8_WAIT_V(n) asm volatile("s_waitcnt vmcnt(" #n ")" ::: "memory")
; #define PG8_WAIT_L(n) asm volatile("s_waitcnt lgkmcnt(" #n ")" ::: "memory")
; #define PG8_BAR __builtin_amdgcn_s_barrier()
; #define PG8_SCHED __builtin_amdgcn_sched_barrier(0)
; template <bool ALIGN_EPI, class Epi, class Sched>
; __device__ __forceinline__ void gemm_phase(LAS unsigned char* lds, const int lda, const int ldb, const int K, const Sched& S, const Epi& E, const size_t kstepA = (size_t)(BK * 2), const size_t kstepB = (size_t)(BK * 2)) {
;     ...
;             PG8_LDA(At, 1, 1); PG8_STAGE(PG8_SB(1, 0), b3, voffB); PG8_STAGE(PG8_SB(1, 1), b3 + hstepB, voffB); PG8_STAGE(PG8_SA(1, 0), a3, voffA);
;             PG8_WAIT_V(8); PG8_WAIT_L(0); PG8_BAR; PG8_MMA(1, 0, At, B0); PG8_MMA(1, 1, At, B1); PG8_BAR; PG8_SCHED;
;         }
	s_add_u32 s20, s16, 0x20000
	s_addc_u32 s21, s17, 0
	s_mov_b32 m0, s56
	v_lshl_add_u64 v[182:183], s[20:21], 0, v[130:131]
	s_add_u32 s16, s16, 0x24000
	ds_read_b128 v[186:189], v142 offset:49152
	ds_read_b128 v[190:193], v142 offset:50176
	ds_read_b128 v[194:197], v142 offset:51200
	ds_read_b128 v[198:201], v142 offset:52224
	ds_read_b128 v[202:205], v142 offset:53248
	ds_read_b128 v[206:209], v142 offset:54272
	ds_read_b128 v[210:213], v142 offset:55296
	ds_read_b128 v[214:217], v142 offset:56320
	global_load_lds_dwordx4 v[182:183], off
	v_lshl_add_u64 v[182:183], s[20:21], 0, v[134:135]
	s_mov_b32 m0, s57
	s_addc_u32 s17, s17, 0
	global_load_lds_dwordx4 v[182:183], off
	v_lshl_add_u64 v[182:183], s[16:17], 0, v[130:131]
	s_mov_b32 m0, s58
	s_nop 0
	global_load_lds_dwordx4 v[182:183], off
	v_lshl_add_u64 v[182:183], s[16:17], 0, v[134:135]
	s_mov_b32 m0, s59
	s_nop 0
	global_load_lds_dwordx4 v[182:183], off
	v_lshl_add_u64 v[182:183], s[14:15], 0, v[128:129]
	s_mov_b32 m0, s43
	s_nop 0
	global_load_lds_dwordx4 v[182:183], off
	v_lshl_add_u64 v[182:183], s[14:15], 0, v[132:133]
	s_mov_b32 m0, s44
	s_nop 0
	global_load_lds_dwordx4 v[182:183], off
	s_waitcnt vmcnt(8)
	s_waitcnt lgkmcnt(0)
	s_barrier
	s_setprio 1
	s_waitcnt lgkmcnt(0)
	v_mfma_f32_16x16x32_bf16 v[60:63], v[146:149], v[186:189], v[60:63]
	v_mfma_f32_16x16x32_bf16 v[60:63], v[150:153], v[190:193], v[60:63]
	v_mfma_f32_16x16x32_bf16 v[56:59], v[158:161], v[186:189], v[56:59]
	v_mfma_f32_16x16x32_bf16 v[56:59], v[162:165], v[190:193], v[56:59]
	v_mfma_f32_16x16x32_bf16 v[44:47], v[146:149], v[194:197], v[44:47]
	v_mfma_f32_16x16x32_bf16 v[44:47], v[150:153], v[198:201], v[44:47]
	v_mfma_f32_16x16x32_bf16 v[40:43], v[158:161], v[194:197], v[40:43]
	v_mfma_f32_16x16x32_bf16 v[40:43], v[162:165], v[198:201], v[40:43]
	v_mfma_f32_16x16x32_bf16 v[28:31], v[146:149], v[202:205], v[28:31]
	v_mfma_f32_16x16x32_bf16 v[28:31], v[150:153], v[206:209], v[28:31]
	v_mfma_f32_16x16x32_bf16 v[24:27], v[158:161], v[202:205], v[24:27]
	v_mfma_f32_16x16x32_bf16 v[24:27], v[162:165], v[206:209], v[24:27]
	v_mfma_f32_16x16x32_bf16 v[12:15], v[146:149], v[210:213], v[12:15]
	v_mfma_f32_16x16x32_bf16 v[12:15], v[150:153], v[214:217], v[12:15]
	v_mfma_f32_16x16x32_bf16 v[8:11], v[158:161], v[210:213], v[8:11]
	v_mfma_f32_16x16x32_bf16 v[8:11], v[162:165], v[214:217], v[8:11]
	s_setprio 0
	s_setprio 1
	v_mfma_f32_16x16x32_bf16 v[52:55], v[166:169], v[186:189], v[52:55]
	v_mfma_f32_16x16x32_bf16 v[52:55], v[170:173], v[190:193], v[52:55]
	v_mfma_f32_16x16x32_bf16 v[48:51], v[174:177], v[186:189], v[48:51]
	v_mfma_f32_16x16x32_bf16 v[48:51], v[178:181], v[190:193], v[48:51]
	v_mfma_f32_16x16x32_bf16 v[36:39], v[166:169], v[194:197], v[36:39]
	v_mfma_f32_16x16x32_bf16 v[36:39], v[170:173], v[198:201], v[36:39]
	v_mfma_f32_16x16x32_bf16 v[32:35], v[174:177], v[194:197], v[32:35]
	v_mfma_f32_16x16x32_bf16 v[32:35], v[178:181], v[198:201], v[32:35]
	v_mfma_f32_16x16x32_bf16 v[20:23], v[166:169], v[202:205], v[20:23]
	v_mfma_f32_16x16x32_bf16 v[20:23], v[170:173], v[206:209], v[20:23]
	v_mfma_f32_16x16x32_bf16 v[16:19], v[174:177], v[202:205], v[16:19]
	v_mfma_f32_16x16x32_bf16 v[16:19], v[178:181], v[206:209], v[16:19]
	v_mfma_f32_16x16x32_bf16 v[4:7], v[166:169], v[210:213], v[4:7]
	v_mfma_f32_16x16x32_bf16 v[4:7], v[170:173], v[214:217], v[4:7]
	v_mfma_f32_16x16x32_bf16 v[0:3], v[174:177], v[210:213], v[0:3]
	v_mfma_f32_16x16x32_bf16 v[0:3], v[178:181], v[214:217], v[0:3]
	s_setprio 0
	s_barrier
	s_add_i32 s49, s49, 2
	s_add_u32 s45, s45, 0x40000
	s_addc_u32 s48, s48, 0
	s_add_u32 s12, s12, 0x400000
	s_addc_u32 s13, s13, 0
	v_lshl_add_u64 v[136:137], v[136:137], 0, s[6:7]
	s_cmp_lt_u32 s49, 30
	v_lshl_add_u64 v[138:139], v[138:139], 0, s[6:7]
	s_cbranch_scc1 .LBB0_813
	s_waitcnt vmcnt(0)
	s_cmpk_gt_u32 s23, 0xff
	s_cbranch_scc1 .LBB0_816
	s_barrier

; #define PG8_STAGE(bufoff, gbase, voff) do { _Pragma("unroll") for (int _i = 0; _i < 2; ++_i) \
;         __builtin_amdgcn_global_load_lds((const unsigned*)((const char*)(gbase) + (voff)[_i]), (LAS unsigned*)(lds + (bufoff) + ldsw + _i * 8192), 16, 0, 0); } while (0)
; #define PG8_LDA(dst, b, h) do { _Pragma("unroll") for (int m = 0; m < 4; ++m) _Pragma("unroll") for (int k = 0; k < 2; ++k) dst[m][k] = *(const LAS bf16x8*)(lds + PG8_SA(b, h) + aoff + m * 2048 + k * 1024); } while (0)
; #define PG8_LDB(dst, b, h) do { _Pragma("unroll") for (int n = 0; n < 2; ++n) _Pragma("unroll") for (int k = 0; k < 2; ++k) dst[n][k] = *(const LAS bf16x8*)(lds + PG8_SB(b, h) + boff + n * 2048 + k * 1024); } while (0)
; #define PG8_MMA(ai, bj, At, Bt) do { __builtin_amdgcn_s_setprio(1); _Pragma("unroll") for (int m = 0; m < 4; ++m) _Pragma("unroll") for (int n = 0; n < 2; ++n) _Pragma("unroll") for (int k = 0; k < 2; ++k) \
;         acc[ai][bj][m][n] = __builtin_amdgcn_mfma_f32_16x16x32_bf16(Bt[n][k], At[m][k], acc[ai][bj][m][n], 0, 0, 0); __builtin_amdgcn_s_setprio(0); } while (0)
; #define PG8_WAIT_V(n) asm volatile("s_waitcnt vmcnt(" #n ")" ::: "memory")
; #define PG8_WAIT_L(n) asm volatile("s_waitcnt lgkmcnt(" #n ")" ::: "memory")
; #define PG8_BAR __builtin_amdgcn_s_barrier()
; #define PG8_SCHED __builtin_amdgcn_sched_barrier(0)
; template <bool ALIGN_EPI, class Epi, class Sched>
; __device__ __forceinline__ void gemm_phase(LAS unsigned char* lds, const int lda, const int ldb, const int K, const Sched& S, const Epi& E, const size_t kstepA = (size_t)(BK * 2), const size_t kstepB = (size_t)(BK * 2)) {
;     ...
;             const char* a1 = cA + (size_t)(t + 1) * kstepA;
;             const char* a2 = last ? nA : cA + (size_t)(t + 2) * kstepA; const char* b2 = last ? nB : cB + (size_t)(t + 2) * kstep;
;             const char* a3 = a2 + kstepA; const char* b3 = b2 + kstep;
;             PG8_LDB(B0, 0, 0); PG8_LDB(B1, 0, 1); PG8_SCHED; PG8_LDA(At, 0, 0); PG8_STAGE(PG8_SA(1, 1), a1 + hstepA, voffA);
;             PG8_WAIT_V(8); PG8_WAIT_L(0); PG8_BAR; PG8_MMA(0, 0, At, B0); PG8_MMA(0, 1, At, B1); PG8_BAR; PG8_SCHED;
;             PG8_LDA(At, 0, 1); PG8_STAGE(PG8_SB(0, 0), b2, voffB); PG8_STAGE(PG8_SB(0, 1), b2 + hstepB, voffB); PG8_STAGE(PG8_SA(0, 0), a2, voffA);
.LBB0_952:
	ds_read_b128 v[88:91], v219
	ds_read_b128 v[92:95], v219 offset:1024
	ds_read_b128 v[112:115], v219 offset:2048
	ds_read_b128 v[116:119], v219 offset:3072
	ds_read_b128 v[144:147], v220
	ds_read_b128 v[148:151], v220 offset:1024
	ds_read_b128 v[152:155], v220 offset:2048
	ds_read_b128 v[156:159], v220 offset:3072
	s_add_u32 s14, s12, 0x1fc000
	s_addc_u32 s15, s13, 0
	s_cmp_eq_u32 s61, 12
	s_cselect_b32 s20, s0, s14
	s_cselect_b32 s21, s1, s15
	s_cselect_b32 s16, s6, s22
	s_cselect_b32 s17, s7, s23
	s_add_u32 s14, s20, 0x200000
	s_addc_u32 s15, s21, 0
	v_lshl_add_u64 v[212:213], s[12:13], 0, v[178:179]
	s_add_i32 m0, s19, 0xc000
	ds_read_b128 v[160:163], v221
	ds_read_b128 v[164:167], v221 offset:1024
	ds_read_b128 v[188:191], v221 offset:2048
	ds_read_b128 v[192:195], v221 offset:3072
	ds_read_b128 v[196:199], v221 offset:4096
	ds_read_b128 v[200:203], v221 offset:5120
	ds_read_b128 v[204:207], v221 offset:6144
	ds_read_b128 v[208:211], v221 offset:7168
	global_load_lds_dwordx4 v[212:213], off
	v_lshl_add_u64 v[212:213], s[12:13], 0, v[180:181]
	s_add_i32 m0, s19, 0xe000
	s_nop 0
	global_load_lds_dwordx4 v[212:213], off
	s_waitcnt vmcnt(8)
	s_waitcnt lgkmcnt(0)
	s_barrier
	s_setprio 1
	s_waitcnt lgkmcnt(0)
	v_mfma_f32_16x16x32_bf16 v[140:143], v[88:91], v[160:163], v[140:143]
	v_mfma_f32_16x16x32_bf16 v[140:143], v[92:95], v[164:167], v[140:143]
	v_mfma_f32_16x16x32_bf16 v[136:139], v[112:115], v[160:163], v[136:139]
	v_mfma_f32_16x16x32_bf16 v[136:139], v[116:119], v[164:167], v[136:139]
	v_mfma_f32_16x16x32_bf16 v[124:127], v[88:91], v[188:191], v[124:127]
	v_mfma_f32_16x16x32_bf16 v[124:127], v[92:95], v[192:195], v[124:127]
	v_mfma_f32_16x16x32_bf16 v[120:123], v[112:115], v[188:191], v[120:123]
	v_mfma_f32_16x16x32_bf16 v[120:123], v[116:119], v[192:195], v[120:123]
	v_mfma_f32_16x16x32_bf16 v[100:103], v[88:91], v[196:199], v[100:103]
	v_mfma_f32_16x16x32_bf16 v[100:103], v[92:95], v[200:203], v[100:103]
	v_mfma_f32_16x16x32_bf16 v[96:99], v[112:115], v[196:199], v[96:99]
	v_mfma_f32_16x16x32_bf16 v[96:99], v[116:119], v[200:203], v[96:99]
	v_mfma_f32_16x16x32_bf16 v[76:79], v[88:91], v[204:207], v[76:79]
	v_mfma_f32_16x16x32_bf16 v[76:79], v[92:95], v[208:211], v[76:79]
	v_mfma_f32_16x16x32_bf16 v[72:75], v[112:115], v[204:207], v[72:75]
	v_mfma_f32_16x16x32_bf16 v[72:75], v[116:119], v[208:211], v[72:75]
	s_setprio 0
	s_setprio 1
	v_mfma_f32_16x16x32_bf16 v[132:135], v[144:147], v[160:163], v[132:135]
	v_mfma_f32_16x16x32_bf16 v[132:135], v[148:151], v[164:167], v[132:135]
	v_mfma_f32_16x16x32_bf16 v[128:131], v[152:155], v[160:163], v[128:131]
	v_mfma_f32_16x16x32_bf16 v[128:131], v[156:159], v[164:167], v[128:131]
	v_mfma_f32_16x16x32_bf16 v[108:111], v[144:147], v[188:191], v[108:111]
	v_mfma_f32_16x16x32_bf16 v[108:111], v[148:151], v[192:195], v[108:111]
	v_mfma_f32_16x16x32_bf16 v[104:107], v[152:155], v[188:191], v[104:107]
	v_mfma_f32_16x16x32_bf16 v[104:107], v[156:159], v[192:195], v[104:107]
	v_mfma_f32_16x16x32_bf16 v[84:87], v[144:147], v[196:199], v[84:87]
	v_mfma_f32_16x16x32_bf16 v[84:87], v[148:151], v[200:203], v[84:87]
	v_mfma_f32_16x16x32_bf16 v[80:83], v[152:155], v[196:199], v[80:83]
	v_mfma_f32_16x16x32_bf16 v[80:83], v[156:159], v[200:203], v[80:83]
	v_mfma_f32_16x16x32_bf16 v[68:71], v[144:147], v[204:207], v[68:71]
	v_mfma_f32_16x16x32_bf16 v[68:71], v[148:151], v[208:211], v[68:71]
	v_mfma_f32_16x16x32_bf16 v[64:67], v[152:155], v[204:207], v[64:67]
	v_mfma_f32_16x16x32_bf16 v[64:67], v[156:159], v[208:211], v[64:67]
	s_setprio 0
	s_barrier
	s_add_i32 s63, s71, s18
	v_lshl_add_u64 v[212:213], s[16:17], 0, v[170:171]
	s_mov_b32 m0, s63
	ds_read_b128 v[160:163], v221 offset:16384
	ds_read_b128 v[164:167], v221 offset:17408
	ds_read_b128 v[188:191], v221 offset:18432
	ds_read_b128 v[192:195], v221 offset:19456
	ds_read_b128 v[196:199], v221 offset:20480
	ds_read_b128 v[200:203], v221 offset:21504
	ds_read_b128 v[204:207], v221 offset:22528
	ds_read_b128 v[208:211], v221 offset:23552
	global_load_lds_dwordx4 v[212:213], off
	s_add_i32 m0, s63, 0x2000
	s_add_u32 s76, s16, 0x4000
	v_lshl_add_u64 v[212:213], s[16:17], 0, v[174:175]
	s_addc_u32 s77, s17, 0
	s_add_i32 s63, s72, s18
	global_load_lds_dwordx4 v[212:213], off
	v_lshl_add_u64 v[212:213], s[76:77], 0, v[170:171]
	s_mov_b32 m0, s63
	s_nop 0
	global_load_lds_dwordx4 v[212:213], off
	v_lshl_add_u64 v[212:213], s[76:77], 0, v[174:175]
	s_add_i32 m0, s63, 0x2000
	s_nop 0
	global_load_lds_dwordx4 v[212:213], off
	v_lshl_add_u64 v[212:213], s[20:21], 0, v[168:169]
	s_mov_b32 m0, s19
	s_nop 0
	global_load_lds_dwordx4 v[212:213], off
	v_lshl_add_u64 v[212:213], s[20:21], 0, v[172:173]
	s_mov_b32 m0, s33
	s_nop 0
	global_load_lds_dwordx4 v[212:213], off
	s_waitcnt vmcnt(8)
	s_waitcnt lgkmcnt(0)
	s_barrier
; #define PG8_STAGE(bufoff, gbase, voff) do { _Pragma("unroll") for (int _i = 0; _i < 2; ++_i) \
;         __builtin_amdgcn_global_load_lds((const unsigned*)((const char*)(gbase) + (voff)[_i]), (LAS unsigned*)(lds + (bufoff) + ldsw + _i * 8192), 16, 0, 0); } while (0)
; #define PG8_LDA(dst, b, h) do { _Pragma("unroll") for (int m = 0; m < 4; ++m) _Pragma("unroll") for (int k = 0; k < 2; ++k) dst[m][k] = *(const LAS bf16x8*)(lds + PG8_SA(b, h) + aoff + m * 2048 + k * 1024); } while (0)
; #define PG8_LDB(dst, b, h) do { _Pragma("unroll") for (int n = 0; n < 2; ++n) _Pragma("unroll") for (int k = 0; k < 2; ++k) dst[n][k] = *(const LAS bf16x8*)(lds + PG8_SB(b, h) + boff + n * 2048 + k * 1024); } while (0)
; #define PG8_MMA(ai, bj, At, Bt) do { __builtin_amdgcn_s_setprio(1); _Pragma("unroll") for (int m = 0; m < 4; ++m) _Pragma("unroll") for (int n = 0; n < 2; ++n) _Pragma("unroll") for (int k = 0; k < 2; ++k) \
;         acc[ai][bj][m][n] = __builtin_amdgcn_mfma_f32_16x16x32_bf16(Bt[n][k], At[m][k], acc[ai][bj][m][n], 0, 0, 0); __builtin_amdgcn_s_setprio(0); } while (0)
; #define PG8_WAIT_V(n) asm volatile("s_waitcnt vmcnt(" #n ")" ::: "memory")
; #define PG8_WAIT_L(n) asm volatile("s_waitcnt lgkmcnt(" #n ")" ::: "memory")
; #define PG8_BAR __builtin_amdgcn_s_barrier()
; #define PG8_SCHED __builtin_amdgcn_sched_barrier(0)
; template <bool ALIGN_EPI, class Epi, class Sched>
; __device__ __forceinline__ void gemm_phase(LAS unsigned char* lds, const int lda, const int ldb, const int K, const Sched& S, const Epi& E, const size_t kstepA = (size_t)(BK * 2), const size_t kstepB = (size_t)(BK * 2)) {
;     ...
;             PG8_WAIT_V(8); PG8_WAIT_L(0); PG8_BAR; PG8_MMA(1, 0, At, B0); PG8_MMA(1, 1, At, B1); PG8_BAR; PG8_SCHED;
;             PG8_LDB(B0, 1, 0); PG8_LDB(B1, 1, 1); PG8_SCHED; PG8_LDA(At, 1, 0); PG8_STAGE(PG8_SA(0, 1), a2 + hstepA, voffA);
;             PG8_WAIT_V(8); PG8_WAIT_L(0); PG8_BAR; PG8_MMA(0, 0, At, B0); PG8_MMA(0, 1, At, B1); PG8_BAR; PG8_SCHED;
	s_setprio 1
	s_waitcnt lgkmcnt(0)
	v_mfma_f32_16x16x32_bf16 v[60:63], v[88:91], v[160:163], v[60:63]
	v_mfma_f32_16x16x32_bf16 v[60:63], v[92:95], v[164:167], v[60:63]
	v_mfma_f32_16x16x32_bf16 v[56:59], v[112:115], v[160:163], v[56:59]
	v_mfma_f32_16x16x32_bf16 v[56:59], v[116:119], v[164:167], v[56:59]
	v_mfma_f32_16x16x32_bf16 v[44:47], v[88:91], v[188:191], v[44:47]
	v_mfma_f32_16x16x32_bf16 v[44:47], v[92:95], v[192:195], v[44:47]
	v_mfma_f32_16x16x32_bf16 v[40:43], v[112:115], v[188:191], v[40:43]
	v_mfma_f32_16x16x32_bf16 v[40:43], v[116:119], v[192:195], v[40:43]
	v_mfma_f32_16x16x32_bf16 v[28:31], v[88:91], v[196:199], v[28:31]
	v_mfma_f32_16x16x32_bf16 v[28:31], v[92:95], v[200:203], v[28:31]
	v_mfma_f32_16x16x32_bf16 v[24:27], v[112:115], v[196:199], v[24:27]
	v_mfma_f32_16x16x32_bf16 v[24:27], v[116:119], v[200:203], v[24:27]
	v_mfma_f32_16x16x32_bf16 v[12:15], v[88:91], v[204:207], v[12:15]
	v_mfma_f32_16x16x32_bf16 v[12:15], v[92:95], v[208:211], v[12:15]
	v_mfma_f32_16x16x32_bf16 v[8:11], v[112:115], v[204:207], v[8:11]
	v_mfma_f32_16x16x32_bf16 v[8:11], v[116:119], v[208:211], v[8:11]
	s_setprio 0
	s_setprio 1
	v_mfma_f32_16x16x32_bf16 v[52:55], v[144:147], v[160:163], v[52:55]
	v_mfma_f32_16x16x32_bf16 v[52:55], v[148:151], v[164:167], v[52:55]
	v_mfma_f32_16x16x32_bf16 v[48:51], v[152:155], v[160:163], v[48:51]
	v_mfma_f32_16x16x32_bf16 v[48:51], v[156:159], v[164:167], v[48:51]
	v_mfma_f32_16x16x32_bf16 v[36:39], v[144:147], v[188:191], v[36:39]
	v_mfma_f32_16x16x32_bf16 v[36:39], v[148:151], v[192:195], v[36:39]
	v_mfma_f32_16x16x32_bf16 v[32:35], v[152:155], v[188:191], v[32:35]
	v_mfma_f32_16x16x32_bf16 v[32:35], v[156:159], v[192:195], v[32:35]
	v_mfma_f32_16x16x32_bf16 v[20:23], v[144:147], v[196:199], v[20:23]
	v_mfma_f32_16x16x32_bf16 v[20:23], v[148:151], v[200:203], v[20:23]
	v_mfma_f32_16x16x32_bf16 v[16:19], v[152:155], v[196:199], v[16:19]
	v_mfma_f32_16x16x32_bf16 v[16:19], v[156:159], v[200:203], v[16:19]
	v_mfma_f32_16x16x32_bf16 v[4:7], v[144:147], v[204:207], v[4:7]
	v_mfma_f32_16x16x32_bf16 v[4:7], v[148:151], v[208:211], v[4:7]
	v_mfma_f32_16x16x32_bf16 v[0:3], v[152:155], v[204:207], v[0:3]
	v_mfma_f32_16x16x32_bf16 v[0:3], v[156:159], v[208:211], v[0:3]
	s_setprio 0
	s_barrier
	s_add_i32 s63, 0, 0x18000
	s_add_i32 s75, 0, 0x1c000
	v_add_u32_e32 v116, s63, v218
	v_add_u32_e32 v156, s75, v218
	ds_read_b128 v[88:91], v116
	ds_read_b128 v[92:95], v116 offset:1024
	ds_read_b128 v[112:115], v116 offset:2048
	ds_read_b128 v[116:119], v116 offset:3072
	ds_read_b128 v[144:147], v156
	ds_read_b128 v[148:151], v156 offset:1024
	ds_read_b128 v[152:155], v156 offset:2048
	ds_read_b128 v[156:159], v156 offset:3072
	s_add_u32 s20, s20, 0x4000
	s_addc_u32 s21, s21, 0
	s_mov_b32 m0, s42
	v_lshl_add_u64 v[212:213], s[20:21], 0, v[168:169]
	ds_read_b128 v[160:163], v221 offset:32768
	ds_read_b128 v[164:167], v221 offset:33792
	ds_read_b128 v[188:191], v221 offset:34816
	ds_read_b128 v[192:195], v221 offset:35840
	ds_read_b128 v[196:199], v221 offset:36864
	ds_read_b128 v[200:203], v221 offset:37888
	ds_read_b128 v[204:207], v221 offset:38912
	ds_read_b128 v[208:211], v221 offset:39936
	global_load_lds_dwordx4 v[212:213], off
	v_lshl_add_u64 v[212:213], s[20:21], 0, v[172:173]
	s_mov_b32 m0, s43
	s_nop 0
	global_load_lds_dwordx4 v[212:213], off
	s_waitcnt vmcnt(8)
	s_waitcnt lgkmcnt(0)
	s_barrier
	s_setprio 1
	s_waitcnt lgkmcnt(0)
	v_mfma_f32_16x16x32_bf16 v[140:143], v[88:91], v[160:163], v[140:143]
	v_mfma_f32_16x16x32_bf16 v[140:143], v[92:95], v[164:167], v[140:143]
	v_mfma_f32_16x16x32_bf16 v[136:139], v[112:115], v[160:163], v[136:139]
	v_mfma_f32_16x16x32_bf16 v[136:139], v[116:119], v[164:167], v[136:139]
	v_mfma_f32_16x16x32_bf16 v[124:127], v[88:91], v[188:191], v[124:127]
	v_mfma_f32_16x16x32_bf16 v[124:127], v[92:95], v[192:195], v[124:127]
	v_mfma_f32_16x16x32_bf16 v[120:123], v[112:115], v[188:191], v[120:123]
	v_mfma_f32_16x16x32_bf16 v[120:123], v[116:119], v[192:195], v[120:123]
	v_mfma_f32_16x16x32_bf16 v[100:103], v[88:91], v[196:199], v[100:103]
	v_mfma_f32_16x16x32_bf16 v[100:103], v[92:95], v[200:203], v[100:103]
	v_mfma_f32_16x16x32_bf16 v[96:99], v[112:115], v[196:199], v[96:99]
	v_mfma_f32_16x16x32_bf16 v[96:99], v[116:119], v[200:203], v[96:99]
	v_mfma_f32_16x16x32_bf16 v[76:79], v[88:91], v[204:207], v[76:79]
	v_mfma_f32_16x16x32_bf16 v[76:79], v[92:95], v[208:211], v[76:79]
	v_mfma_f32_16x16x32_bf16 v[72:75], v[112:115], v[204:207], v[72:75]
	v_mfma_f32_16x16x32_bf16 v[72:75], v[116:119], v[208:211], v[72:75]
	s_setprio 0
	s_setprio 1
	v_mfma_f32_16x16x32_bf16 v[132:135], v[144:147], v[160:163], v[132:135]
	v_mfma_f32_16x16x32_bf16 v[132:135], v[148:151], v[164:167], v[132:135]
	v_mfma_f32_16x16x32_bf16 v[128:131], v[152:155], v[160:163], v[128:131]
	v_mfma_f32_16x16x32_bf16 v[128:131], v[156:159], v[164:167], v[128:131]
	v_mfma_f32_16x16x32_bf16 v[108:111], v[144:147], v[188:191], v[108:111]
	v_mfma_f32_16x16x32_bf16 v[108:111], v[148:151], v[192:195], v[108:111]
	v_mfma_f32_16x16x32_bf16 v[104:107], v[152:155], v[188:191], v[104:107]
	v_mfma_f32_16x16x32_bf16 v[104:107], v[156:159], v[192:195], v[104:107]
	v_mfma_f32_16x16x32_bf16 v[84:87], v[144:147], v[196:199], v[84:87]
	v_mfma_f32_16x16x32_bf16 v[84:87], v[148:151], v[200:203], v[84:87]
	v_mfma_f32_16x16x32_bf16 v[80:83], v[152:155], v[196:199], v[80:83]
	v_mfma_f32_16x16x32_bf16 v[80:83], v[156:159], v[200:203], v[80:83]
	v_mfma_f32_16x16x32_bf16 v[68:71], v[144:147], v[204:207], v[68:71]
	v_mfma_f32_16x16x32_bf16 v[68:71], v[148:151], v[208:211], v[68:71]
	v_mfma_f32_16x16x32_bf16 v[64:67], v[152:155], v[204:207], v[64:67]
	v_mfma_f32_16x16x32_bf16 v[64:67], v[156:159], v[208:211], v[64:67]
	s_setprio 0
	s_barrier
; #define PG8_STAGE(bufoff, gbase, voff) do { _Pragma("unroll") for (int _i = 0; _i < 2; ++_i) \
;         __builtin_amdgcn_global_load_lds((const unsigned*)((const char*)(gbase) + (voff)[_i]), (LAS unsigned*)(lds + (bufoff) + ldsw + _i * 8192), 16, 0, 0); } while (0)
; #define PG8_LDA(dst, b, h) do { _Pragma("unroll") for (int m = 0; m < 4; ++m) _Pragma("unroll") for (int k = 0; k < 2; ++k) dst[m][k] = *(const LAS bf16x8*)(lds + PG8_SA(b, h) + aoff + m * 2048 + k * 1024); } while (0)
; #define PG8_MMA(ai, bj, At, Bt) do { __builtin_amdgcn_s_setprio(1); _Pragma("unroll") for (int m = 0; m < 4; ++m) _Pragma("unroll") for (int n = 0; n < 2; ++n) _Pragma("unroll") for (int k = 0; k < 2; ++k) \
;         acc[ai][bj][m][n] = __builtin_amdgcn_mfma_f32_16x16x32_bf16(Bt[n][k], At[m][k], acc[ai][bj][m][n], 0, 0, 0); __builtin_amdgcn_s_setprio(0); } while (0)
; #define PG8_WAIT_V(n) asm volatile("s_waitcnt vmcnt(" #n ")" ::: "memory")
; #define PG8_WAIT_L(n) asm volatile("s_waitcnt lgkmcnt(" #n ")" ::: "memory")
; #define PG8_BAR __builtin_amdgcn_s_barrier()
; #define PG8_SCHED __builtin_amdgcn_sched_barrier(0)
; template <bool ALIGN_EPI, class Epi, class Sched>
; __device__ __forceinline__ void gemm_phase(LAS unsigned char* lds, const int lda, const int ldb, const int K, const Sched& S, const Epi& E, const size_t kstepA = (size_t)(BK * 2), const size_t kstepB = (size_t)(BK * 2)) {
;     ...
;             PG8_LDA(At, 1, 1); PG8_STAGE(PG8_SB(1, 0), b3, voffB); PG8_STAGE(PG8_SB(1, 1), b3 + hstepB, voffB); PG8_STAGE(PG8_SA(1, 0), a3, voffA);
;             PG8_WAIT_V(8); PG8_WAIT_L(0); PG8_BAR; PG8_MMA(1, 0, At, B0); PG8_MMA(1, 1, At, B1); PG8_BAR; PG8_SCHED;
;         }
;         if constexpr (ALIGN_EPI) { if (wr == 0) PG8_BAR; }
	s_add_u32 s20, s16, 0x40000
	s_addc_u32 s21, s17, 0
	s_add_i32 s63, s63, s18
	v_lshl_add_u64 v[212:213], s[20:21], 0, v[170:171]
	s_mov_b32 m0, s63
	ds_read_b128 v[160:163], v221 offset:49152
	ds_read_b128 v[164:167], v221 offset:50176
	ds_read_b128 v[188:191], v221 offset:51200
	ds_read_b128 v[192:195], v221 offset:52224
	ds_read_b128 v[196:199], v221 offset:53248
	ds_read_b128 v[200:203], v221 offset:54272
	ds_read_b128 v[204:207], v221 offset:55296
	ds_read_b128 v[208:211], v221 offset:56320
	global_load_lds_dwordx4 v[212:213], off
	s_add_i32 m0, s63, 0x2000
	s_add_u32 s16, s16, 0x44000
	v_lshl_add_u64 v[212:213], s[20:21], 0, v[174:175]
	s_addc_u32 s17, s17, 0
	s_add_i32 s20, s75, s18
	global_load_lds_dwordx4 v[212:213], off
	v_lshl_add_u64 v[212:213], s[16:17], 0, v[170:171]
	s_mov_b32 m0, s20
	s_nop 0
	global_load_lds_dwordx4 v[212:213], off
	v_lshl_add_u64 v[212:213], s[16:17], 0, v[174:175]
	s_add_i32 m0, s20, 0x2000
	s_nop 0
	global_load_lds_dwordx4 v[212:213], off
	v_lshl_add_u64 v[212:213], s[14:15], 0, v[168:169]
	s_mov_b32 m0, s64
	s_nop 0
	global_load_lds_dwordx4 v[212:213], off
	v_lshl_add_u64 v[212:213], s[14:15], 0, v[172:173]
	s_mov_b32 m0, s65
	s_nop 0
	global_load_lds_dwordx4 v[212:213], off
	s_waitcnt vmcnt(8)
	s_waitcnt lgkmcnt(0)
	s_barrier
	s_setprio 1
	s_waitcnt lgkmcnt(0)
	v_mfma_f32_16x16x32_bf16 v[60:63], v[88:91], v[160:163], v[60:63]
	v_mfma_f32_16x16x32_bf16 v[60:63], v[92:95], v[164:167], v[60:63]
	v_mfma_f32_16x16x32_bf16 v[56:59], v[112:115], v[160:163], v[56:59]
	v_mfma_f32_16x16x32_bf16 v[56:59], v[116:119], v[164:167], v[56:59]
	v_mfma_f32_16x16x32_bf16 v[44:47], v[88:91], v[188:191], v[44:47]
	v_mfma_f32_16x16x32_bf16 v[44:47], v[92:95], v[192:195], v[44:47]
	v_mfma_f32_16x16x32_bf16 v[40:43], v[112:115], v[188:191], v[40:43]
	v_mfma_f32_16x16x32_bf16 v[40:43], v[116:119], v[192:195], v[40:43]
	v_mfma_f32_16x16x32_bf16 v[28:31], v[88:91], v[196:199], v[28:31]
	v_mfma_f32_16x16x32_bf16 v[28:31], v[92:95], v[200:203], v[28:31]
	v_mfma_f32_16x16x32_bf16 v[24:27], v[112:115], v[196:199], v[24:27]
	v_mfma_f32_16x16x32_bf16 v[24:27], v[116:119], v[200:203], v[24:27]
	v_mfma_f32_16x16x32_bf16 v[12:15], v[88:91], v[204:207], v[12:15]
	v_mfma_f32_16x16x32_bf16 v[12:15], v[92:95], v[208:211], v[12:15]
	v_mfma_f32_16x16x32_bf16 v[8:11], v[112:115], v[204:207], v[8:11]
	v_mfma_f32_16x16x32_bf16 v[8:11], v[116:119], v[208:211], v[8:11]
	s_setprio 0
	s_setprio 1
	v_mfma_f32_16x16x32_bf16 v[52:55], v[144:147], v[160:163], v[52:55]
	v_mfma_f32_16x16x32_bf16 v[52:55], v[148:151], v[164:167], v[52:55]
	v_mfma_f32_16x16x32_bf16 v[48:51], v[152:155], v[160:163], v[48:51]
	v_mfma_f32_16x16x32_bf16 v[48:51], v[156:159], v[164:167], v[48:51]
	v_mfma_f32_16x16x32_bf16 v[36:39], v[144:147], v[188:191], v[36:39]
	v_mfma_f32_16x16x32_bf16 v[36:39], v[148:151], v[192:195], v[36:39]
	v_mfma_f32_16x16x32_bf16 v[32:35], v[152:155], v[188:191], v[32:35]
	v_mfma_f32_16x16x32_bf16 v[32:35], v[156:159], v[192:195], v[32:35]
	v_mfma_f32_16x16x32_bf16 v[20:23], v[144:147], v[196:199], v[20:23]
	v_mfma_f32_16x16x32_bf16 v[20:23], v[148:151], v[200:203], v[20:23]
	v_mfma_f32_16x16x32_bf16 v[16:19], v[152:155], v[196:199], v[16:19]
	v_mfma_f32_16x16x32_bf16 v[16:19], v[156:159], v[200:203], v[16:19]
	v_mfma_f32_16x16x32_bf16 v[4:7], v[144:147], v[204:207], v[4:7]
	v_mfma_f32_16x16x32_bf16 v[4:7], v[148:151], v[208:211], v[4:7]
	v_mfma_f32_16x16x32_bf16 v[0:3], v[152:155], v[204:207], v[0:3]
	v_mfma_f32_16x16x32_bf16 v[0:3], v[156:159], v[208:211], v[0:3]
	s_setprio 0
	s_barrier
	s_add_i32 s61, s61, 2
	s_add_u32 s22, s22, 0x80000
	s_addc_u32 s23, s23, 0
	s_add_u32 s12, s12, 0x400000
	s_addc_u32 s13, s13, 0
	s_cmp_gt_u32 s61, 13
	s_cbranch_scc0 .LBB0_952
	s_and_b64 vcc, exec, s[52:53]
	s_cbranch_vccz .LBB0_955
	s_barrier

; #define PG8_STAGE(bufoff, gbase, voff) do { _Pragma("unroll") for (int _i = 0; _i < 2; ++_i) \
;         __builtin_amdgcn_global_load_lds((const unsigned*)((const char*)(gbase) + (voff)[_i]), (LAS unsigned*)(lds + (bufoff) + ldsw + _i * 8192), 16, 0, 0); } while (0)
; #define PG8_LDA(dst, b, h) do { _Pragma("unroll") for (int m = 0; m < 4; ++m) _Pragma("unroll") for (int k = 0; k < 2; ++k) dst[m][k] = *(const LAS bf16x8*)(lds + PG8_SA(b, h) + aoff + m * 2048 + k * 1024); } while (0)
; #define PG8_LDB(dst, b, h) do { _Pragma("unroll") for (int n = 0; n < 2; ++n) _Pragma("unroll") for (int k = 0; k < 2; ++k) dst[n][k] = *(const LAS bf16x8*)(lds + PG8_SB(b, h) + boff + n * 2048 + k * 1024); } while (0)
; #define PG8_MMA(ai, bj, At, Bt) do { __builtin_amdgcn_s_setprio(1); _Pragma("unroll") for (int m = 0; m < 4; ++m) _Pragma("unroll") for (int n = 0; n < 2; ++n) _Pragma("unroll") for (int k = 0; k < 2; ++k) \
;         acc[ai][bj][m][n] = __builtin_amdgcn_mfma_f32_16x16x32_bf16(Bt[n][k], At[m][k], acc[ai][bj][m][n], 0, 0, 0); __builtin_amdgcn_s_setprio(0); } while (0)
; #define PG8_WAIT_V(n) asm volatile("s_waitcnt vmcnt(" #n ")" ::: "memory")
; #define PG8_WAIT_L(n) asm volatile("s_waitcnt lgkmcnt(" #n ")" ::: "memory")
; #define PG8_BAR __builtin_amdgcn_s_barrier()
; #define PG8_SCHED __builtin_amdgcn_sched_barrier(0)
; template <bool ALIGN_EPI, class Epi, class Sched>
; __device__ __forceinline__ void gemm_phase(LAS unsigned char* lds, const int lda, const int ldb, const int K, const Sched& S, const Epi& E, const size_t kstepA = (size_t)(BK * 2), const size_t kstepB = (size_t)(BK * 2)) {
;     ...
;         for (int t = 0; t < nt; t += 2) {
;             const bool last = (t == nt - 2);
;             const char* a1 = cA + (size_t)(t + 1) * kstepA;
;             const char* a2 = last ? nA : cA + (size_t)(t + 2) * kstepA; const char* b2 = last ? nB : cB + (size_t)(t + 2) * kstep;
;             const char* a3 = a2 + kstepA; const char* b3 = b2 + kstep;
;             PG8_LDB(B0, 0, 0); PG8_LDB(B1, 0, 1); PG8_SCHED; PG8_LDA(At, 0, 0); PG8_STAGE(PG8_SA(1, 1), a1 + hstepA, voffA);
;             PG8_WAIT_V(8); PG8_WAIT_L(0); PG8_BAR; PG8_MMA(0, 0, At, B0); PG8_MMA(0, 1, At, B1); PG8_BAR; PG8_SCHED;
;             PG8_LDA(At, 0, 1); PG8_STAGE(PG8_SB(0, 0), b2, voffB); PG8_STAGE(PG8_SB(0, 1), b2 + hstepB, voffB); PG8_STAGE(PG8_SA(0, 0), a2, voffA);
.LBB0_1044:
	ds_read_b128 v[148:151], v168
	ds_read_b128 v[172:175], v168 offset:1024
	ds_read_b128 v[176:179], v168 offset:2048
	ds_read_b128 v[180:183], v168 offset:3072
	ds_read_b128 v[186:189], v169
	ds_read_b128 v[190:193], v169 offset:1024
	ds_read_b128 v[194:197], v169 offset:2048
	ds_read_b128 v[198:201], v169 offset:3072
	s_add_u32 s48, s46, 0x1fc000
	s_addc_u32 s49, s47, 0
	s_cmp_eq_u32 s15, 28
	s_cselect_b32 s54, s22, s48
	s_cselect_b32 s55, s23, s49
	s_cselect_b32 s52, s44, s9
	s_cselect_b32 s53, s45, s13
	s_add_u32 s48, s54, 0x200000
	s_addc_u32 s49, s55, 0
	v_lshl_add_u64 v[234:235], s[46:47], 0, v[140:141]
	s_add_i32 m0, s29, 0xc000
	ds_read_b128 v[202:205], v170
	ds_read_b128 v[206:209], v170 offset:1024
	ds_read_b128 v[210:213], v170 offset:2048
	ds_read_b128 v[214:217], v170 offset:3072
	ds_read_b128 v[218:221], v170 offset:4096
	ds_read_b128 v[222:225], v170 offset:5120
	ds_read_b128 v[226:229], v170 offset:6144
	ds_read_b128 v[230:233], v170 offset:7168
	global_load_lds_dwordx4 v[234:235], off
	v_lshl_add_u64 v[234:235], s[46:47], 0, v[142:143]
	s_add_i32 m0, s29, 0xe000
	s_nop 0
	global_load_lds_dwordx4 v[234:235], off
	s_waitcnt vmcnt(8)
	s_waitcnt lgkmcnt(0)
	s_barrier
	s_setprio 1
	s_waitcnt lgkmcnt(0)
	v_mfma_f32_16x16x32_bf16 v[124:127], v[148:151], v[202:205], v[124:127]
	v_mfma_f32_16x16x32_bf16 v[124:127], v[172:175], v[206:209], v[124:127]
	v_mfma_f32_16x16x32_bf16 v[120:123], v[176:179], v[202:205], v[120:123]
	v_mfma_f32_16x16x32_bf16 v[120:123], v[180:183], v[206:209], v[120:123]
	v_mfma_f32_16x16x32_bf16 v[108:111], v[148:151], v[210:213], v[108:111]
	v_mfma_f32_16x16x32_bf16 v[108:111], v[172:175], v[214:217], v[108:111]
	v_mfma_f32_16x16x32_bf16 v[104:107], v[176:179], v[210:213], v[104:107]
	v_mfma_f32_16x16x32_bf16 v[104:107], v[180:183], v[214:217], v[104:107]
	v_mfma_f32_16x16x32_bf16 v[92:95], v[148:151], v[218:221], v[92:95]
	v_mfma_f32_16x16x32_bf16 v[92:95], v[172:175], v[222:225], v[92:95]
	v_mfma_f32_16x16x32_bf16 v[88:91], v[176:179], v[218:221], v[88:91]
	v_mfma_f32_16x16x32_bf16 v[88:91], v[180:183], v[222:225], v[88:91]
	v_mfma_f32_16x16x32_bf16 v[76:79], v[148:151], v[226:229], v[76:79]
	v_mfma_f32_16x16x32_bf16 v[76:79], v[172:175], v[230:233], v[76:79]
	v_mfma_f32_16x16x32_bf16 v[72:75], v[176:179], v[226:229], v[72:75]
	v_mfma_f32_16x16x32_bf16 v[72:75], v[180:183], v[230:233], v[72:75]
	s_setprio 0
	s_setprio 1
	v_mfma_f32_16x16x32_bf16 v[116:119], v[186:189], v[202:205], v[116:119]
	v_mfma_f32_16x16x32_bf16 v[116:119], v[190:193], v[206:209], v[116:119]
	v_mfma_f32_16x16x32_bf16 v[112:115], v[194:197], v[202:205], v[112:115]
	v_mfma_f32_16x16x32_bf16 v[112:115], v[198:201], v[206:209], v[112:115]
	v_mfma_f32_16x16x32_bf16 v[100:103], v[186:189], v[210:213], v[100:103]
	v_mfma_f32_16x16x32_bf16 v[100:103], v[190:193], v[214:217], v[100:103]
	v_mfma_f32_16x16x32_bf16 v[96:99], v[194:197], v[210:213], v[96:99]
	v_mfma_f32_16x16x32_bf16 v[96:99], v[198:201], v[214:217], v[96:99]
	v_mfma_f32_16x16x32_bf16 v[84:87], v[186:189], v[218:221], v[84:87]
	v_mfma_f32_16x16x32_bf16 v[84:87], v[190:193], v[222:225], v[84:87]
	v_mfma_f32_16x16x32_bf16 v[80:83], v[194:197], v[218:221], v[80:83]
	v_mfma_f32_16x16x32_bf16 v[80:83], v[198:201], v[222:225], v[80:83]
	v_mfma_f32_16x16x32_bf16 v[68:71], v[186:189], v[226:229], v[68:71]
	v_mfma_f32_16x16x32_bf16 v[68:71], v[190:193], v[230:233], v[68:71]
	v_mfma_f32_16x16x32_bf16 v[64:67], v[194:197], v[226:229], v[64:67]
	v_mfma_f32_16x16x32_bf16 v[64:67], v[198:201], v[230:233], v[64:67]
	s_setprio 0
	s_barrier
	s_add_i32 s61, s57, s19
	v_lshl_add_u64 v[234:235], s[52:53], 0, v[130:131]
	s_mov_b32 m0, s61
	ds_read_b128 v[202:205], v170 offset:16384
	ds_read_b128 v[206:209], v170 offset:17408
	ds_read_b128 v[210:213], v170 offset:18432
	ds_read_b128 v[214:217], v170 offset:19456
	ds_read_b128 v[218:221], v170 offset:20480
	ds_read_b128 v[222:225], v170 offset:21504
	ds_read_b128 v[226:229], v170 offset:22528
	ds_read_b128 v[230:233], v170 offset:23552
	global_load_lds_dwordx4 v[234:235], off
	s_add_i32 m0, s61, 0x2000
	s_add_u32 s62, s52, 0x4000
	v_lshl_add_u64 v[234:235], s[52:53], 0, v[134:135]
	s_addc_u32 s63, s53, 0
	s_add_i32 s61, s58, s19
	global_load_lds_dwordx4 v[234:235], off
	v_lshl_add_u64 v[234:235], s[62:63], 0, v[130:131]
	s_mov_b32 m0, s61
	s_nop 0
	global_load_lds_dwordx4 v[234:235], off
	v_lshl_add_u64 v[234:235], s[62:63], 0, v[134:135]
	s_add_i32 m0, s61, 0x2000
	s_nop 0
	global_load_lds_dwordx4 v[234:235], off
	v_lshl_add_u64 v[234:235], s[54:55], 0, v[128:129]
	s_mov_b32 m0, s29
	s_nop 0
	global_load_lds_dwordx4 v[234:235], off
	v_lshl_add_u64 v[234:235], s[54:55], 0, v[132:133]
	s_mov_b32 m0, s30
	s_nop 0
	global_load_lds_dwordx4 v[234:235], off
	s_waitcnt vmcnt(8)
	s_waitcnt lgkmcnt(0)
	s_barrier
; #define PG8_STAGE(bufoff, gbase, voff) do { _Pragma("unroll") for (int _i = 0; _i < 2; ++_i) \
;         __builtin_amdgcn_global_load_lds((const unsigned*)((const char*)(gbase) + (voff)[_i]), (LAS unsigned*)(lds + (bufoff) + ldsw + _i * 8192), 16, 0, 0); } while (0)
; #define PG8_LDA(dst, b, h) do { _Pragma("unroll") for (int m = 0; m < 4; ++m) _Pragma("unroll") for (int k = 0; k < 2; ++k) dst[m][k] = *(const LAS bf16x8*)(lds + PG8_SA(b, h) + aoff + m * 2048 + k * 1024); } while (0)
; #define PG8_LDB(dst, b, h) do { _Pragma("unroll") for (int n = 0; n < 2; ++n) _Pragma("unroll") for (int k = 0; k < 2; ++k) dst[n][k] = *(const LAS bf16x8*)(lds + PG8_SB(b, h) + boff + n * 2048 + k * 1024); } while (0)
; #define PG8_MMA(ai, bj, At, Bt) do { __builtin_amdgcn_s_setprio(1); _Pragma("unroll") for (int m = 0; m < 4; ++m) _Pragma("unroll") for (int n = 0; n < 2; ++n) _Pragma("unroll") for (int k = 0; k < 2; ++k) \
;         acc[ai][bj][m][n] = __builtin_amdgcn_mfma_f32_16x16x32_bf16(Bt[n][k], At[m][k], acc[ai][bj][m][n], 0, 0, 0); __builtin_amdgcn_s_setprio(0); } while (0)
; #define PG8_WAIT_V(n) asm volatile("s_waitcnt vmcnt(" #n ")" ::: "memory")
; #define PG8_WAIT_L(n) asm volatile("s_waitcnt lgkmcnt(" #n ")" ::: "memory")
; #define PG8_BAR __builtin_amdgcn_s_barrier()
; #define PG8_SCHED __builtin_amdgcn_sched_barrier(0)
; template <bool ALIGN_EPI, class Epi, class Sched>
; __device__ __forceinline__ void gemm_phase(LAS unsigned char* lds, const int lda, const int ldb, const int K, const Sched& S, const Epi& E, const size_t kstepA = (size_t)(BK * 2), const size_t kstepB = (size_t)(BK * 2)) {
;     ...
;             PG8_WAIT_V(8); PG8_WAIT_L(0); PG8_BAR; PG8_MMA(1, 0, At, B0); PG8_MMA(1, 1, At, B1); PG8_BAR; PG8_SCHED;
;             PG8_LDB(B0, 1, 0); PG8_LDB(B1, 1, 1); PG8_SCHED; PG8_LDA(At, 1, 0); PG8_STAGE(PG8_SA(0, 1), a2 + hstepA, voffA);
;             PG8_WAIT_V(8); PG8_WAIT_L(0); PG8_BAR; PG8_MMA(0, 0, At, B0); PG8_MMA(0, 1, At, B1); PG8_BAR; PG8_SCHED;
	s_setprio 1
	s_waitcnt lgkmcnt(0)
	v_mfma_f32_16x16x32_bf16 v[60:63], v[148:151], v[202:205], v[60:63]
	v_mfma_f32_16x16x32_bf16 v[60:63], v[172:175], v[206:209], v[60:63]
	v_mfma_f32_16x16x32_bf16 v[56:59], v[176:179], v[202:205], v[56:59]
	v_mfma_f32_16x16x32_bf16 v[56:59], v[180:183], v[206:209], v[56:59]
	v_mfma_f32_16x16x32_bf16 v[44:47], v[148:151], v[210:213], v[44:47]
	v_mfma_f32_16x16x32_bf16 v[44:47], v[172:175], v[214:217], v[44:47]
	v_mfma_f32_16x16x32_bf16 v[40:43], v[176:179], v[210:213], v[40:43]
	v_mfma_f32_16x16x32_bf16 v[40:43], v[180:183], v[214:217], v[40:43]
	v_mfma_f32_16x16x32_bf16 v[28:31], v[148:151], v[218:221], v[28:31]
	v_mfma_f32_16x16x32_bf16 v[28:31], v[172:175], v[222:225], v[28:31]
	v_mfma_f32_16x16x32_bf16 v[24:27], v[176:179], v[218:221], v[24:27]
	v_mfma_f32_16x16x32_bf16 v[24:27], v[180:183], v[222:225], v[24:27]
	v_mfma_f32_16x16x32_bf16 v[12:15], v[148:151], v[226:229], v[12:15]
	v_mfma_f32_16x16x32_bf16 v[12:15], v[172:175], v[230:233], v[12:15]
	v_mfma_f32_16x16x32_bf16 v[8:11], v[176:179], v[226:229], v[8:11]
	v_mfma_f32_16x16x32_bf16 v[8:11], v[180:183], v[230:233], v[8:11]
	s_setprio 0
	s_setprio 1
	v_mfma_f32_16x16x32_bf16 v[52:55], v[186:189], v[202:205], v[52:55]
	v_mfma_f32_16x16x32_bf16 v[52:55], v[190:193], v[206:209], v[52:55]
	v_mfma_f32_16x16x32_bf16 v[48:51], v[194:197], v[202:205], v[48:51]
	v_mfma_f32_16x16x32_bf16 v[48:51], v[198:201], v[206:209], v[48:51]
	v_mfma_f32_16x16x32_bf16 v[36:39], v[186:189], v[210:213], v[36:39]
	v_mfma_f32_16x16x32_bf16 v[36:39], v[190:193], v[214:217], v[36:39]
	v_mfma_f32_16x16x32_bf16 v[32:35], v[194:197], v[210:213], v[32:35]
	v_mfma_f32_16x16x32_bf16 v[32:35], v[198:201], v[214:217], v[32:35]
	v_mfma_f32_16x16x32_bf16 v[20:23], v[186:189], v[218:221], v[20:23]
	v_mfma_f32_16x16x32_bf16 v[20:23], v[190:193], v[222:225], v[20:23]
	v_mfma_f32_16x16x32_bf16 v[16:19], v[194:197], v[218:221], v[16:19]
	v_mfma_f32_16x16x32_bf16 v[16:19], v[198:201], v[222:225], v[16:19]
	v_mfma_f32_16x16x32_bf16 v[4:7], v[186:189], v[226:229], v[4:7]
	v_mfma_f32_16x16x32_bf16 v[4:7], v[190:193], v[230:233], v[4:7]
	v_mfma_f32_16x16x32_bf16 v[0:3], v[194:197], v[226:229], v[0:3]
	v_mfma_f32_16x16x32_bf16 v[0:3], v[198:201], v[230:233], v[0:3]
	s_setprio 0
	s_barrier
	s_add_i32 s61, 0, 0x18000
	v_add_u32_e32 v136, s61, v152
	s_add_i32 s62, 0, 0x1c000
	ds_read_b128 v[148:151], v136
	ds_read_b128 v[172:175], v136 offset:1024
	ds_read_b128 v[176:179], v136 offset:2048
	ds_read_b128 v[180:183], v136 offset:3072
	v_add_u32_e32 v136, s62, v152
	ds_read_b128 v[186:189], v136
	ds_read_b128 v[190:193], v136 offset:1024
	ds_read_b128 v[194:197], v136 offset:2048
	ds_read_b128 v[198:201], v136 offset:3072
	s_add_u32 s54, s54, 0x4000
	s_addc_u32 s55, s55, 0
	s_mov_b32 m0, s31
	v_lshl_add_u64 v[234:235], s[54:55], 0, v[128:129]
	ds_read_b128 v[202:205], v170 offset:32768
	ds_read_b128 v[206:209], v170 offset:33792
	ds_read_b128 v[210:213], v170 offset:34816
	ds_read_b128 v[214:217], v170 offset:35840
	ds_read_b128 v[218:221], v170 offset:36864
	ds_read_b128 v[222:225], v170 offset:37888
	ds_read_b128 v[226:229], v170 offset:38912
	ds_read_b128 v[230:233], v170 offset:39936
	global_load_lds_dwordx4 v[234:235], off
	v_lshl_add_u64 v[234:235], s[54:55], 0, v[132:133]
	s_mov_b32 m0, s33
	s_nop 0
	global_load_lds_dwordx4 v[234:235], off
	s_waitcnt vmcnt(8)
	s_waitcnt lgkmcnt(0)
	s_barrier
	s_setprio 1
	s_waitcnt lgkmcnt(0)
	v_mfma_f32_16x16x32_bf16 v[124:127], v[148:151], v[202:205], v[124:127]
	v_mfma_f32_16x16x32_bf16 v[124:127], v[172:175], v[206:209], v[124:127]
	v_mfma_f32_16x16x32_bf16 v[120:123], v[176:179], v[202:205], v[120:123]
	v_mfma_f32_16x16x32_bf16 v[120:123], v[180:183], v[206:209], v[120:123]
	v_mfma_f32_16x16x32_bf16 v[108:111], v[148:151], v[210:213], v[108:111]
	v_mfma_f32_16x16x32_bf16 v[108:111], v[172:175], v[214:217], v[108:111]
	v_mfma_f32_16x16x32_bf16 v[104:107], v[176:179], v[210:213], v[104:107]
	v_mfma_f32_16x16x32_bf16 v[104:107], v[180:183], v[214:217], v[104:107]
	v_mfma_f32_16x16x32_bf16 v[92:95], v[148:151], v[218:221], v[92:95]
	v_mfma_f32_16x16x32_bf16 v[92:95], v[172:175], v[222:225], v[92:95]
	v_mfma_f32_16x16x32_bf16 v[88:91], v[176:179], v[218:221], v[88:91]
	v_mfma_f32_16x16x32_bf16 v[88:91], v[180:183], v[222:225], v[88:91]
	v_mfma_f32_16x16x32_bf16 v[76:79], v[148:151], v[226:229], v[76:79]
	v_mfma_f32_16x16x32_bf16 v[76:79], v[172:175], v[230:233], v[76:79]
	v_mfma_f32_16x16x32_bf16 v[72:75], v[176:179], v[226:229], v[72:75]
	v_mfma_f32_16x16x32_bf16 v[72:75], v[180:183], v[230:233], v[72:75]
	s_setprio 0
	s_setprio 1
	v_mfma_f32_16x16x32_bf16 v[116:119], v[186:189], v[202:205], v[116:119]
	v_mfma_f32_16x16x32_bf16 v[116:119], v[190:193], v[206:209], v[116:119]
	v_mfma_f32_16x16x32_bf16 v[112:115], v[194:197], v[202:205], v[112:115]
	v_mfma_f32_16x16x32_bf16 v[112:115], v[198:201], v[206:209], v[112:115]
	v_mfma_f32_16x16x32_bf16 v[100:103], v[186:189], v[210:213], v[100:103]
	v_mfma_f32_16x16x32_bf16 v[100:103], v[190:193], v[214:217], v[100:103]
	v_mfma_f32_16x16x32_bf16 v[96:99], v[194:197], v[210:213], v[96:99]
	v_mfma_f32_16x16x32_bf16 v[96:99], v[198:201], v[214:217], v[96:99]
	v_mfma_f32_16x16x32_bf16 v[84:87], v[186:189], v[218:221], v[84:87]
	v_mfma_f32_16x16x32_bf16 v[84:87], v[190:193], v[222:225], v[84:87]
	v_mfma_f32_16x16x32_bf16 v[80:83], v[194:197], v[218:221], v[80:83]
	v_mfma_f32_16x16x32_bf16 v[80:83], v[198:201], v[222:225], v[80:83]
	v_mfma_f32_16x16x32_bf16 v[68:71], v[186:189], v[226:229], v[68:71]
	v_mfma_f32_16x16x32_bf16 v[68:71], v[190:193], v[230:233], v[68:71]
	v_mfma_f32_16x16x32_bf16 v[64:67], v[194:197], v[226:229], v[64:67]
	v_mfma_f32_16x16x32_bf16 v[64:67], v[198:201], v[230:233], v[64:67]
	s_setprio 0
	s_barrier
; #define PG8_STAGE(bufoff, gbase, voff) do { _Pragma("unroll") for (int _i = 0; _i < 2; ++_i) \
;         __builtin_amdgcn_global_load_lds((const unsigned*)((const char*)(gbase) + (voff)[_i]), (LAS unsigned*)(lds + (bufoff) + ldsw + _i * 8192), 16, 0, 0); } while (0)
; #define PG8_LDA(dst, b, h) do { _Pragma("unroll") for (int m = 0; m < 4; ++m) _Pragma("unroll") for (int k = 0; k < 2; ++k) dst[m][k] = *(const LAS bf16x8*)(lds + PG8_SA(b, h) + aoff + m * 2048 + k * 1024); } while (0)
; #define PG8_MMA(ai, bj, At, Bt) do { __builtin_amdgcn_s_setprio(1); _Pragma("unroll") for (int m = 0; m < 4; ++m) _Pragma("unroll") for (int n = 0; n < 2; ++n) _Pragma("unroll") for (int k = 0; k < 2; ++k) \
;         acc[ai][bj][m][n] = __builtin_amdgcn_mfma_f32_16x16x32_bf16(Bt[n][k], At[m][k], acc[ai][bj][m][n], 0, 0, 0); __builtin_amdgcn_s_setprio(0); } while (0)
; #define PG8_WAIT_V(n) asm volatile("s_waitcnt vmcnt(" #n ")" ::: "memory")
; #define PG8_WAIT_L(n) asm volatile("s_waitcnt lgkmcnt(" #n ")" ::: "memory")
; #define PG8_BAR __builtin_amdgcn_s_barrier()
; #define PG8_SCHED __builtin_amdgcn_sched_barrier(0)
; template <bool ALIGN_EPI, class Epi, class Sched>
; __device__ __forceinline__ void gemm_phase(LAS unsigned char* lds, const int lda, const int ldb, const int K, const Sched& S, const Epi& E, const size_t kstepA = (size_t)(BK * 2), const size_t kstepB = (size_t)(BK * 2)) {
;     ...
;             PG8_LDA(At, 1, 1); PG8_STAGE(PG8_SB(1, 0), b3, voffB); PG8_STAGE(PG8_SB(1, 1), b3 + hstepB, voffB); PG8_STAGE(PG8_SA(1, 0), a3, voffA);
;             PG8_WAIT_V(8); PG8_WAIT_L(0); PG8_BAR; PG8_MMA(1, 0, At, B0); PG8_MMA(1, 1, At, B1); PG8_BAR; PG8_SCHED;
;         }
;         if constexpr (ALIGN_EPI) { if (wr == 0) PG8_BAR; }
	s_add_u32 s54, s52, 0x160000
	s_addc_u32 s55, s53, 0
	s_add_i32 s61, s61, s19
	v_lshl_add_u64 v[234:235], s[54:55], 0, v[130:131]
	s_mov_b32 m0, s61
	ds_read_b128 v[202:205], v170 offset:49152
	ds_read_b128 v[206:209], v170 offset:50176
	ds_read_b128 v[210:213], v170 offset:51200
	ds_read_b128 v[214:217], v170 offset:52224
	ds_read_b128 v[218:221], v170 offset:53248
	ds_read_b128 v[222:225], v170 offset:54272
	ds_read_b128 v[226:229], v170 offset:55296
	ds_read_b128 v[230:233], v170 offset:56320
	global_load_lds_dwordx4 v[234:235], off
	s_add_i32 m0, s61, 0x2000
	s_add_u32 s52, s52, 0x164000
	v_lshl_add_u64 v[234:235], s[54:55], 0, v[134:135]
	s_addc_u32 s53, s53, 0
	s_add_i32 s54, s62, s19
	global_load_lds_dwordx4 v[234:235], off
	v_lshl_add_u64 v[234:235], s[52:53], 0, v[130:131]
	s_mov_b32 m0, s54
	s_nop 0
	global_load_lds_dwordx4 v[234:235], off
	v_lshl_add_u64 v[234:235], s[52:53], 0, v[134:135]
	s_add_i32 m0, s54, 0x2000
	s_nop 0
	global_load_lds_dwordx4 v[234:235], off
	v_lshl_add_u64 v[234:235], s[48:49], 0, v[128:129]
	s_mov_b32 m0, s50
	s_nop 0
	global_load_lds_dwordx4 v[234:235], off
	v_lshl_add_u64 v[234:235], s[48:49], 0, v[132:133]
	s_mov_b32 m0, s51
	s_nop 0
	global_load_lds_dwordx4 v[234:235], off
	s_waitcnt vmcnt(8)
	s_waitcnt lgkmcnt(0)
	s_barrier
	s_setprio 1
	s_waitcnt lgkmcnt(0)
	v_mfma_f32_16x16x32_bf16 v[60:63], v[148:151], v[202:205], v[60:63]
	v_mfma_f32_16x16x32_bf16 v[60:63], v[172:175], v[206:209], v[60:63]
	v_mfma_f32_16x16x32_bf16 v[56:59], v[176:179], v[202:205], v[56:59]
	v_mfma_f32_16x16x32_bf16 v[56:59], v[180:183], v[206:209], v[56:59]
	v_mfma_f32_16x16x32_bf16 v[44:47], v[148:151], v[210:213], v[44:47]
	v_mfma_f32_16x16x32_bf16 v[44:47], v[172:175], v[214:217], v[44:47]
	v_mfma_f32_16x16x32_bf16 v[40:43], v[176:179], v[210:213], v[40:43]
	v_mfma_f32_16x16x32_bf16 v[40:43], v[180:183], v[214:217], v[40:43]
	v_mfma_f32_16x16x32_bf16 v[28:31], v[148:151], v[218:221], v[28:31]
	v_mfma_f32_16x16x32_bf16 v[28:31], v[172:175], v[222:225], v[28:31]
	v_mfma_f32_16x16x32_bf16 v[24:27], v[176:179], v[218:221], v[24:27]
	v_mfma_f32_16x16x32_bf16 v[24:27], v[180:183], v[222:225], v[24:27]
	v_mfma_f32_16x16x32_bf16 v[12:15], v[148:151], v[226:229], v[12:15]
	v_mfma_f32_16x16x32_bf16 v[12:15], v[172:175], v[230:233], v[12:15]
	v_mfma_f32_16x16x32_bf16 v[8:11], v[176:179], v[226:229], v[8:11]
	v_mfma_f32_16x16x32_bf16 v[8:11], v[180:183], v[230:233], v[8:11]
	s_setprio 0
	s_setprio 1
	v_mfma_f32_16x16x32_bf16 v[52:55], v[186:189], v[202:205], v[52:55]
	v_mfma_f32_16x16x32_bf16 v[52:55], v[190:193], v[206:209], v[52:55]
	v_mfma_f32_16x16x32_bf16 v[48:51], v[194:197], v[202:205], v[48:51]
	v_mfma_f32_16x16x32_bf16 v[48:51], v[198:201], v[206:209], v[48:51]
	v_mfma_f32_16x16x32_bf16 v[36:39], v[186:189], v[210:213], v[36:39]
	v_mfma_f32_16x16x32_bf16 v[36:39], v[190:193], v[214:217], v[36:39]
	v_mfma_f32_16x16x32_bf16 v[32:35], v[194:197], v[210:213], v[32:35]
	v_mfma_f32_16x16x32_bf16 v[32:35], v[198:201], v[214:217], v[32:35]
	v_mfma_f32_16x16x32_bf16 v[20:23], v[186:189], v[218:221], v[20:23]
	v_mfma_f32_16x16x32_bf16 v[20:23], v[190:193], v[222:225], v[20:23]
	v_mfma_f32_16x16x32_bf16 v[16:19], v[194:197], v[218:221], v[16:19]
	v_mfma_f32_16x16x32_bf16 v[16:19], v[198:201], v[222:225], v[16:19]
	v_mfma_f32_16x16x32_bf16 v[4:7], v[186:189], v[226:229], v[4:7]
	v_mfma_f32_16x16x32_bf16 v[4:7], v[190:193], v[230:233], v[4:7]
	v_mfma_f32_16x16x32_bf16 v[0:3], v[194:197], v[226:229], v[0:3]
	v_mfma_f32_16x16x32_bf16 v[0:3], v[198:201], v[230:233], v[0:3]
	s_setprio 0
	s_barrier
	s_add_i32 s15, s15, 2
	s_add_u32 s9, s9, 0x2c0000
	s_addc_u32 s13, s13, 0
	s_add_u32 s46, s46, 0x400000
	s_addc_u32 s47, s47, 0
	s_cmp_gt_u32 s15, 29
	s_cbranch_scc0 .LBB0_1044
	s_and_b64 vcc, exec, s[10:11]
	s_cbranch_vccz .LBB0_1047
	s_barrier

; #define PG8_STAGE(bufoff, gbase, voff) do { _Pragma("unroll") for (int _i = 0; _i < 2; ++_i) \
;         __builtin_amdgcn_global_load_lds((const unsigned*)((const char*)(gbase) + (voff)[_i]), (LAS unsigned*)(lds + (bufoff) + ldsw + _i * 8192), 16, 0, 0); } while (0)
; #define PG8_LDA(dst, b, h) do { _Pragma("unroll") for (int m = 0; m < 4; ++m) _Pragma("unroll") for (int k = 0; k < 2; ++k) dst[m][k] = *(const LAS bf16x8*)(lds + PG8_SA(b, h) + aoff + m * 2048 + k * 1024); } while (0)
; #define PG8_LDB(dst, b, h) do { _Pragma("unroll") for (int n = 0; n < 2; ++n) _Pragma("unroll") for (int k = 0; k < 2; ++k) dst[n][k] = *(const LAS bf16x8*)(lds + PG8_SB(b, h) + boff + n * 2048 + k * 1024); } while (0)
; #define PG8_MMA(ai, bj, At, Bt) do { __builtin_amdgcn_s_setprio(1); _Pragma("unroll") for (int m = 0; m < 4; ++m) _Pragma("unroll") for (int n = 0; n < 2; ++n) _Pragma("unroll") for (int k = 0; k < 2; ++k) \
;         acc[ai][bj][m][n] = __builtin_amdgcn_mfma_f32_16x16x32_bf16(Bt[n][k], At[m][k], acc[ai][bj][m][n], 0, 0, 0); __builtin_amdgcn_s_setprio(0); } while (0)
; #define PG8_WAIT_V(n) asm volatile("s_waitcnt vmcnt(" #n ")" ::: "memory")
; #define PG8_WAIT_L(n) asm volatile("s_waitcnt lgkmcnt(" #n ")" ::: "memory")
; #define PG8_BAR __builtin_amdgcn_s_barrier()
; #define PG8_SCHED __builtin_amdgcn_sched_barrier(0)
; template <bool ALIGN_EPI, class Epi, class Sched>
; __device__ __forceinline__ void gemm_phase(LAS unsigned char* lds, const int lda, const int ldb, const int K, const Sched& S, const Epi& E, const size_t kstepA = (size_t)(BK * 2), const size_t kstepB = (size_t)(BK * 2)) {
;     ...
;         for (int t = 0; t < nt; t += 2) {
;             const bool last = (t == nt - 2);
;             const char* a1 = cA + (size_t)(t + 1) * kstepA;
;             const char* a2 = last ? nA : cA + (size_t)(t + 2) * kstepA; const char* b2 = last ? nB : cB + (size_t)(t + 2) * kstep;
;             const char* a3 = a2 + kstepA; const char* b3 = b2 + kstep;
;             PG8_LDB(B0, 0, 0); PG8_LDB(B1, 0, 1); PG8_SCHED; PG8_LDA(At, 0, 0); PG8_STAGE(PG8_SA(1, 1), a1 + hstepA, voffA);
;             PG8_WAIT_V(8); PG8_WAIT_L(0); PG8_BAR; PG8_MMA(0, 0, At, B0); PG8_MMA(0, 1, At, B1); PG8_BAR; PG8_SCHED;
;             PG8_LDA(At, 0, 1); PG8_STAGE(PG8_SB(0, 0), b2, voffB); PG8_STAGE(PG8_SB(0, 1), b2 + hstepB, voffB); PG8_STAGE(PG8_SA(0, 0), a2, voffA);
.LBB0_1154:
	ds_read_b128 v[80:83], v219
	ds_read_b128 v[84:87], v219 offset:1024
	ds_read_b128 v[104:107], v219 offset:2048
	ds_read_b128 v[108:111], v219 offset:3072
	ds_read_b128 v[144:147], v220
	ds_read_b128 v[148:151], v220 offset:1024
	ds_read_b128 v[152:155], v220 offset:2048
	ds_read_b128 v[156:159], v220 offset:3072
	s_add_u32 s12, s10, 0x1fc000
	s_addc_u32 s13, s11, 0
	s_cmpk_eq_i32 s67, 0x54
	s_cselect_b32 s16, s0, s12
	s_cselect_b32 s17, s1, s13
	s_cselect_b32 s14, s8, s57
	s_cselect_b32 s15, s9, s59
	s_add_u32 s12, s16, 0x200000
	s_addc_u32 s13, s17, 0
	v_lshl_add_u64 v[212:213], s[10:11], 0, v[178:179]
	s_add_i32 m0, s19, 0xc000
	ds_read_b128 v[160:163], v221
	ds_read_b128 v[164:167], v221 offset:1024
	ds_read_b128 v[188:191], v221 offset:2048
	ds_read_b128 v[192:195], v221 offset:3072
	ds_read_b128 v[196:199], v221 offset:4096
	ds_read_b128 v[200:203], v221 offset:5120
	ds_read_b128 v[204:207], v221 offset:6144
	ds_read_b128 v[208:211], v221 offset:7168
	global_load_lds_dwordx4 v[212:213], off
	v_lshl_add_u64 v[212:213], s[10:11], 0, v[180:181]
	s_add_i32 m0, s19, 0xe000
	s_nop 0
	global_load_lds_dwordx4 v[212:213], off
	s_waitcnt vmcnt(8)
	s_waitcnt lgkmcnt(0)
	s_barrier
	s_setprio 1
	s_waitcnt lgkmcnt(0)
	v_mfma_f32_16x16x32_bf16 v[140:143], v[80:83], v[160:163], v[140:143]
	v_mfma_f32_16x16x32_bf16 v[140:143], v[84:87], v[164:167], v[140:143]
	v_mfma_f32_16x16x32_bf16 v[136:139], v[104:107], v[160:163], v[136:139]
	v_mfma_f32_16x16x32_bf16 v[136:139], v[108:111], v[164:167], v[136:139]
	v_mfma_f32_16x16x32_bf16 v[124:127], v[80:83], v[188:191], v[124:127]
	v_mfma_f32_16x16x32_bf16 v[124:127], v[84:87], v[192:195], v[124:127]
	v_mfma_f32_16x16x32_bf16 v[120:123], v[104:107], v[188:191], v[120:123]
	v_mfma_f32_16x16x32_bf16 v[120:123], v[108:111], v[192:195], v[120:123]
	v_mfma_f32_16x16x32_bf16 v[100:103], v[80:83], v[196:199], v[100:103]
	v_mfma_f32_16x16x32_bf16 v[100:103], v[84:87], v[200:203], v[100:103]
	v_mfma_f32_16x16x32_bf16 v[96:99], v[104:107], v[196:199], v[96:99]
	v_mfma_f32_16x16x32_bf16 v[96:99], v[108:111], v[200:203], v[96:99]
	v_mfma_f32_16x16x32_bf16 v[76:79], v[80:83], v[204:207], v[76:79]
	v_mfma_f32_16x16x32_bf16 v[76:79], v[84:87], v[208:211], v[76:79]
	v_mfma_f32_16x16x32_bf16 v[72:75], v[104:107], v[204:207], v[72:75]
	v_mfma_f32_16x16x32_bf16 v[72:75], v[108:111], v[208:211], v[72:75]
	s_setprio 0
	s_setprio 1
	v_mfma_f32_16x16x32_bf16 v[132:135], v[144:147], v[160:163], v[132:135]
	v_mfma_f32_16x16x32_bf16 v[132:135], v[148:151], v[164:167], v[132:135]
	v_mfma_f32_16x16x32_bf16 v[128:131], v[152:155], v[160:163], v[128:131]
	v_mfma_f32_16x16x32_bf16 v[128:131], v[156:159], v[164:167], v[128:131]
	v_mfma_f32_16x16x32_bf16 v[116:119], v[144:147], v[188:191], v[116:119]
	v_mfma_f32_16x16x32_bf16 v[116:119], v[148:151], v[192:195], v[116:119]
	v_mfma_f32_16x16x32_bf16 v[112:115], v[152:155], v[188:191], v[112:115]
	v_mfma_f32_16x16x32_bf16 v[112:115], v[156:159], v[192:195], v[112:115]
	v_mfma_f32_16x16x32_bf16 v[92:95], v[144:147], v[196:199], v[92:95]
	v_mfma_f32_16x16x32_bf16 v[92:95], v[148:151], v[200:203], v[92:95]
	v_mfma_f32_16x16x32_bf16 v[88:91], v[152:155], v[196:199], v[88:91]
	v_mfma_f32_16x16x32_bf16 v[88:91], v[156:159], v[200:203], v[88:91]
	v_mfma_f32_16x16x32_bf16 v[68:71], v[144:147], v[204:207], v[68:71]
	v_mfma_f32_16x16x32_bf16 v[68:71], v[148:151], v[208:211], v[68:71]
	v_mfma_f32_16x16x32_bf16 v[64:67], v[152:155], v[204:207], v[64:67]
	v_mfma_f32_16x16x32_bf16 v[64:67], v[156:159], v[208:211], v[64:67]
	s_setprio 0
	s_barrier
	s_add_i32 s68, s51, s18
	v_lshl_add_u64 v[212:213], s[14:15], 0, v[170:171]
	s_mov_b32 m0, s68
	ds_read_b128 v[160:163], v221 offset:16384
	ds_read_b128 v[164:167], v221 offset:17408
	ds_read_b128 v[188:191], v221 offset:18432
	ds_read_b128 v[192:195], v221 offset:19456
	ds_read_b128 v[196:199], v221 offset:20480
	ds_read_b128 v[200:203], v221 offset:21504
	ds_read_b128 v[204:207], v221 offset:22528
	ds_read_b128 v[208:211], v221 offset:23552
	global_load_lds_dwordx4 v[212:213], off
	s_add_i32 m0, s68, 0x2000
	s_add_u32 s68, s14, 0x4000
	v_lshl_add_u64 v[212:213], s[14:15], 0, v[174:175]
	s_addc_u32 s69, s15, 0
	s_add_i32 s70, s64, s18
	global_load_lds_dwordx4 v[212:213], off
	v_lshl_add_u64 v[212:213], s[68:69], 0, v[170:171]
	s_mov_b32 m0, s70
	s_nop 0
	global_load_lds_dwordx4 v[212:213], off
	v_lshl_add_u64 v[212:213], s[68:69], 0, v[174:175]
	s_add_i32 m0, s70, 0x2000
	s_nop 0
	global_load_lds_dwordx4 v[212:213], off
	v_lshl_add_u64 v[212:213], s[16:17], 0, v[168:169]
	s_mov_b32 m0, s19
	s_nop 0
	global_load_lds_dwordx4 v[212:213], off
	v_lshl_add_u64 v[212:213], s[16:17], 0, v[172:173]
	s_mov_b32 m0, s29
	s_nop 0
	global_load_lds_dwordx4 v[212:213], off
	s_waitcnt vmcnt(8)
	s_waitcnt lgkmcnt(0)
	s_barrier
; #define PG8_STAGE(bufoff, gbase, voff) do { _Pragma("unroll") for (int _i = 0; _i < 2; ++_i) \
;         __builtin_amdgcn_global_load_lds((const unsigned*)((const char*)(gbase) + (voff)[_i]), (LAS unsigned*)(lds + (bufoff) + ldsw + _i * 8192), 16, 0, 0); } while (0)
; #define PG8_LDA(dst, b, h) do { _Pragma("unroll") for (int m = 0; m < 4; ++m) _Pragma("unroll") for (int k = 0; k < 2; ++k) dst[m][k] = *(const LAS bf16x8*)(lds + PG8_SA(b, h) + aoff + m * 2048 + k * 1024); } while (0)
; #define PG8_LDB(dst, b, h) do { _Pragma("unroll") for (int n = 0; n < 2; ++n) _Pragma("unroll") for (int k = 0; k < 2; ++k) dst[n][k] = *(const LAS bf16x8*)(lds + PG8_SB(b, h) + boff + n * 2048 + k * 1024); } while (0)
; #define PG8_MMA(ai, bj, At, Bt) do { __builtin_amdgcn_s_setprio(1); _Pragma("unroll") for (int m = 0; m < 4; ++m) _Pragma("unroll") for (int n = 0; n < 2; ++n) _Pragma("unroll") for (int k = 0; k < 2; ++k) \
;         acc[ai][bj][m][n] = __builtin_amdgcn_mfma_f32_16x16x32_bf16(Bt[n][k], At[m][k], acc[ai][bj][m][n], 0, 0, 0); __builtin_amdgcn_s_setprio(0); } while (0)
; #define PG8_WAIT_V(n) asm volatile("s_waitcnt vmcnt(" #n ")" ::: "memory")
; #define PG8_WAIT_L(n) asm volatile("s_waitcnt lgkmcnt(" #n ")" ::: "memory")
; #define PG8_BAR __builtin_amdgcn_s_barrier()
; #define PG8_SCHED __builtin_amdgcn_sched_barrier(0)
; template <bool ALIGN_EPI, class Epi, class Sched>
; __device__ __forceinline__ void gemm_phase(LAS unsigned char* lds, const int lda, const int ldb, const int K, const Sched& S, const Epi& E, const size_t kstepA = (size_t)(BK * 2), const size_t kstepB = (size_t)(BK * 2)) {
;     ...
;             PG8_WAIT_V(8); PG8_WAIT_L(0); PG8_BAR; PG8_MMA(1, 0, At, B0); PG8_MMA(1, 1, At, B1); PG8_BAR; PG8_SCHED;
;             PG8_LDB(B0, 1, 0); PG8_LDB(B1, 1, 1); PG8_SCHED; PG8_LDA(At, 1, 0); PG8_STAGE(PG8_SA(0, 1), a2 + hstepA, voffA);
;             PG8_WAIT_V(8); PG8_WAIT_L(0); PG8_BAR; PG8_MMA(0, 0, At, B0); PG8_MMA(0, 1, At, B1); PG8_BAR; PG8_SCHED;
	s_setprio 1
	s_waitcnt lgkmcnt(0)
	v_mfma_f32_16x16x32_bf16 v[60:63], v[80:83], v[160:163], v[60:63]
	v_mfma_f32_16x16x32_bf16 v[60:63], v[84:87], v[164:167], v[60:63]
	v_mfma_f32_16x16x32_bf16 v[56:59], v[104:107], v[160:163], v[56:59]
	v_mfma_f32_16x16x32_bf16 v[56:59], v[108:111], v[164:167], v[56:59]
	v_mfma_f32_16x16x32_bf16 v[44:47], v[80:83], v[188:191], v[44:47]
	v_mfma_f32_16x16x32_bf16 v[44:47], v[84:87], v[192:195], v[44:47]
	v_mfma_f32_16x16x32_bf16 v[40:43], v[104:107], v[188:191], v[40:43]
	v_mfma_f32_16x16x32_bf16 v[40:43], v[108:111], v[192:195], v[40:43]
	v_mfma_f32_16x16x32_bf16 v[28:31], v[80:83], v[196:199], v[28:31]
	v_mfma_f32_16x16x32_bf16 v[28:31], v[84:87], v[200:203], v[28:31]
	v_mfma_f32_16x16x32_bf16 v[24:27], v[104:107], v[196:199], v[24:27]
	v_mfma_f32_16x16x32_bf16 v[24:27], v[108:111], v[200:203], v[24:27]
	v_mfma_f32_16x16x32_bf16 v[12:15], v[80:83], v[204:207], v[12:15]
	v_mfma_f32_16x16x32_bf16 v[12:15], v[84:87], v[208:211], v[12:15]
	v_mfma_f32_16x16x32_bf16 v[8:11], v[104:107], v[204:207], v[8:11]
	v_mfma_f32_16x16x32_bf16 v[8:11], v[108:111], v[208:211], v[8:11]
	s_setprio 0
	s_setprio 1
	v_mfma_f32_16x16x32_bf16 v[52:55], v[144:147], v[160:163], v[52:55]
	v_mfma_f32_16x16x32_bf16 v[52:55], v[148:151], v[164:167], v[52:55]
	v_mfma_f32_16x16x32_bf16 v[48:51], v[152:155], v[160:163], v[48:51]
	v_mfma_f32_16x16x32_bf16 v[48:51], v[156:159], v[164:167], v[48:51]
	v_mfma_f32_16x16x32_bf16 v[36:39], v[144:147], v[188:191], v[36:39]
	v_mfma_f32_16x16x32_bf16 v[36:39], v[148:151], v[192:195], v[36:39]
	v_mfma_f32_16x16x32_bf16 v[32:35], v[152:155], v[188:191], v[32:35]
	v_mfma_f32_16x16x32_bf16 v[32:35], v[156:159], v[192:195], v[32:35]
	v_mfma_f32_16x16x32_bf16 v[20:23], v[144:147], v[196:199], v[20:23]
	v_mfma_f32_16x16x32_bf16 v[20:23], v[148:151], v[200:203], v[20:23]
	v_mfma_f32_16x16x32_bf16 v[16:19], v[152:155], v[196:199], v[16:19]
	v_mfma_f32_16x16x32_bf16 v[16:19], v[156:159], v[200:203], v[16:19]
	v_mfma_f32_16x16x32_bf16 v[4:7], v[144:147], v[204:207], v[4:7]
	v_mfma_f32_16x16x32_bf16 v[4:7], v[148:151], v[208:211], v[4:7]
	v_mfma_f32_16x16x32_bf16 v[0:3], v[152:155], v[204:207], v[0:3]
	v_mfma_f32_16x16x32_bf16 v[0:3], v[156:159], v[208:211], v[0:3]
	s_setprio 0
	s_barrier
	s_add_i32 s68, 0, 0x18000
	s_add_i32 s69, 0, 0x1c000
	v_add_u32_e32 v108, s68, v218
	v_add_u32_e32 v156, s69, v218
	ds_read_b128 v[80:83], v108
	ds_read_b128 v[84:87], v108 offset:1024
	ds_read_b128 v[104:107], v108 offset:2048
	ds_read_b128 v[108:111], v108 offset:3072
	ds_read_b128 v[144:147], v156
	ds_read_b128 v[148:151], v156 offset:1024
	ds_read_b128 v[152:155], v156 offset:2048
	ds_read_b128 v[156:159], v156 offset:3072
	s_add_u32 s16, s16, 0x4000
	s_addc_u32 s17, s17, 0
	s_mov_b32 m0, s30
	v_lshl_add_u64 v[212:213], s[16:17], 0, v[168:169]
	ds_read_b128 v[160:163], v221 offset:32768
	ds_read_b128 v[164:167], v221 offset:33792
	ds_read_b128 v[188:191], v221 offset:34816
	ds_read_b128 v[192:195], v221 offset:35840
	ds_read_b128 v[196:199], v221 offset:36864
	ds_read_b128 v[200:203], v221 offset:37888
	ds_read_b128 v[204:207], v221 offset:38912
	ds_read_b128 v[208:211], v221 offset:39936
	global_load_lds_dwordx4 v[212:213], off
	v_lshl_add_u64 v[212:213], s[16:17], 0, v[172:173]
	s_mov_b32 m0, s31
	s_nop 0
	global_load_lds_dwordx4 v[212:213], off
	s_waitcnt vmcnt(8)
	s_waitcnt lgkmcnt(0)
	s_barrier
	s_setprio 1
	s_waitcnt lgkmcnt(0)
	v_mfma_f32_16x16x32_bf16 v[140:143], v[80:83], v[160:163], v[140:143]
	v_mfma_f32_16x16x32_bf16 v[140:143], v[84:87], v[164:167], v[140:143]
	v_mfma_f32_16x16x32_bf16 v[136:139], v[104:107], v[160:163], v[136:139]
	v_mfma_f32_16x16x32_bf16 v[136:139], v[108:111], v[164:167], v[136:139]
	v_mfma_f32_16x16x32_bf16 v[124:127], v[80:83], v[188:191], v[124:127]
	v_mfma_f32_16x16x32_bf16 v[124:127], v[84:87], v[192:195], v[124:127]
	v_mfma_f32_16x16x32_bf16 v[120:123], v[104:107], v[188:191], v[120:123]
	v_mfma_f32_16x16x32_bf16 v[120:123], v[108:111], v[192:195], v[120:123]
	v_mfma_f32_16x16x32_bf16 v[100:103], v[80:83], v[196:199], v[100:103]
	v_mfma_f32_16x16x32_bf16 v[100:103], v[84:87], v[200:203], v[100:103]
	v_mfma_f32_16x16x32_bf16 v[96:99], v[104:107], v[196:199], v[96:99]
	v_mfma_f32_16x16x32_bf16 v[96:99], v[108:111], v[200:203], v[96:99]
	v_mfma_f32_16x16x32_bf16 v[76:79], v[80:83], v[204:207], v[76:79]
	v_mfma_f32_16x16x32_bf16 v[76:79], v[84:87], v[208:211], v[76:79]
	v_mfma_f32_16x16x32_bf16 v[72:75], v[104:107], v[204:207], v[72:75]
	v_mfma_f32_16x16x32_bf16 v[72:75], v[108:111], v[208:211], v[72:75]
	s_setprio 0
	s_setprio 1
	v_mfma_f32_16x16x32_bf16 v[132:135], v[144:147], v[160:163], v[132:135]
	v_mfma_f32_16x16x32_bf16 v[132:135], v[148:151], v[164:167], v[132:135]
	v_mfma_f32_16x16x32_bf16 v[128:131], v[152:155], v[160:163], v[128:131]
	v_mfma_f32_16x16x32_bf16 v[128:131], v[156:159], v[164:167], v[128:131]
	v_mfma_f32_16x16x32_bf16 v[116:119], v[144:147], v[188:191], v[116:119]
	v_mfma_f32_16x16x32_bf16 v[116:119], v[148:151], v[192:195], v[116:119]
	v_mfma_f32_16x16x32_bf16 v[112:115], v[152:155], v[188:191], v[112:115]
	v_mfma_f32_16x16x32_bf16 v[112:115], v[156:159], v[192:195], v[112:115]
	v_mfma_f32_16x16x32_bf16 v[92:95], v[144:147], v[196:199], v[92:95]
	v_mfma_f32_16x16x32_bf16 v[92:95], v[148:151], v[200:203], v[92:95]
	v_mfma_f32_16x16x32_bf16 v[88:91], v[152:155], v[196:199], v[88:91]
	v_mfma_f32_16x16x32_bf16 v[88:91], v[156:159], v[200:203], v[88:91]
	v_mfma_f32_16x16x32_bf16 v[68:71], v[144:147], v[204:207], v[68:71]
	v_mfma_f32_16x16x32_bf16 v[68:71], v[148:151], v[208:211], v[68:71]
	v_mfma_f32_16x16x32_bf16 v[64:67], v[152:155], v[204:207], v[64:67]
	v_mfma_f32_16x16x32_bf16 v[64:67], v[156:159], v[208:211], v[64:67]
	s_setprio 0
	s_barrier
; #define PG8_STAGE(bufoff, gbase, voff) do { _Pragma("unroll") for (int _i = 0; _i < 2; ++_i) \
;         __builtin_amdgcn_global_load_lds((const unsigned*)((const char*)(gbase) + (voff)[_i]), (LAS unsigned*)(lds + (bufoff) + ldsw + _i * 8192), 16, 0, 0); } while (0)
; #define PG8_LDA(dst, b, h) do { _Pragma("unroll") for (int m = 0; m < 4; ++m) _Pragma("unroll") for (int k = 0; k < 2; ++k) dst[m][k] = *(const LAS bf16x8*)(lds + PG8_SA(b, h) + aoff + m * 2048 + k * 1024); } while (0)
; #define PG8_MMA(ai, bj, At, Bt) do { __builtin_amdgcn_s_setprio(1); _Pragma("unroll") for (int m = 0; m < 4; ++m) _Pragma("unroll") for (int n = 0; n < 2; ++n) _Pragma("unroll") for (int k = 0; k < 2; ++k) \
;         acc[ai][bj][m][n] = __builtin_amdgcn_mfma_f32_16x16x32_bf16(Bt[n][k], At[m][k], acc[ai][bj][m][n], 0, 0, 0); __builtin_amdgcn_s_setprio(0); } while (0)
; #define PG8_WAIT_V(n) asm volatile("s_waitcnt vmcnt(" #n ")" ::: "memory")
; #define PG8_WAIT_L(n) asm volatile("s_waitcnt lgkmcnt(" #n ")" ::: "memory")
; #define PG8_BAR __builtin_amdgcn_s_barrier()
; #define PG8_SCHED __builtin_amdgcn_sched_barrier(0)
; template <bool ALIGN_EPI, class Epi, class Sched>
; __device__ __forceinline__ void gemm_phase(LAS unsigned char* lds, const int lda, const int ldb, const int K, const Sched& S, const Epi& E, const size_t kstepA = (size_t)(BK * 2), const size_t kstepB = (size_t)(BK * 2)) {
;     ...
;             PG8_LDA(At, 1, 1); PG8_STAGE(PG8_SB(1, 0), b3, voffB); PG8_STAGE(PG8_SB(1, 1), b3 + hstepB, voffB); PG8_STAGE(PG8_SA(1, 0), a3, voffA);
;             PG8_WAIT_V(8); PG8_WAIT_L(0); PG8_BAR; PG8_MMA(1, 0, At, B0); PG8_MMA(1, 1, At, B1); PG8_BAR; PG8_SCHED;
;         }
;         if constexpr (ALIGN_EPI) { if (wr == 0) PG8_BAR; }
	s_add_u32 s16, s14, 0x40000
	s_addc_u32 s17, s15, 0
	s_add_i32 s68, s68, s18
	v_lshl_add_u64 v[212:213], s[16:17], 0, v[170:171]
	s_mov_b32 m0, s68
	ds_read_b128 v[160:163], v221 offset:49152
	ds_read_b128 v[164:167], v221 offset:50176
	ds_read_b128 v[188:191], v221 offset:51200
	ds_read_b128 v[192:195], v221 offset:52224
	ds_read_b128 v[196:199], v221 offset:53248
	ds_read_b128 v[200:203], v221 offset:54272
	ds_read_b128 v[204:207], v221 offset:55296
	ds_read_b128 v[208:211], v221 offset:56320
	global_load_lds_dwordx4 v[212:213], off
	s_add_i32 m0, s68, 0x2000
	s_add_u32 s14, s14, 0x44000
	v_lshl_add_u64 v[212:213], s[16:17], 0, v[174:175]
	s_addc_u32 s15, s15, 0
	s_add_i32 s16, s69, s18
	global_load_lds_dwordx4 v[212:213], off
	v_lshl_add_u64 v[212:213], s[14:15], 0, v[170:171]
	s_mov_b32 m0, s16
	s_nop 0
	global_load_lds_dwordx4 v[212:213], off
	v_lshl_add_u64 v[212:213], s[14:15], 0, v[174:175]
	s_add_i32 m0, s16, 0x2000
	s_nop 0
	global_load_lds_dwordx4 v[212:213], off
	v_lshl_add_u64 v[212:213], s[12:13], 0, v[168:169]
	s_mov_b32 m0, s43
	s_nop 0
	global_load_lds_dwordx4 v[212:213], off
	v_lshl_add_u64 v[212:213], s[12:13], 0, v[172:173]
	s_mov_b32 m0, s50
	s_nop 0
	global_load_lds_dwordx4 v[212:213], off
	s_waitcnt vmcnt(8)
	s_waitcnt lgkmcnt(0)
	s_barrier
	s_setprio 1
	s_waitcnt lgkmcnt(0)
	v_mfma_f32_16x16x32_bf16 v[60:63], v[80:83], v[160:163], v[60:63]
	v_mfma_f32_16x16x32_bf16 v[60:63], v[84:87], v[164:167], v[60:63]
	v_mfma_f32_16x16x32_bf16 v[56:59], v[104:107], v[160:163], v[56:59]
	v_mfma_f32_16x16x32_bf16 v[56:59], v[108:111], v[164:167], v[56:59]
	v_mfma_f32_16x16x32_bf16 v[44:47], v[80:83], v[188:191], v[44:47]
	v_mfma_f32_16x16x32_bf16 v[44:47], v[84:87], v[192:195], v[44:47]
	v_mfma_f32_16x16x32_bf16 v[40:43], v[104:107], v[188:191], v[40:43]
	v_mfma_f32_16x16x32_bf16 v[40:43], v[108:111], v[192:195], v[40:43]
	v_mfma_f32_16x16x32_bf16 v[28:31], v[80:83], v[196:199], v[28:31]
	v_mfma_f32_16x16x32_bf16 v[28:31], v[84:87], v[200:203], v[28:31]
	v_mfma_f32_16x16x32_bf16 v[24:27], v[104:107], v[196:199], v[24:27]
	v_mfma_f32_16x16x32_bf16 v[24:27], v[108:111], v[200:203], v[24:27]
	v_mfma_f32_16x16x32_bf16 v[12:15], v[80:83], v[204:207], v[12:15]
	v_mfma_f32_16x16x32_bf16 v[12:15], v[84:87], v[208:211], v[12:15]
	v_mfma_f32_16x16x32_bf16 v[8:11], v[104:107], v[204:207], v[8:11]
	v_mfma_f32_16x16x32_bf16 v[8:11], v[108:111], v[208:211], v[8:11]
	s_setprio 0
	s_setprio 1
	v_mfma_f32_16x16x32_bf16 v[52:55], v[144:147], v[160:163], v[52:55]
	v_mfma_f32_16x16x32_bf16 v[52:55], v[148:151], v[164:167], v[52:55]
	v_mfma_f32_16x16x32_bf16 v[48:51], v[152:155], v[160:163], v[48:51]
	v_mfma_f32_16x16x32_bf16 v[48:51], v[156:159], v[164:167], v[48:51]
	v_mfma_f32_16x16x32_bf16 v[36:39], v[144:147], v[188:191], v[36:39]
	v_mfma_f32_16x16x32_bf16 v[36:39], v[148:151], v[192:195], v[36:39]
	v_mfma_f32_16x16x32_bf16 v[32:35], v[152:155], v[188:191], v[32:35]
	v_mfma_f32_16x16x32_bf16 v[32:35], v[156:159], v[192:195], v[32:35]
	v_mfma_f32_16x16x32_bf16 v[20:23], v[144:147], v[196:199], v[20:23]
	v_mfma_f32_16x16x32_bf16 v[20:23], v[148:151], v[200:203], v[20:23]
	v_mfma_f32_16x16x32_bf16 v[16:19], v[152:155], v[196:199], v[16:19]
	v_mfma_f32_16x16x32_bf16 v[16:19], v[156:159], v[200:203], v[16:19]
	v_mfma_f32_16x16x32_bf16 v[4:7], v[144:147], v[204:207], v[4:7]
	v_mfma_f32_16x16x32_bf16 v[4:7], v[148:151], v[208:211], v[4:7]
	v_mfma_f32_16x16x32_bf16 v[0:3], v[152:155], v[204:207], v[0:3]
	v_mfma_f32_16x16x32_bf16 v[0:3], v[156:159], v[208:211], v[0:3]
	s_setprio 0
	s_barrier
	s_add_i32 s67, s67, 2
	s_add_u32 s57, s57, 0x80000
	s_addc_u32 s59, s59, 0
	s_add_u32 s10, s10, 0x400000
	s_addc_u32 s11, s11, 0
	s_cmpk_gt_u32 s67, 0x55
	s_cbranch_scc0 .LBB0_1154
	s_and_b64 vcc, exec, s[46:47]
	s_cbranch_vccz .LBB0_1157
	s_barrier
